# plus: packed f32 ops in the residual/rmsnorm phases split into scalar f32 ops
# speedup vs baseline: 1.0027x; 1.0027x over previous
; template <int NR>
; __device__ __forceinline__ void norm_add_rows(const bf16_t* __restrict__ Yb, const float* xi, float* xo, const float* __restrict__ gpost,
;                                               const float* __restrict__ gpre, bf16_t* __restrict__ Hb, int row0, int rstride, int lane) {
;     u32x2 yb[NR][8]; f32x4 v[NR][8];
; #pragma unroll
;     for (int q = 0; q < NR; ++q) { const size_t ro = (size_t)(row0 + q * rstride) * DM;
; #pragma unroll
;         for (int j = 0; j < 8; ++j) yb[q][j] = ((const u32x2*)(Yb + ro))[lane + 64 * j];
; #pragma unroll
;         for (int j = 0; j < 8; ++j) v[q][j] = ((const f32x4*)(xi + ro))[lane + 64 * j]; }
;     f32x4 gp[8];
; #pragma unroll
;     for (int j = 0; j < 8; ++j) gp[j] = ((const f32x4*)gpost)[lane + 64 * j];
; #pragma unroll
;     for (int q = 0; q < NR; ++q) { const size_t ro = (size_t)(row0 + q * rstride) * DM;
;         f32x4 y[8]; float ss = 0.f;
; #pragma unroll
;         for (int j = 0; j < 8; ++j) { y[j].x = __uint_as_float(yb[q][j].x << 16); y[j].y = __uint_as_float(yb[q][j].x & 0xffff0000u); y[j].z = __uint_as_float(yb[q][j].y << 16); y[j].w = __uint_as_float(yb[q][j].y & 0xffff0000u);
;             ss += (y[j].x * y[j].x + y[j].y * y[j].y) + (y[j].z * y[j].z + y[j].w * y[j].w); }
;         const float rs = rsqrtf(wave_sum(ss) * (1.0f / DM) + EPS);
.LBB0_661:
	global_load_dwordx2 v[34:35], v[116:117], off
	global_load_dwordx2 v[36:37], v[116:117], off offset:512
	global_load_dwordx2 v[38:39], v[116:117], off offset:1024
	global_load_dwordx2 v[40:41], v[116:117], off offset:1536
	global_load_dwordx2 v[42:43], v[116:117], off offset:2048
	global_load_dwordx2 v[44:45], v[116:117], off offset:2560
	global_load_dwordx2 v[46:47], v[116:117], off offset:3072
	global_load_dwordx2 v[48:49], v[116:117], off offset:3584
	v_lshl_add_u64 v[50:51], s[26:27], 0, v[0:1]
	s_movk_i32 s15, 0x1000
	s_ashr_i32 s31, s30, 31
	global_load_dwordx4 v[86:89], v[50:51], off
	global_load_dwordx4 v[90:93], v[50:51], off offset:1024
	global_load_dwordx4 v[138:141], v[50:51], off offset:2048
	global_load_dwordx4 v[82:85], v[50:51], off offset:3072
	v_add_co_u32_e32 v50, vcc, s15, v50
	s_lshl_b64 s[6:7], s[30:31], 12
	s_nop 0
	v_addc_co_u32_e32 v51, vcc, 0, v51, vcc
	global_load_dwordx4 v[78:81], v[50:51], off
	global_load_dwordx4 v[74:77], v[50:51], off offset:1024
	global_load_dwordx4 v[70:73], v[50:51], off offset:2048
	global_load_dwordx4 v[66:69], v[50:51], off offset:3072
	v_lshl_add_u64 v[50:51], v[112:113], 0, s[6:7]
	global_load_dwordx2 v[132:133], v[50:51], off
	global_load_dwordx2 v[130:131], v[50:51], off offset:512
	global_load_dwordx2 v[128:129], v[50:51], off offset:1024
	global_load_dwordx2 v[126:127], v[50:51], off offset:1536
	global_load_dwordx2 v[124:125], v[50:51], off offset:2048
	global_load_dwordx2 v[122:123], v[50:51], off offset:2560
	global_load_dwordx2 v[120:121], v[50:51], off offset:3072
	global_load_dwordx2 v[118:119], v[50:51], off offset:3584
	s_lshl_b64 s[10:11], s[30:31], 13
	s_add_u32 s6, s20, s10
	v_lshlrev_b32_e32 v137, 4, v100
	s_addc_u32 s7, s21, s11
	global_load_dwordx4 v[62:65], v137, s[6:7]
	global_load_dwordx4 v[58:61], v137, s[6:7] offset:1024
	global_load_dwordx4 v[54:57], v137, s[6:7] offset:2048
	global_load_dwordx4 v[50:53], v137, s[6:7] offset:3072
	s_waitcnt vmcnt(0)
	v_and_b32_e32 v95, 0xffff0000, v34
	v_and_b32_e32 v97, 0xffff0000, v35
	v_and_b32_e32 v143, 0xffff0000, v36
	v_and_b32_e32 v145, 0xffff0000, v37
	v_lshlrev_b32_e32 v94, 16, v34
	v_lshlrev_b32_e32 v96, 16, v35
	v_lshlrev_b32_e32 v142, 16, v36
	v_lshlrev_b32_e32 v144, 16, v37
	v_and_b32_e32 v147, 0xffff0000, v38
	v_and_b32_e32 v149, 0xffff0000, v39
	v_mul_f32_e32 v34, v95, v95
	v_mul_f32_e32 v35, v97, v97
	v_mul_f32_e32 v36, v143, v143
	v_mul_f32_e32 v37, v145, v145
	v_lshlrev_b32_e32 v146, 16, v38
	v_lshlrev_b32_e32 v148, 16, v39
	v_and_b32_e32 v151, 0xffff0000, v40
	v_and_b32_e32 v153, 0xffff0000, v41
	v_mul_f32_e32 v38, v147, v147
	v_mul_f32_e32 v39, v149, v149
	v_fmac_f32_e32 v34, v94, v94
	v_fmac_f32_e32 v35, v96, v96
	v_fmac_f32_e32 v36, v142, v142
	v_fmac_f32_e32 v37, v144, v144
	v_lshlrev_b32_e32 v150, 16, v40
	v_lshlrev_b32_e32 v152, 16, v41
	v_and_b32_e32 v155, 0xffff0000, v42
	v_and_b32_e32 v157, 0xffff0000, v43
	v_mul_f32_e32 v40, v151, v151
	v_mul_f32_e32 v41, v153, v153
	v_fmac_f32_e32 v38, v146, v146
	v_fmac_f32_e32 v39, v148, v148
	v_add_f32_e32 v34, v34, v35
	v_add_f32_e32 v35, v36, v37
	v_lshlrev_b32_e32 v154, 16, v42
	v_lshlrev_b32_e32 v156, 16, v43
	v_and_b32_e32 v159, 0xffff0000, v44
	v_mul_f32_e32 v42, v155, v155
	v_mul_f32_e32 v43, v157, v157
	v_fmac_f32_e32 v40, v150, v150
	v_fmac_f32_e32 v41, v152, v152
	v_add_f32_e32 v36, v38, v39
	v_add_f32_e32 v34, v34, v35
	v_and_b32_e32 v161, 0xffff0000, v45
	v_lshlrev_b32_e32 v158, 16, v44
	v_lshlrev_b32_e32 v160, 16, v45
	v_fmac_f32_e32 v42, v154, v154
	v_fmac_f32_e32 v43, v156, v156
	v_add_f32_e32 v37, v40, v41
	v_add_f32_e32 v34, v34, v36
	v_mul_f32_e32 v35, v159, v159
	v_mul_f32_e32 v36, v161, v161
	v_add_f32_e32 v38, v42, v43
	v_add_f32_e32 v34, v34, v37
	v_fmac_f32_e32 v35, v158, v158
	v_fmac_f32_e32 v36, v160, v160
	v_add_f32_e32 v34, v34, v38
	v_add_f32_e32 v35, v35, v36
	v_and_b32_e32 v163, 0xffff0000, v46
	v_and_b32_e32 v165, 0xffff0000, v47
	v_add_f32_e32 v34, v34, v35
	v_lshlrev_b32_e32 v162, 16, v46
	v_lshlrev_b32_e32 v164, 16, v47
	v_mul_f32_e32 v35, v163, v163
	v_mul_f32_e32 v36, v165, v165
	v_fmac_f32_e32 v35, v162, v162
	v_fmac_f32_e32 v36, v164, v164
	v_add_f32_e32 v35, v35, v36
	v_and_b32_e32 v167, 0xffff0000, v48
	v_and_b32_e32 v169, 0xffff0000, v49
	v_add_f32_e32 v34, v34, v35
	v_lshlrev_b32_e32 v166, 16, v48
	v_lshlrev_b32_e32 v168, 16, v49
	v_mul_f32_e32 v35, v167, v167
	v_mul_f32_e32 v36, v169, v169
	v_fmac_f32_e32 v35, v166, v166
	v_fmac_f32_e32 v36, v168, v168
	v_add_f32_e32 v35, v35, v36
	v_add_f32_e32 v34, v34, v35
	ds_swizzle_b32 v35, v34 offset:swizzle(SWAP,1)
	s_waitcnt lgkmcnt(0)
	v_add_f32_e32 v134, v34, v35
	global_load_dwordx4 v[46:49], v99, s[6:7]
	global_load_dwordx4 v[42:45], v101, s[6:7]
	global_load_dwordx4 v[38:41], v135, s[6:7]
	global_load_dwordx4 v[34:37], v136, s[6:7]
	ds_swizzle_b32 v170, v134 offset:swizzle(SWAP,2)
	s_waitcnt lgkmcnt(0)
	v_add_f32_e32 v134, v134, v170
	ds_swizzle_b32 v170, v134 offset:swizzle(SWAP,4)
	s_waitcnt lgkmcnt(0)
	v_add_f32_e32 v134, v134, v170
	ds_swizzle_b32 v170, v134 offset:swizzle(SWAP,8)
	s_waitcnt lgkmcnt(0)
	v_add_f32_e32 v134, v134, v170
	ds_swizzle_b32 v170, v134 offset:swizzle(SWAP,16)
	s_waitcnt lgkmcnt(0)
; __device__ __forceinline__ unsigned pk2(float lo, float hi) { return f2bf(lo) | (f2bf(hi) << 16); }
; template <int NR>
; __device__ __forceinline__ void norm_add_rows(const bf16_t* __restrict__ Yb, const float* xi, float* xo, const float* __restrict__ gpost,
;                                               const float* __restrict__ gpre, bf16_t* __restrict__ Hb, int row0, int rstride, int lane) {
;     ...
;         const float rs = rsqrtf(wave_sum(ss) * (1.0f / DM) + EPS);
;         float ss2 = 0.f;
; #pragma unroll
;         for (int j = 0; j < 8; ++j) { v[q][j] = v[q][j] + y[j] * rs * gp[j]; ((f32x4*)(xo + ro))[lane + 64 * j] = v[q][j];
;             ss2 += (v[q][j].x * v[q][j].x + v[q][j].y * v[q][j].y) + (v[q][j].z * v[q][j].z + v[q][j].w * v[q][j].w); }
;         if (gpre) {
;             const float rs2 = rsqrtf(wave_sum(ss2) * (1.0f / DM) + EPS);
; #pragma unroll
;             for (int j = 0; j < 8; ++j) { const f32x4 gg = ((const f32x4*)gpre)[lane + 64 * j];
;                 u32x2 w; w.x = pk2(v[q][j].x * rs2 * gg.x, v[q][j].y * rs2 * gg.y); w.y = pk2(v[q][j].z * rs2 * gg.z, v[q][j].w * rs2 * gg.w); ((u32x2*)(Hb + ro))[lane + 64 * j] = w; }
	v_add_f32_e32 v134, v134, v170
	v_mov_b32_e32 v170, v134
	s_nop 1
	v_permlane32_swap_b32_e32 v134, v170
	v_add_f32_e32 v134, v134, v170
	v_fmamk_f32 v134, v134, 0x3a000000, v177
	v_mul_f32_e32 v170, 0x4b800000, v134
	v_cmp_gt_f32_e32 vcc, s35, v134
	s_nop 1
	v_cndmask_b32_e32 v134, v134, v170, vcc
	v_rsq_f32_e32 v134, v134
	s_nop 0
	v_mul_f32_e32 v170, 0x45800000, v134
	v_cndmask_b32_e32 v134, v134, v170, vcc
	v_mul_f32_e32 v96, v96, v134
	v_mul_f32_e32 v97, v97, v134
	v_mul_f32_e32 v94, v94, v134
	v_mul_f32_e32 v95, v95, v134
	v_fma_f32 v96, v4, v96, v88
	v_fma_f32 v97, v5, v97, v89
	v_mul_f32_e32 v88, v144, v134
	v_mul_f32_e32 v89, v145, v134
	v_fma_f32 v94, v2, v94, v86
	v_fma_f32 v95, v3, v95, v87
	v_mul_f32_e32 v86, v142, v134
	v_mul_f32_e32 v87, v143, v134
	v_fma_f32 v92, v8, v88, v92
	v_fma_f32 v93, v9, v89, v93
	v_mul_f32_e32 v88, v148, v134
	v_mul_f32_e32 v89, v149, v134
	v_fma_f32 v90, v6, v86, v90
	v_fma_f32 v91, v7, v87, v91
	v_mul_f32_e32 v86, v146, v134
	v_mul_f32_e32 v87, v147, v134
	v_fma_f32 v88, v12, v88, v140
	v_fma_f32 v89, v13, v89, v141
	v_mul_f32_e32 v140, v152, v134
	v_mul_f32_e32 v141, v153, v134
	v_fma_f32 v86, v10, v86, v138
	v_fma_f32 v87, v11, v87, v139
	v_mul_f32_e32 v138, v150, v134
	v_mul_f32_e32 v139, v151, v134
	v_fma_f32 v84, v16, v140, v84
	v_fma_f32 v85, v17, v141, v85
	v_mul_f32_e32 v140, v156, v134
	v_mul_f32_e32 v141, v157, v134
	v_lshl_add_u64 v[170:171], s[18:19], 0, v[0:1]
	v_fma_f32 v82, v14, v138, v82
	v_fma_f32 v83, v15, v139, v83
	v_mul_f32_e32 v138, v154, v134
	v_mul_f32_e32 v139, v155, v134
	v_fma_f32 v80, v20, v140, v80
	v_fma_f32 v81, v21, v141, v81
	v_mul_f32_e32 v140, v158, v134
	v_mul_f32_e32 v141, v159, v134
	v_mul_f32_e32 v142, v160, v134
	v_mul_f32_e32 v143, v161, v134
	v_fma_f32 v78, v18, v138, v78
	v_fma_f32 v79, v19, v139, v79
	v_add_co_u32_e32 v138, vcc, s15, v170
	v_fma_f32 v76, v24, v142, v76
	v_fma_f32 v77, v25, v143, v77
	v_fma_f32 v74, v22, v140, v74
	v_fma_f32 v75, v23, v141, v75
	v_mul_f32_e32 v140, v162, v134
	v_mul_f32_e32 v141, v163, v134
	v_mul_f32_e32 v142, v164, v134
	v_mul_f32_e32 v143, v165, v134
	v_addc_co_u32_e32 v139, vcc, 0, v171, vcc
	v_fma_f32 v72, v28, v142, v72
	v_fma_f32 v73, v29, v143, v73
	v_fma_f32 v70, v26, v140, v70
	v_fma_f32 v71, v27, v141, v71
	v_mul_f32_e32 v140, v166, v134
	v_mul_f32_e32 v141, v167, v134
	v_mul_f32_e32 v142, v168, v134
	v_mul_f32_e32 v143, v169, v134
	v_cndmask_b32_e64 v134, 0, 1, s[22:23]
	v_fma_f32 v68, v32, v142, v68
	v_fma_f32 v69, v33, v143, v69
	v_fma_f32 v66, v30, v140, v66
	v_fma_f32 v67, v31, v141, v67
	v_cmp_ne_u32_e64 s[6:7], 1, v134
	s_andn2_b64 vcc, exec, s[22:23]
	global_store_dwordx4 v[170:171], v[94:97], off
	global_store_dwordx4 v[170:171], v[90:93], off offset:1024
	global_store_dwordx4 v[170:171], v[86:89], off offset:2048
	global_store_dwordx4 v[170:171], v[82:85], off offset:3072
	global_store_dwordx4 v[138:139], v[78:81], off
	global_store_dwordx4 v[138:139], v[74:77], off offset:1024
	global_store_dwordx4 v[138:139], v[70:73], off offset:2048
	global_store_dwordx4 v[138:139], v[66:69], off offset:3072
	s_cbranch_vccnz .LBB0_663
	v_mul_f32_e32 v134, v95, v95
	v_mul_f32_e32 v138, v97, v97
	v_fmac_f32_e32 v134, v94, v94
	v_fmac_f32_e32 v138, v96, v96
	v_add_f32_e32 v134, v134, v138
	v_mul_f32_e32 v138, v91, v91
	v_mul_f32_e32 v139, v93, v93
	v_fmac_f32_e32 v138, v90, v90
	v_fmac_f32_e32 v139, v92, v92
	v_add_f32_e32 v138, v138, v139
	v_add_f32_e32 v134, v134, v138
	v_mul_f32_e32 v138, v87, v87
	v_mul_f32_e32 v139, v89, v89
	v_fmac_f32_e32 v138, v86, v86
	v_fmac_f32_e32 v139, v88, v88
	v_add_f32_e32 v138, v138, v139
	v_add_f32_e32 v134, v138, v134
	v_mul_f32_e32 v138, v83, v83
	v_mul_f32_e32 v139, v85, v85
	v_fmac_f32_e32 v138, v82, v82
	v_fmac_f32_e32 v139, v84, v84
	v_add_f32_e32 v138, v138, v139
	v_add_f32_e32 v134, v138, v134
	v_mul_f32_e32 v138, v79, v79
	v_mul_f32_e32 v139, v81, v81
	v_fmac_f32_e32 v138, v78, v78
	v_fmac_f32_e32 v139, v80, v80
	v_add_f32_e32 v138, v138, v139
	v_add_f32_e32 v134, v138, v134
	v_mul_f32_e32 v138, v75, v75
	v_mul_f32_e32 v139, v77, v77
	v_fmac_f32_e32 v138, v74, v74
	v_fmac_f32_e32 v139, v76, v76
	v_add_f32_e32 v138, v138, v139
	v_add_f32_e32 v134, v138, v134
	v_mul_f32_e32 v138, v71, v71
	v_mul_f32_e32 v139, v73, v73
	v_fmac_f32_e32 v138, v70, v70
	v_fmac_f32_e32 v139, v72, v72
	v_add_f32_e32 v138, v138, v139
	v_add_f32_e32 v134, v138, v134
	v_mul_f32_e32 v138, v67, v67
	v_mul_f32_e32 v139, v69, v69
	v_fmac_f32_e32 v138, v66, v66
	v_fmac_f32_e32 v139, v68, v68
	v_add_f32_e32 v138, v138, v139
	v_add_f32_e32 v134, v138, v134
	ds_swizzle_b32 v138, v134 offset:swizzle(SWAP,1)
	v_mov_b32_e32 v143, v96
	v_mov_b32_e32 v96, v95
	v_mov_b32_e32 v142, v94
	s_mov_b32 s10, 0xe7600000
	s_waitcnt lgkmcnt(0)
	v_add_f32_e32 v134, v134, v138
	ds_swizzle_b32 v138, v134 offset:swizzle(SWAP,2)
	s_waitcnt lgkmcnt(0)
	v_add_f32_e32 v134, v134, v138
	ds_swizzle_b32 v138, v134 offset:swizzle(SWAP,4)
	s_waitcnt lgkmcnt(0)
	v_add_f32_e32 v134, v134, v138
	ds_swizzle_b32 v138, v134 offset:swizzle(SWAP,8)
	s_waitcnt lgkmcnt(0)
	v_add_f32_e32 v134, v134, v138
	ds_swizzle_b32 v138, v134 offset:swizzle(SWAP,16)
	s_waitcnt lgkmcnt(0)
	v_add_f32_e32 v134, v134, v138
	v_mov_b32_e32 v138, v134
	s_nop 1
	v_permlane32_swap_b32_e32 v134, v138
	v_add_f32_e32 v134, v134, v138
	v_fmamk_f32 v134, v134, 0x3a000000, v177
	v_cmp_gt_f32_e32 vcc, s35, v134
	v_mul_f32_e32 v138, 0x4b800000, v134
	s_nop 0
	v_cndmask_b32_e32 v134, v134, v138, vcc
	v_rsq_f32_e32 v134, v134
	s_nop 0
	v_mul_f32_e32 v138, 0x45800000, v134
	v_cndmask_b32_e32 v134, v134, v138, vcc
	global_load_dwordx4 v[138:141], v[102:103], off
	v_mul_f32_e32 v94, v96, v134
	v_mul_f32_e32 v95, v97, v134
	v_mul_f32_e32 v142, v142, v134
	v_mul_f32_e32 v143, v143, v134
	s_waitcnt vmcnt(0)
; __device__ __forceinline__ unsigned pk2(float lo, float hi) { return f2bf(lo) | (f2bf(hi) << 16); }
; template <int NR>
; __device__ __forceinline__ void norm_add_rows(const bf16_t* __restrict__ Yb, const float* xi, float* xo, const float* __restrict__ gpost,
;                                               const float* __restrict__ gpre, bf16_t* __restrict__ Hb, int row0, int rstride, int lane) {
;     ...
;         if (gpre) {
;             const float rs2 = rsqrtf(wave_sum(ss2) * (1.0f / DM) + EPS);
; #pragma unroll
;             for (int j = 0; j < 8; ++j) { const f32x4 gg = ((const f32x4*)gpre)[lane + 64 * j];
;                 u32x2 w; w.x = pk2(v[q][j].x * rs2 * gg.x, v[q][j].y * rs2 * gg.y); w.y = pk2(v[q][j].z * rs2 * gg.z, v[q][j].w * rs2 * gg.w); ((u32x2*)(Hb + ro))[lane + 64 * j] = w; }
	v_mov_b32_e32 v145, v140
	v_mov_b32_e32 v140, v139
	v_mov_b32_e32 v144, v138
	v_mul_f32_e32 v94, v140, v94
	v_mul_f32_e32 v95, v141, v95
	v_mul_f32_e32 v142, v144, v142
	v_mul_f32_e32 v143, v145, v143
	v_and_b32_sdwa v138, v95, v206 dst_sel:DWORD dst_unused:UNUSED_PAD src0_sel:WORD_1 src1_sel:DWORD
	v_and_b32_sdwa v96, v143, v206 dst_sel:DWORD dst_unused:UNUSED_PAD src0_sel:WORD_1 src1_sel:DWORD
	v_and_b32_sdwa v139, v94, v206 dst_sel:DWORD dst_unused:UNUSED_PAD src0_sel:WORD_1 src1_sel:DWORD
	v_add3_u32 v95, v95, v138, s0
	v_and_b32_sdwa v97, v142, v206 dst_sel:DWORD dst_unused:UNUSED_PAD src0_sel:WORD_1 src1_sel:DWORD
	v_add3_u32 v96, v143, v96, s0
	v_add3_u32 v94, v94, v139, s0
	v_and_b32_e32 v95, 0xffff0000, v95
	v_add3_u32 v97, v142, v97, s0
	v_and_b32_e32 v94, 0xffff0000, v94
	v_or_b32_sdwa v95, v95, v96 dst_sel:DWORD dst_unused:UNUSED_PAD src0_sel:DWORD src1_sel:WORD_1
	v_add_co_u32_e32 v96, vcc, s10, v116
	v_or_b32_sdwa v94, v94, v97 dst_sel:DWORD dst_unused:UNUSED_PAD src0_sel:DWORD src1_sel:WORD_1
	s_nop 0
	v_addc_co_u32_e32 v97, vcc, -1, v117, vcc
	global_store_dwordx2 v[96:97], v[94:95], off
	global_load_dwordx4 v[94:97], v[102:103], off offset:1024
	v_mov_b32_e32 v138, v90
	v_mov_b32_e32 v139, v92
	v_mul_f32_e32 v138, v138, v134
	v_mul_f32_e32 v139, v139, v134
	v_mov_b32_e32 v92, v91
	v_mul_f32_e32 v90, v92, v134
	v_mul_f32_e32 v91, v93, v134
	s_mov_b32 s10, 0xe7601000
	s_waitcnt vmcnt(0)
	v_mov_b32_e32 v140, v94
	v_mov_b32_e32 v141, v96
	v_mul_f32_e32 v138, v140, v138
	v_mul_f32_e32 v139, v141, v139
	v_mov_b32_e32 v96, v95
	v_mul_f32_e32 v90, v96, v90
	v_mul_f32_e32 v91, v97, v91
	v_and_b32_sdwa v93, v138, v206 dst_sel:DWORD dst_unused:UNUSED_PAD src0_sel:WORD_1 src1_sel:DWORD
	v_add3_u32 v94, v138, v93, s0
	v_and_b32_sdwa v93, v91, v206 dst_sel:DWORD dst_unused:UNUSED_PAD src0_sel:WORD_1 src1_sel:DWORD
	v_and_b32_sdwa v95, v90, v206 dst_sel:DWORD dst_unused:UNUSED_PAD src0_sel:WORD_1 src1_sel:DWORD
	v_and_b32_sdwa v92, v139, v206 dst_sel:DWORD dst_unused:UNUSED_PAD src0_sel:WORD_1 src1_sel:DWORD
	v_add3_u32 v91, v91, v93, s0
	v_add3_u32 v90, v90, v95, s0
	v_add3_u32 v92, v139, v92, s0
	v_and_b32_e32 v91, 0xffff0000, v91
	v_and_b32_e32 v90, 0xffff0000, v90
	v_or_b32_sdwa v93, v91, v92 dst_sel:DWORD dst_unused:UNUSED_PAD src0_sel:DWORD src1_sel:WORD_1
	v_or_b32_sdwa v92, v90, v94 dst_sel:DWORD dst_unused:UNUSED_PAD src0_sel:DWORD src1_sel:WORD_1
	v_add_co_u32_e32 v90, vcc, s10, v116
	v_mov_b32_e32 v97, v88
	s_nop 0
	v_addc_co_u32_e32 v91, vcc, -1, v117, vcc
	global_store_dwordx2 v[90:91], v[92:93], off offset:-3584
	global_load_dwordx4 v[92:95], v[102:103], off offset:2048
	v_mov_b32_e32 v88, v87
	v_mov_b32_e32 v96, v86
	v_mul_f32_e32 v86, v88, v134
	v_mul_f32_e32 v87, v89, v134
	v_mul_f32_e32 v96, v96, v134
	v_mul_f32_e32 v97, v97, v134
	s_waitcnt vmcnt(0)
	v_mov_b32_e32 v139, v94
	v_mov_b32_e32 v94, v93
	v_mov_b32_e32 v138, v92
	v_mul_f32_e32 v86, v94, v86
	v_mul_f32_e32 v87, v95, v87
	v_mul_f32_e32 v96, v138, v96
	v_mul_f32_e32 v97, v139, v97
	v_and_b32_sdwa v92, v87, v206 dst_sel:DWORD dst_unused:UNUSED_PAD src0_sel:WORD_1 src1_sel:DWORD
	v_and_b32_sdwa v93, v86, v206 dst_sel:DWORD dst_unused:UNUSED_PAD src0_sel:WORD_1 src1_sel:DWORD
	v_and_b32_sdwa v88, v97, v206 dst_sel:DWORD dst_unused:UNUSED_PAD src0_sel:WORD_1 src1_sel:DWORD
	v_and_b32_sdwa v89, v96, v206 dst_sel:DWORD dst_unused:UNUSED_PAD src0_sel:WORD_1 src1_sel:DWORD
	v_add3_u32 v87, v87, v92, s0
	v_add3_u32 v86, v86, v93, s0
	v_add3_u32 v89, v96, v89, s0
	v_add3_u32 v88, v97, v88, s0
	v_and_b32_e32 v87, 0xffff0000, v87
	v_and_b32_e32 v86, 0xffff0000, v86
	v_or_b32_sdwa v87, v87, v88 dst_sel:DWORD dst_unused:UNUSED_PAD src0_sel:DWORD src1_sel:WORD_1
	v_or_b32_sdwa v86, v86, v89 dst_sel:DWORD dst_unused:UNUSED_PAD src0_sel:DWORD src1_sel:WORD_1
	global_store_dwordx2 v[90:91], v[86:87], off offset:-3072
	global_load_dwordx4 v[86:89], v[102:103], off offset:3072
	v_mov_b32_e32 v93, v84
	v_mov_b32_e32 v84, v83
	v_mov_b32_e32 v92, v82
	v_mul_f32_e32 v82, v84, v134
	v_mul_f32_e32 v83, v85, v134
	v_mul_f32_e32 v92, v92, v134
	v_mul_f32_e32 v93, v93, v134
	s_waitcnt vmcnt(0)
	v_mov_b32_e32 v95, v88
	v_mov_b32_e32 v88, v87
	v_mov_b32_e32 v94, v86
	v_mul_f32_e32 v82, v88, v82
	v_mul_f32_e32 v83, v89, v83
	v_mul_f32_e32 v92, v94, v92
	v_mul_f32_e32 v93, v95, v93
	v_and_b32_sdwa v86, v83, v206 dst_sel:DWORD dst_unused:UNUSED_PAD src0_sel:WORD_1 src1_sel:DWORD
	v_and_b32_sdwa v87, v82, v206 dst_sel:DWORD dst_unused:UNUSED_PAD src0_sel:WORD_1 src1_sel:DWORD
	v_and_b32_sdwa v84, v93, v206 dst_sel:DWORD dst_unused:UNUSED_PAD src0_sel:WORD_1 src1_sel:DWORD
	v_and_b32_sdwa v85, v92, v206 dst_sel:DWORD dst_unused:UNUSED_PAD src0_sel:WORD_1 src1_sel:DWORD
	v_add3_u32 v83, v83, v86, s0
	v_add3_u32 v82, v82, v87, s0
	v_add3_u32 v85, v92, v85, s0
	v_add3_u32 v84, v93, v84, s0
	v_and_b32_e32 v83, 0xffff0000, v83
	v_and_b32_e32 v82, 0xffff0000, v82
	v_or_b32_sdwa v83, v83, v84 dst_sel:DWORD dst_unused:UNUSED_PAD src0_sel:DWORD src1_sel:WORD_1
	v_or_b32_sdwa v82, v82, v85 dst_sel:DWORD dst_unused:UNUSED_PAD src0_sel:DWORD src1_sel:WORD_1
	global_store_dwordx2 v[90:91], v[82:83], off offset:-2560
	global_load_dwordx4 v[82:85], v[104:105], off
	v_mov_b32_e32 v87, v80
	v_mov_b32_e32 v80, v79
	v_mov_b32_e32 v86, v78
	v_mul_f32_e32 v78, v80, v134
	v_mul_f32_e32 v79, v81, v134
	v_mul_f32_e32 v86, v86, v134
	v_mul_f32_e32 v87, v87, v134
	s_waitcnt vmcnt(0)
; __device__ __forceinline__ unsigned pk2(float lo, float hi) { return f2bf(lo) | (f2bf(hi) << 16); }
; template <int NR>
; __device__ __forceinline__ void norm_add_rows(const bf16_t* __restrict__ Yb, const float* xi, float* xo, const float* __restrict__ gpost,
;                                               const float* __restrict__ gpre, bf16_t* __restrict__ Hb, int row0, int rstride, int lane) {
;     ...
;         if (gpre) {
;             const float rs2 = rsqrtf(wave_sum(ss2) * (1.0f / DM) + EPS);
; #pragma unroll
;             for (int j = 0; j < 8; ++j) { const f32x4 gg = ((const f32x4*)gpre)[lane + 64 * j];
;                 u32x2 w; w.x = pk2(v[q][j].x * rs2 * gg.x, v[q][j].y * rs2 * gg.y); w.y = pk2(v[q][j].z * rs2 * gg.z, v[q][j].w * rs2 * gg.w); ((u32x2*)(Hb + ro))[lane + 64 * j] = w; }
	v_mov_b32_e32 v89, v84
	v_mov_b32_e32 v84, v83
	v_mov_b32_e32 v88, v82
	v_mul_f32_e32 v78, v84, v78
	v_mul_f32_e32 v79, v85, v79
	v_mul_f32_e32 v86, v88, v86
	v_mul_f32_e32 v87, v89, v87
	v_and_b32_sdwa v82, v79, v206 dst_sel:DWORD dst_unused:UNUSED_PAD src0_sel:WORD_1 src1_sel:DWORD
	v_and_b32_sdwa v83, v78, v206 dst_sel:DWORD dst_unused:UNUSED_PAD src0_sel:WORD_1 src1_sel:DWORD
	v_and_b32_sdwa v80, v87, v206 dst_sel:DWORD dst_unused:UNUSED_PAD src0_sel:WORD_1 src1_sel:DWORD
	v_and_b32_sdwa v81, v86, v206 dst_sel:DWORD dst_unused:UNUSED_PAD src0_sel:WORD_1 src1_sel:DWORD
	v_add3_u32 v79, v79, v82, s0
	v_add3_u32 v78, v78, v83, s0
	v_add3_u32 v81, v86, v81, s0
	v_add3_u32 v80, v87, v80, s0
	v_and_b32_e32 v79, 0xffff0000, v79
	v_and_b32_e32 v78, 0xffff0000, v78
	v_or_b32_sdwa v79, v79, v80 dst_sel:DWORD dst_unused:UNUSED_PAD src0_sel:DWORD src1_sel:WORD_1
	v_or_b32_sdwa v78, v78, v81 dst_sel:DWORD dst_unused:UNUSED_PAD src0_sel:DWORD src1_sel:WORD_1
	global_store_dwordx2 v[90:91], v[78:79], off offset:-2048
	global_load_dwordx4 v[78:81], v[106:107], off
	v_mov_b32_e32 v83, v76
	v_mov_b32_e32 v76, v75
	v_mov_b32_e32 v82, v74
	v_mul_f32_e32 v74, v76, v134
	v_mul_f32_e32 v75, v77, v134
	v_mul_f32_e32 v82, v82, v134
	v_mul_f32_e32 v83, v83, v134
	s_waitcnt vmcnt(0)
	v_mov_b32_e32 v85, v80
	v_mov_b32_e32 v80, v79
	v_mov_b32_e32 v84, v78
	v_mul_f32_e32 v74, v74, v80
	v_mul_f32_e32 v75, v75, v81
	v_mul_f32_e32 v82, v82, v84
	v_mul_f32_e32 v83, v83, v85
	v_and_b32_sdwa v78, v75, v206 dst_sel:DWORD dst_unused:UNUSED_PAD src0_sel:WORD_1 src1_sel:DWORD
	v_and_b32_sdwa v79, v74, v206 dst_sel:DWORD dst_unused:UNUSED_PAD src0_sel:WORD_1 src1_sel:DWORD
	v_and_b32_sdwa v76, v83, v206 dst_sel:DWORD dst_unused:UNUSED_PAD src0_sel:WORD_1 src1_sel:DWORD
	v_and_b32_sdwa v77, v82, v206 dst_sel:DWORD dst_unused:UNUSED_PAD src0_sel:WORD_1 src1_sel:DWORD
	v_add3_u32 v75, v75, v78, s0
	v_add3_u32 v74, v74, v79, s0
	v_add3_u32 v77, v82, v77, s0
	v_add3_u32 v76, v83, v76, s0
	v_and_b32_e32 v75, 0xffff0000, v75
	v_and_b32_e32 v74, 0xffff0000, v74
	v_or_b32_sdwa v75, v75, v76 dst_sel:DWORD dst_unused:UNUSED_PAD src0_sel:DWORD src1_sel:WORD_1
	v_or_b32_sdwa v74, v74, v77 dst_sel:DWORD dst_unused:UNUSED_PAD src0_sel:DWORD src1_sel:WORD_1
	global_store_dwordx2 v[90:91], v[74:75], off offset:-1536
	global_load_dwordx4 v[74:77], v[108:109], off
	v_mov_b32_e32 v79, v72
	v_mov_b32_e32 v72, v71
	v_mov_b32_e32 v78, v70
	v_mul_f32_e32 v70, v72, v134
	v_mul_f32_e32 v71, v73, v134
	v_mul_f32_e32 v78, v78, v134
	v_mul_f32_e32 v79, v79, v134
	s_waitcnt vmcnt(0)
	v_mov_b32_e32 v81, v76
	v_mov_b32_e32 v76, v75
	v_mov_b32_e32 v80, v74
	v_mul_f32_e32 v70, v70, v76
	v_mul_f32_e32 v71, v71, v77
	v_mul_f32_e32 v78, v78, v80
	v_mul_f32_e32 v79, v79, v81
	v_and_b32_sdwa v74, v71, v206 dst_sel:DWORD dst_unused:UNUSED_PAD src0_sel:WORD_1 src1_sel:DWORD
	v_and_b32_sdwa v75, v70, v206 dst_sel:DWORD dst_unused:UNUSED_PAD src0_sel:WORD_1 src1_sel:DWORD
	v_and_b32_sdwa v72, v79, v206 dst_sel:DWORD dst_unused:UNUSED_PAD src0_sel:WORD_1 src1_sel:DWORD
	v_and_b32_sdwa v73, v78, v206 dst_sel:DWORD dst_unused:UNUSED_PAD src0_sel:WORD_1 src1_sel:DWORD
	v_add3_u32 v71, v71, v74, s0
	v_add3_u32 v70, v70, v75, s0
	v_add3_u32 v73, v78, v73, s0
	v_add3_u32 v72, v79, v72, s0
	v_and_b32_e32 v71, 0xffff0000, v71
	v_and_b32_e32 v70, 0xffff0000, v70
	v_or_b32_sdwa v71, v71, v72 dst_sel:DWORD dst_unused:UNUSED_PAD src0_sel:DWORD src1_sel:WORD_1
	v_or_b32_sdwa v70, v70, v73 dst_sel:DWORD dst_unused:UNUSED_PAD src0_sel:DWORD src1_sel:WORD_1
	global_store_dwordx2 v[90:91], v[70:71], off offset:-1024
	global_load_dwordx4 v[70:73], v[110:111], off
	v_mov_b32_e32 v75, v68
	v_mov_b32_e32 v68, v67
	v_mov_b32_e32 v74, v66
	v_mul_f32_e32 v66, v68, v134
	v_mul_f32_e32 v67, v69, v134
	v_mul_f32_e32 v74, v74, v134
	v_mul_f32_e32 v75, v75, v134
	s_waitcnt vmcnt(0)
	v_mov_b32_e32 v77, v72
	v_mov_b32_e32 v72, v71
	v_mov_b32_e32 v76, v70
	v_mul_f32_e32 v66, v66, v72
	v_mul_f32_e32 v67, v67, v73
	v_mul_f32_e32 v74, v74, v76
	v_mul_f32_e32 v75, v75, v77
	v_and_b32_sdwa v70, v67, v206 dst_sel:DWORD dst_unused:UNUSED_PAD src0_sel:WORD_1 src1_sel:DWORD
	v_and_b32_sdwa v71, v66, v206 dst_sel:DWORD dst_unused:UNUSED_PAD src0_sel:WORD_1 src1_sel:DWORD
	v_and_b32_sdwa v68, v75, v206 dst_sel:DWORD dst_unused:UNUSED_PAD src0_sel:WORD_1 src1_sel:DWORD
	v_and_b32_sdwa v69, v74, v206 dst_sel:DWORD dst_unused:UNUSED_PAD src0_sel:WORD_1 src1_sel:DWORD
	v_add3_u32 v67, v67, v70, s0
	v_add3_u32 v66, v66, v71, s0
	v_add3_u32 v69, v74, v69, s0
	v_add3_u32 v68, v75, v68, s0
	v_and_b32_e32 v67, 0xffff0000, v67
	v_and_b32_e32 v66, 0xffff0000, v66
	v_or_b32_sdwa v67, v67, v68 dst_sel:DWORD dst_unused:UNUSED_PAD src0_sel:DWORD src1_sel:WORD_1
	v_or_b32_sdwa v66, v66, v69 dst_sel:DWORD dst_unused:UNUSED_PAD src0_sel:DWORD src1_sel:WORD_1
	global_store_dwordx2 v[90:91], v[66:67], off offset:-512
; template <int NR>
; __device__ __forceinline__ void norm_add_rows(const bf16_t* __restrict__ Yb, const float* xi, float* xo, const float* __restrict__ gpost,
;                                               const float* __restrict__ gpre, bf16_t* __restrict__ Hb, int row0, int rstride, int lane) {
;     ...
;     for (int q = 0; q < NR; ++q) { const size_t ro = (size_t)(row0 + q * rstride) * DM;
;         f32x4 y[8]; float ss = 0.f;
; #pragma unroll
;         for (int j = 0; j < 8; ++j) { y[j].x = __uint_as_float(yb[q][j].x << 16); y[j].y = __uint_as_float(yb[q][j].x & 0xffff0000u); y[j].z = __uint_as_float(yb[q][j].y << 16); y[j].w = __uint_as_float(yb[q][j].y & 0xffff0000u);
;             ss += (y[j].x * y[j].x + y[j].y * y[j].y) + (y[j].z * y[j].z + y[j].w * y[j].w); }
;         const float rs = rsqrtf(wave_sum(ss) * (1.0f / DM) + EPS);
;         float ss2 = 0.f;
; #pragma unroll
;         for (int j = 0; j < 8; ++j) { v[q][j] = v[q][j] + y[j] * rs * gp[j]; ((f32x4*)(xo + ro))[lane + 64 * j] = v[q][j];
.LBB0_663:
	s_nop 0
	v_and_b32_e32 v67, 0xffff0000, v132
	v_and_b32_e32 v69, 0xffff0000, v133
	v_lshlrev_b32_e32 v66, 16, v132
	v_lshlrev_b32_e32 v68, 16, v133
	v_mul_f32_e32 v70, v67, v67
	v_mul_f32_e32 v71, v69, v69
	v_fmac_f32_e32 v70, v66, v66
	v_fmac_f32_e32 v71, v68, v68
	v_add_f32_e32 v74, v70, v71
	v_and_b32_e32 v71, 0xffff0000, v130
	v_and_b32_e32 v73, 0xffff0000, v131
	v_lshlrev_b32_e32 v70, 16, v130
	v_lshlrev_b32_e32 v72, 16, v131
	v_mul_f32_e32 v75, v71, v71
	v_mul_f32_e32 v76, v73, v73
	v_fmac_f32_e32 v75, v70, v70
	v_fmac_f32_e32 v76, v72, v72
	v_add_f32_e32 v75, v75, v76
	v_add_f32_e32 v78, v74, v75
	v_and_b32_e32 v75, 0xffff0000, v128
	v_and_b32_e32 v77, 0xffff0000, v129
	v_lshlrev_b32_e32 v74, 16, v128
	v_lshlrev_b32_e32 v76, 16, v129
	v_mul_f32_e32 v79, v75, v75
	v_mul_f32_e32 v80, v77, v77
	v_fmac_f32_e32 v79, v74, v74
	v_fmac_f32_e32 v80, v76, v76
	v_add_f32_e32 v79, v79, v80
	v_add_f32_e32 v82, v78, v79
	v_and_b32_e32 v79, 0xffff0000, v126
	v_and_b32_e32 v81, 0xffff0000, v127
	v_lshlrev_b32_e32 v78, 16, v126
	v_lshlrev_b32_e32 v80, 16, v127
	v_mul_f32_e32 v83, v79, v79
	v_mul_f32_e32 v84, v81, v81
	v_fmac_f32_e32 v83, v78, v78
	v_fmac_f32_e32 v84, v80, v80
	v_add_f32_e32 v83, v83, v84
	v_add_f32_e32 v86, v82, v83
	v_and_b32_e32 v83, 0xffff0000, v124
	v_and_b32_e32 v85, 0xffff0000, v125
	v_lshlrev_b32_e32 v82, 16, v124
	v_lshlrev_b32_e32 v84, 16, v125
	v_mul_f32_e32 v87, v83, v83
	v_mul_f32_e32 v88, v85, v85
	v_fmac_f32_e32 v87, v82, v82
	v_fmac_f32_e32 v88, v84, v84
	v_add_f32_e32 v87, v87, v88
	v_add_f32_e32 v90, v86, v87
	v_and_b32_e32 v87, 0xffff0000, v122
	v_and_b32_e32 v89, 0xffff0000, v123
	v_lshlrev_b32_e32 v86, 16, v122
	v_lshlrev_b32_e32 v88, 16, v123
	v_mul_f32_e32 v91, v87, v87
	v_mul_f32_e32 v92, v89, v89
	v_fmac_f32_e32 v91, v86, v86
	v_fmac_f32_e32 v92, v88, v88
	v_add_f32_e32 v91, v91, v92
	v_add_f32_e32 v94, v90, v91
	v_and_b32_e32 v91, 0xffff0000, v120
	v_and_b32_e32 v93, 0xffff0000, v121
	v_lshlrev_b32_e32 v90, 16, v120
	v_lshlrev_b32_e32 v92, 16, v121
	v_mul_f32_e32 v95, v91, v91
	v_mul_f32_e32 v96, v93, v93
	v_fmac_f32_e32 v95, v90, v90
	v_fmac_f32_e32 v96, v92, v92
	v_add_f32_e32 v95, v95, v96
	v_add_f32_e32 v120, v94, v95
	v_and_b32_e32 v95, 0xffff0000, v118
	v_and_b32_e32 v97, 0xffff0000, v119
	v_lshlrev_b32_e32 v94, 16, v118
	v_lshlrev_b32_e32 v96, 16, v119
	v_mul_f32_e32 v118, v95, v95
	v_mul_f32_e32 v119, v97, v97
	v_fmac_f32_e32 v118, v94, v94
	v_fmac_f32_e32 v119, v96, v96
	v_add_f32_e32 v118, v118, v119
	v_add_f32_e32 v118, v120, v118
	ds_swizzle_b32 v119, v118 offset:swizzle(SWAP,1)
	s_lshl_b64 s[30:31], s[30:31], 11
	s_lshl_b64 s[10:11], s[30:31], 2
	s_add_u32 s10, s16, s10
	s_addc_u32 s11, s17, s11
	s_waitcnt lgkmcnt(0)
	v_add_f32_e32 v118, v118, v119
	ds_swizzle_b32 v119, v118 offset:swizzle(SWAP,2)
	s_waitcnt lgkmcnt(0)
	v_add_f32_e32 v118, v118, v119
	ds_swizzle_b32 v119, v118 offset:swizzle(SWAP,4)
	s_waitcnt lgkmcnt(0)
	v_add_f32_e32 v118, v118, v119
	ds_swizzle_b32 v119, v118 offset:swizzle(SWAP,8)
	s_waitcnt lgkmcnt(0)
	v_add_f32_e32 v118, v118, v119
	ds_swizzle_b32 v119, v118 offset:swizzle(SWAP,16)
	s_waitcnt lgkmcnt(0)
	v_add_f32_e32 v118, v118, v119
	v_mov_b32_e32 v119, v118
	s_nop 1
	v_permlane32_swap_b32_e32 v118, v119
	v_add_f32_e32 v118, v118, v119
	v_fmamk_f32 v118, v118, 0x3a000000, v177
	v_cmp_gt_f32_e32 vcc, s35, v118
	v_mul_f32_e32 v119, 0x4b800000, v118
	s_nop 0
	v_cndmask_b32_e32 v118, v118, v119, vcc
	v_rsq_f32_e32 v118, v118
	s_nop 0
	v_mul_f32_e32 v119, 0x45800000, v118
	v_cndmask_b32_e32 v118, v118, v119, vcc
	v_mul_f32_e32 v66, v66, v118
	v_mul_f32_e32 v67, v67, v118
	v_mul_f32_e32 v68, v68, v118
	v_mul_f32_e32 v69, v69, v118
	v_fma_f32 v62, v2, v66, v62
	v_fma_f32 v63, v3, v67, v63
	v_fma_f32 v64, v4, v68, v64
	v_fma_f32 v65, v5, v69, v65
	v_mul_f32_e32 v66, v70, v118
	v_mul_f32_e32 v67, v71, v118
	v_mul_f32_e32 v68, v72, v118
	v_mul_f32_e32 v69, v73, v118
	v_fma_f32 v58, v6, v66, v58
	v_fma_f32 v59, v7, v67, v59
	v_fma_f32 v60, v8, v68, v60
	v_fma_f32 v61, v9, v69, v61
	v_mul_f32_e32 v66, v74, v118
	v_mul_f32_e32 v67, v75, v118
	v_mul_f32_e32 v68, v76, v118
	v_mul_f32_e32 v69, v77, v118
	v_fma_f32 v54, v10, v66, v54
	v_fma_f32 v55, v11, v67, v55
	v_fma_f32 v56, v12, v68, v56
	v_fma_f32 v57, v13, v69, v57
	v_mul_f32_e32 v66, v78, v118
	v_mul_f32_e32 v67, v79, v118
	v_mul_f32_e32 v68, v80, v118
	v_mul_f32_e32 v69, v81, v118
	v_fma_f32 v50, v14, v66, v50
	v_fma_f32 v51, v15, v67, v51
	v_fma_f32 v52, v16, v68, v52
	v_fma_f32 v53, v17, v69, v53
	v_mul_f32_e32 v66, v82, v118
	v_mul_f32_e32 v67, v83, v118
	v_mul_f32_e32 v68, v84, v118
	v_mul_f32_e32 v69, v85, v118
	s_waitcnt vmcnt(11)
	v_fma_f32 v46, v18, v66, v46
	v_fma_f32 v47, v19, v67, v47
	v_fma_f32 v48, v20, v68, v48
	v_fma_f32 v49, v21, v69, v49
	v_mul_f32_e32 v66, v86, v118
	v_mul_f32_e32 v67, v87, v118
	v_mul_f32_e32 v68, v88, v118
	v_mul_f32_e32 v69, v89, v118
	s_waitcnt vmcnt(10)
	v_fma_f32 v42, v22, v66, v42
	v_fma_f32 v43, v23, v67, v43
	v_fma_f32 v44, v24, v68, v44
	v_fma_f32 v45, v25, v69, v45
	v_mul_f32_e32 v66, v90, v118
	v_mul_f32_e32 v67, v91, v118
	v_mul_f32_e32 v68, v92, v118
	v_mul_f32_e32 v69, v93, v118
	s_waitcnt vmcnt(9)
	v_fma_f32 v38, v26, v66, v38
	v_fma_f32 v39, v27, v67, v39
	v_fma_f32 v40, v28, v68, v40
	v_fma_f32 v41, v29, v69, v41
	v_mul_f32_e32 v66, v94, v118
	v_mul_f32_e32 v67, v95, v118
	v_mul_f32_e32 v68, v96, v118
	v_mul_f32_e32 v69, v97, v118
	s_waitcnt vmcnt(8)
	v_fma_f32 v34, v30, v66, v34
	v_fma_f32 v35, v31, v67, v35
	v_fma_f32 v36, v32, v68, v36
	v_fma_f32 v37, v33, v69, v37
	s_and_b64 vcc, exec, s[6:7]
	global_store_dwordx4 v137, v[62:65], s[10:11]
	global_store_dwordx4 v137, v[58:61], s[10:11] offset:1024
	global_store_dwordx4 v137, v[54:57], s[10:11] offset:2048
	global_store_dwordx4 v137, v[50:53], s[10:11] offset:3072
	global_store_dwordx4 v99, v[46:49], s[10:11]
	global_store_dwordx4 v101, v[42:45], s[10:11]
	global_store_dwordx4 v135, v[38:41], s[10:11]
	global_store_dwordx4 v136, v[34:37], s[10:11]
	s_cbranch_vccnz .LBB0_660
; __device__ __forceinline__ unsigned pk2(float lo, float hi) { return f2bf(lo) | (f2bf(hi) << 16); }
; template <int NR>
; __device__ __forceinline__ void norm_add_rows(const bf16_t* __restrict__ Yb, const float* xi, float* xo, const float* __restrict__ gpost,
;                                               const float* __restrict__ gpre, bf16_t* __restrict__ Hb, int row0, int rstride, int lane) {
;     ...
;         float ss2 = 0.f;
; #pragma unroll
;         for (int j = 0; j < 8; ++j) { v[q][j] = v[q][j] + y[j] * rs * gp[j]; ((f32x4*)(xo + ro))[lane + 64 * j] = v[q][j];
;             ss2 += (v[q][j].x * v[q][j].x + v[q][j].y * v[q][j].y) + (v[q][j].z * v[q][j].z + v[q][j].w * v[q][j].w); }
;         if (gpre) {
;             const float rs2 = rsqrtf(wave_sum(ss2) * (1.0f / DM) + EPS);
; #pragma unroll
;             for (int j = 0; j < 8; ++j) { const f32x4 gg = ((const f32x4*)gpre)[lane + 64 * j];
;                 u32x2 w; w.x = pk2(v[q][j].x * rs2 * gg.x, v[q][j].y * rs2 * gg.y); w.y = pk2(v[q][j].z * rs2 * gg.z, v[q][j].w * rs2 * gg.w); ((u32x2*)(Hb + ro))[lane + 64 * j] = w; }
	v_mul_f32_e32 v66, v63, v63
	v_mul_f32_e32 v67, v65, v65
	v_fmac_f32_e32 v66, v62, v62
	v_fmac_f32_e32 v67, v64, v64
	v_add_f32_e32 v66, v66, v67
	v_mul_f32_e32 v67, v59, v59
	v_mul_f32_e32 v68, v61, v61
	v_fmac_f32_e32 v67, v58, v58
	v_fmac_f32_e32 v68, v60, v60
	v_add_f32_e32 v67, v67, v68
	v_add_f32_e32 v66, v66, v67
	v_mul_f32_e32 v67, v55, v55
	v_mul_f32_e32 v68, v57, v57
	v_fmac_f32_e32 v67, v54, v54
	v_fmac_f32_e32 v68, v56, v56
	v_add_f32_e32 v67, v67, v68
	v_add_f32_e32 v66, v67, v66
	v_mul_f32_e32 v67, v51, v51
	v_mul_f32_e32 v68, v53, v53
	v_fmac_f32_e32 v67, v50, v50
	v_fmac_f32_e32 v68, v52, v52
	v_add_f32_e32 v67, v67, v68
	v_add_f32_e32 v66, v67, v66
	v_mul_f32_e32 v67, v47, v47
	v_mul_f32_e32 v68, v49, v49
	v_fmac_f32_e32 v67, v46, v46
	v_fmac_f32_e32 v68, v48, v48
	v_add_f32_e32 v67, v67, v68
	v_add_f32_e32 v66, v67, v66
	v_mul_f32_e32 v67, v43, v43
	v_mul_f32_e32 v68, v45, v45
	v_fmac_f32_e32 v67, v42, v42
	v_fmac_f32_e32 v68, v44, v44
	v_add_f32_e32 v67, v67, v68
	v_add_f32_e32 v66, v67, v66
	v_mul_f32_e32 v67, v39, v39
	v_mul_f32_e32 v68, v41, v41
	v_fmac_f32_e32 v67, v38, v38
	v_fmac_f32_e32 v68, v40, v40
	v_add_f32_e32 v67, v67, v68
	v_add_f32_e32 v66, v67, v66
	v_mul_f32_e32 v67, v35, v35
	v_mul_f32_e32 v68, v37, v37
	v_fmac_f32_e32 v67, v34, v34
	v_fmac_f32_e32 v68, v36, v36
	v_add_f32_e32 v67, v67, v68
	global_load_dwordx4 v[68:71], v[102:103], off
	v_add_f32_e32 v66, v67, v66
	ds_swizzle_b32 v67, v66 offset:swizzle(SWAP,1)
	v_mov_b32_e32 v73, v64
	v_mov_b32_e32 v64, v63
	v_mov_b32_e32 v72, v62
	s_waitcnt lgkmcnt(0)
	v_add_f32_e32 v66, v66, v67
	ds_swizzle_b32 v67, v66 offset:swizzle(SWAP,2)
	s_waitcnt lgkmcnt(0)
	v_add_f32_e32 v66, v66, v67
	ds_swizzle_b32 v67, v66 offset:swizzle(SWAP,4)
	s_waitcnt lgkmcnt(0)
	v_add_f32_e32 v66, v66, v67
	ds_swizzle_b32 v67, v66 offset:swizzle(SWAP,8)
	s_waitcnt lgkmcnt(0)
	v_add_f32_e32 v66, v66, v67
	ds_swizzle_b32 v67, v66 offset:swizzle(SWAP,16)
	s_waitcnt lgkmcnt(0)
	v_add_f32_e32 v66, v66, v67
	v_mov_b32_e32 v67, v66
	s_nop 1
	v_permlane32_swap_b32_e32 v66, v67
	v_add_f32_e32 v66, v66, v67
	v_fmamk_f32 v66, v66, 0x3a000000, v177
	v_cmp_gt_f32_e32 vcc, s35, v66
	v_mul_f32_e32 v67, 0x4b800000, v66
	s_waitcnt vmcnt(0)
	v_mov_b32_e32 v75, v70
	v_cndmask_b32_e32 v66, v66, v67, vcc
	v_rsq_f32_e32 v66, v66
	v_mov_b32_e32 v70, v69
	v_mov_b32_e32 v74, v68
	v_mul_f32_e32 v67, 0x45800000, v66
	v_cndmask_b32_e32 v66, v66, v67, vcc
	v_mul_f32_e32 v62, v64, v66
	v_mul_f32_e32 v63, v65, v66
	v_mul_f32_e32 v72, v72, v66
	v_mul_f32_e32 v73, v73, v66
	v_mul_f32_e32 v62, v70, v62
	v_mul_f32_e32 v63, v71, v63
	v_mul_f32_e32 v72, v74, v72
	v_mul_f32_e32 v73, v75, v73
	v_and_b32_sdwa v68, v62, v206 dst_sel:DWORD dst_unused:UNUSED_PAD src0_sel:WORD_1 src1_sel:DWORD
	v_add3_u32 v62, v62, v68, s0
	global_load_dwordx4 v[68:71], v[102:103], off offset:1024
	v_and_b32_sdwa v65, v72, v206 dst_sel:DWORD dst_unused:UNUSED_PAD src0_sel:WORD_1 src1_sel:DWORD
	v_add3_u32 v67, v72, v65, s0
	v_and_b32_sdwa v65, v63, v206 dst_sel:DWORD dst_unused:UNUSED_PAD src0_sel:WORD_1 src1_sel:DWORD
	v_and_b32_sdwa v64, v73, v206 dst_sel:DWORD dst_unused:UNUSED_PAD src0_sel:WORD_1 src1_sel:DWORD
	v_add3_u32 v63, v63, v65, s0
	v_add3_u32 v64, v73, v64, s0
	v_and_b32_e32 v63, 0xffff0000, v63
	v_and_b32_e32 v62, 0xffff0000, v62
	v_or_b32_sdwa v65, v63, v64 dst_sel:DWORD dst_unused:UNUSED_PAD src0_sel:DWORD src1_sel:WORD_1
	v_or_b32_sdwa v64, v62, v67 dst_sel:DWORD dst_unused:UNUSED_PAD src0_sel:DWORD src1_sel:WORD_1
	v_lshl_add_u64 v[62:63], s[30:31], 1, v[114:115]
	global_store_dwordx2 v[62:63], v[64:65], off
	v_mov_b32_e32 v64, v58
	v_mov_b32_e32 v65, v60
	v_mul_f32_e32 v64, v64, v66
	v_mul_f32_e32 v65, v65, v66
	v_mov_b32_e32 v60, v59
	v_mul_f32_e32 v58, v60, v66
	v_mul_f32_e32 v59, v61, v66
	s_waitcnt vmcnt(1)
	v_mov_b32_e32 v72, v68
	v_mov_b32_e32 v73, v70
	v_mul_f32_e32 v64, v72, v64
	v_mul_f32_e32 v65, v73, v65
	v_mov_b32_e32 v70, v69
	v_mul_f32_e32 v58, v70, v58
	v_mul_f32_e32 v59, v71, v59
	v_and_b32_sdwa v60, v65, v206 dst_sel:DWORD dst_unused:UNUSED_PAD src0_sel:WORD_1 src1_sel:DWORD
	v_and_b32_sdwa v61, v64, v206 dst_sel:DWORD dst_unused:UNUSED_PAD src0_sel:WORD_1 src1_sel:DWORD
	v_add3_u32 v61, v64, v61, s0
	v_add3_u32 v60, v65, v60, s0
	v_and_b32_sdwa v64, v59, v206 dst_sel:DWORD dst_unused:UNUSED_PAD src0_sel:WORD_1 src1_sel:DWORD
	v_and_b32_sdwa v65, v58, v206 dst_sel:DWORD dst_unused:UNUSED_PAD src0_sel:WORD_1 src1_sel:DWORD
	v_add3_u32 v59, v59, v64, s0
	v_add3_u32 v58, v58, v65, s0
	v_and_b32_e32 v59, 0xffff0000, v59
	v_and_b32_e32 v58, 0xffff0000, v58
	v_or_b32_sdwa v59, v59, v60 dst_sel:DWORD dst_unused:UNUSED_PAD src0_sel:DWORD src1_sel:WORD_1
	v_or_b32_sdwa v58, v58, v61 dst_sel:DWORD dst_unused:UNUSED_PAD src0_sel:DWORD src1_sel:WORD_1
	global_store_dwordx2 v[62:63], v[58:59], off offset:512
	global_load_dwordx4 v[58:61], v[102:103], off offset:2048
	v_mov_b32_e32 v65, v56
	v_mov_b32_e32 v56, v55
	v_mov_b32_e32 v64, v54
	v_mul_f32_e32 v54, v56, v66
	v_mul_f32_e32 v55, v57, v66
	v_mul_f32_e32 v64, v64, v66
	v_mul_f32_e32 v65, v65, v66
	s_waitcnt vmcnt(0)
; __device__ __forceinline__ unsigned pk2(float lo, float hi) { return f2bf(lo) | (f2bf(hi) << 16); }
; template <int NR>
; __device__ __forceinline__ void norm_add_rows(const bf16_t* __restrict__ Yb, const float* xi, float* xo, const float* __restrict__ gpost,
;                                               const float* __restrict__ gpre, bf16_t* __restrict__ Hb, int row0, int rstride, int lane) {
;     ...
;         if (gpre) {
;             const float rs2 = rsqrtf(wave_sum(ss2) * (1.0f / DM) + EPS);
; #pragma unroll
;             for (int j = 0; j < 8; ++j) { const f32x4 gg = ((const f32x4*)gpre)[lane + 64 * j];
;                 u32x2 w; w.x = pk2(v[q][j].x * rs2 * gg.x, v[q][j].y * rs2 * gg.y); w.y = pk2(v[q][j].z * rs2 * gg.z, v[q][j].w * rs2 * gg.w); ((u32x2*)(Hb + ro))[lane + 64 * j] = w; }
	v_mov_b32_e32 v69, v60
	v_mov_b32_e32 v60, v59
	v_mov_b32_e32 v68, v58
	v_mul_f32_e32 v54, v60, v54
	v_mul_f32_e32 v55, v61, v55
	v_mul_f32_e32 v64, v68, v64
	v_mul_f32_e32 v65, v69, v65
	v_and_b32_sdwa v58, v55, v206 dst_sel:DWORD dst_unused:UNUSED_PAD src0_sel:WORD_1 src1_sel:DWORD
	v_and_b32_sdwa v59, v54, v206 dst_sel:DWORD dst_unused:UNUSED_PAD src0_sel:WORD_1 src1_sel:DWORD
	v_and_b32_sdwa v56, v65, v206 dst_sel:DWORD dst_unused:UNUSED_PAD src0_sel:WORD_1 src1_sel:DWORD
	v_and_b32_sdwa v57, v64, v206 dst_sel:DWORD dst_unused:UNUSED_PAD src0_sel:WORD_1 src1_sel:DWORD
	v_add3_u32 v55, v55, v58, s0
	v_add3_u32 v54, v54, v59, s0
	v_add3_u32 v57, v64, v57, s0
	v_add3_u32 v56, v65, v56, s0
	v_and_b32_e32 v55, 0xffff0000, v55
	v_and_b32_e32 v54, 0xffff0000, v54
	v_or_b32_sdwa v55, v55, v56 dst_sel:DWORD dst_unused:UNUSED_PAD src0_sel:DWORD src1_sel:WORD_1
	v_or_b32_sdwa v54, v54, v57 dst_sel:DWORD dst_unused:UNUSED_PAD src0_sel:DWORD src1_sel:WORD_1
	global_store_dwordx2 v[62:63], v[54:55], off offset:1024
	global_load_dwordx4 v[54:57], v[102:103], off offset:3072
	v_mov_b32_e32 v59, v52
	v_mov_b32_e32 v52, v51
	v_mov_b32_e32 v58, v50
	v_mul_f32_e32 v50, v52, v66
	v_mul_f32_e32 v51, v53, v66
	v_mul_f32_e32 v58, v58, v66
	v_mul_f32_e32 v59, v59, v66
	s_waitcnt vmcnt(0)
	v_mov_b32_e32 v61, v56
	v_mov_b32_e32 v56, v55
	v_mov_b32_e32 v60, v54
	v_mul_f32_e32 v50, v56, v50
	v_mul_f32_e32 v51, v57, v51
	v_mul_f32_e32 v58, v60, v58
	v_mul_f32_e32 v59, v61, v59
	v_and_b32_sdwa v54, v51, v206 dst_sel:DWORD dst_unused:UNUSED_PAD src0_sel:WORD_1 src1_sel:DWORD
	v_and_b32_sdwa v55, v50, v206 dst_sel:DWORD dst_unused:UNUSED_PAD src0_sel:WORD_1 src1_sel:DWORD
	v_and_b32_sdwa v52, v59, v206 dst_sel:DWORD dst_unused:UNUSED_PAD src0_sel:WORD_1 src1_sel:DWORD
	v_and_b32_sdwa v53, v58, v206 dst_sel:DWORD dst_unused:UNUSED_PAD src0_sel:WORD_1 src1_sel:DWORD
	v_add3_u32 v51, v51, v54, s0
	v_add3_u32 v50, v50, v55, s0
	v_add3_u32 v53, v58, v53, s0
	v_add3_u32 v52, v59, v52, s0
	v_and_b32_e32 v51, 0xffff0000, v51
	v_and_b32_e32 v50, 0xffff0000, v50
	v_or_b32_sdwa v51, v51, v52 dst_sel:DWORD dst_unused:UNUSED_PAD src0_sel:DWORD src1_sel:WORD_1
	v_or_b32_sdwa v50, v50, v53 dst_sel:DWORD dst_unused:UNUSED_PAD src0_sel:DWORD src1_sel:WORD_1
	global_store_dwordx2 v[62:63], v[50:51], off offset:1536
	global_load_dwordx4 v[50:53], v[104:105], off
	v_mov_b32_e32 v55, v48
	v_mov_b32_e32 v48, v47
	v_mov_b32_e32 v54, v46
	v_mul_f32_e32 v46, v48, v66
	v_mul_f32_e32 v47, v49, v66
	v_mul_f32_e32 v54, v54, v66
	v_mul_f32_e32 v55, v55, v66
	s_waitcnt vmcnt(0)
	v_mov_b32_e32 v57, v52
	v_mov_b32_e32 v52, v51
	v_mov_b32_e32 v56, v50
	v_mul_f32_e32 v46, v52, v46
	v_mul_f32_e32 v47, v53, v47
	v_mul_f32_e32 v54, v56, v54
	v_mul_f32_e32 v55, v57, v55
	v_and_b32_sdwa v50, v47, v206 dst_sel:DWORD dst_unused:UNUSED_PAD src0_sel:WORD_1 src1_sel:DWORD
	v_and_b32_sdwa v51, v46, v206 dst_sel:DWORD dst_unused:UNUSED_PAD src0_sel:WORD_1 src1_sel:DWORD
	v_and_b32_sdwa v48, v55, v206 dst_sel:DWORD dst_unused:UNUSED_PAD src0_sel:WORD_1 src1_sel:DWORD
	v_and_b32_sdwa v49, v54, v206 dst_sel:DWORD dst_unused:UNUSED_PAD src0_sel:WORD_1 src1_sel:DWORD
	v_add3_u32 v47, v47, v50, s0
	v_add3_u32 v46, v46, v51, s0
	v_add3_u32 v49, v54, v49, s0
	v_add3_u32 v48, v55, v48, s0
	v_and_b32_e32 v47, 0xffff0000, v47
	v_and_b32_e32 v46, 0xffff0000, v46
	v_or_b32_sdwa v47, v47, v48 dst_sel:DWORD dst_unused:UNUSED_PAD src0_sel:DWORD src1_sel:WORD_1
	v_or_b32_sdwa v46, v46, v49 dst_sel:DWORD dst_unused:UNUSED_PAD src0_sel:DWORD src1_sel:WORD_1
	global_store_dwordx2 v[62:63], v[46:47], off offset:2048
	global_load_dwordx4 v[46:49], v[106:107], off
	v_mov_b32_e32 v51, v44
	v_mov_b32_e32 v44, v43
	v_mov_b32_e32 v50, v42
	v_mul_f32_e32 v42, v44, v66
	v_mul_f32_e32 v43, v45, v66
	v_mul_f32_e32 v50, v50, v66
	v_mul_f32_e32 v51, v51, v66
	s_waitcnt vmcnt(0)
; __device__ __forceinline__ unsigned pk2(float lo, float hi) { return f2bf(lo) | (f2bf(hi) << 16); }
; template <int NR>
; __device__ __forceinline__ void norm_add_rows(const bf16_t* __restrict__ Yb, const float* xi, float* xo, const float* __restrict__ gpost,
;                                               const float* __restrict__ gpre, bf16_t* __restrict__ Hb, int row0, int rstride, int lane) {
;     ...
;         if (gpre) {
;             const float rs2 = rsqrtf(wave_sum(ss2) * (1.0f / DM) + EPS);
; #pragma unroll
;             for (int j = 0; j < 8; ++j) { const f32x4 gg = ((const f32x4*)gpre)[lane + 64 * j];
;                 u32x2 w; w.x = pk2(v[q][j].x * rs2 * gg.x, v[q][j].y * rs2 * gg.y); w.y = pk2(v[q][j].z * rs2 * gg.z, v[q][j].w * rs2 * gg.w); ((u32x2*)(Hb + ro))[lane + 64 * j] = w; }
	v_mov_b32_e32 v53, v48
	v_mov_b32_e32 v48, v47
	v_mov_b32_e32 v52, v46
	v_mul_f32_e32 v42, v42, v48
	v_mul_f32_e32 v43, v43, v49
	v_mul_f32_e32 v50, v50, v52
	v_mul_f32_e32 v51, v51, v53
	v_and_b32_sdwa v46, v43, v206 dst_sel:DWORD dst_unused:UNUSED_PAD src0_sel:WORD_1 src1_sel:DWORD
	v_and_b32_sdwa v47, v42, v206 dst_sel:DWORD dst_unused:UNUSED_PAD src0_sel:WORD_1 src1_sel:DWORD
	v_and_b32_sdwa v44, v51, v206 dst_sel:DWORD dst_unused:UNUSED_PAD src0_sel:WORD_1 src1_sel:DWORD
	v_and_b32_sdwa v45, v50, v206 dst_sel:DWORD dst_unused:UNUSED_PAD src0_sel:WORD_1 src1_sel:DWORD
	v_add3_u32 v43, v43, v46, s0
	v_add3_u32 v42, v42, v47, s0
	v_add3_u32 v45, v50, v45, s0
	v_add3_u32 v44, v51, v44, s0
	v_and_b32_e32 v43, 0xffff0000, v43
	v_and_b32_e32 v42, 0xffff0000, v42
	v_or_b32_sdwa v43, v43, v44 dst_sel:DWORD dst_unused:UNUSED_PAD src0_sel:DWORD src1_sel:WORD_1
	v_or_b32_sdwa v42, v42, v45 dst_sel:DWORD dst_unused:UNUSED_PAD src0_sel:DWORD src1_sel:WORD_1
	global_store_dwordx2 v[62:63], v[42:43], off offset:2560
	global_load_dwordx4 v[42:45], v[108:109], off
	v_mov_b32_e32 v47, v40
	v_mov_b32_e32 v40, v39
	v_mov_b32_e32 v46, v38
	v_mul_f32_e32 v38, v40, v66
	v_mul_f32_e32 v39, v41, v66
	v_mul_f32_e32 v46, v46, v66
	v_mul_f32_e32 v47, v47, v66
	s_waitcnt vmcnt(0)
	v_mov_b32_e32 v49, v44
	v_mov_b32_e32 v44, v43
	v_mov_b32_e32 v48, v42
	v_mul_f32_e32 v38, v38, v44
	v_mul_f32_e32 v39, v39, v45
	v_mul_f32_e32 v46, v46, v48
	v_mul_f32_e32 v47, v47, v49
	v_and_b32_sdwa v42, v39, v206 dst_sel:DWORD dst_unused:UNUSED_PAD src0_sel:WORD_1 src1_sel:DWORD
	v_and_b32_sdwa v43, v38, v206 dst_sel:DWORD dst_unused:UNUSED_PAD src0_sel:WORD_1 src1_sel:DWORD
	v_and_b32_sdwa v40, v47, v206 dst_sel:DWORD dst_unused:UNUSED_PAD src0_sel:WORD_1 src1_sel:DWORD
	v_and_b32_sdwa v41, v46, v206 dst_sel:DWORD dst_unused:UNUSED_PAD src0_sel:WORD_1 src1_sel:DWORD
	v_add3_u32 v39, v39, v42, s0
	v_add3_u32 v38, v38, v43, s0
	v_add3_u32 v41, v46, v41, s0
	v_add3_u32 v40, v47, v40, s0
	v_and_b32_e32 v39, 0xffff0000, v39
	v_and_b32_e32 v38, 0xffff0000, v38
	v_or_b32_sdwa v39, v39, v40 dst_sel:DWORD dst_unused:UNUSED_PAD src0_sel:DWORD src1_sel:WORD_1
	v_or_b32_sdwa v38, v38, v41 dst_sel:DWORD dst_unused:UNUSED_PAD src0_sel:DWORD src1_sel:WORD_1
	global_store_dwordx2 v[62:63], v[38:39], off offset:3072
	global_load_dwordx4 v[38:41], v[110:111], off
	v_mov_b32_e32 v43, v36
	v_mov_b32_e32 v36, v35
	v_mov_b32_e32 v42, v34
	v_mul_f32_e32 v34, v36, v66
	v_mul_f32_e32 v35, v37, v66
	v_mul_f32_e32 v42, v42, v66
	v_mul_f32_e32 v43, v43, v66
	s_waitcnt vmcnt(0)
	v_mov_b32_e32 v45, v40
	v_mov_b32_e32 v40, v39
	v_mov_b32_e32 v44, v38
	v_mul_f32_e32 v34, v34, v40
	v_mul_f32_e32 v35, v35, v41
	v_mul_f32_e32 v42, v42, v44
	v_mul_f32_e32 v43, v43, v45
	v_and_b32_sdwa v38, v35, v206 dst_sel:DWORD dst_unused:UNUSED_PAD src0_sel:WORD_1 src1_sel:DWORD
	v_and_b32_sdwa v39, v34, v206 dst_sel:DWORD dst_unused:UNUSED_PAD src0_sel:WORD_1 src1_sel:DWORD
	v_and_b32_sdwa v36, v43, v206 dst_sel:DWORD dst_unused:UNUSED_PAD src0_sel:WORD_1 src1_sel:DWORD
	v_and_b32_sdwa v37, v42, v206 dst_sel:DWORD dst_unused:UNUSED_PAD src0_sel:WORD_1 src1_sel:DWORD
	v_add3_u32 v35, v35, v38, s0
	v_add3_u32 v34, v34, v39, s0
	v_add3_u32 v37, v42, v37, s0
	v_add3_u32 v36, v43, v36, s0
	v_and_b32_e32 v35, 0xffff0000, v35
	v_and_b32_e32 v34, 0xffff0000, v34
	v_or_b32_sdwa v35, v35, v36 dst_sel:DWORD dst_unused:UNUSED_PAD src0_sel:DWORD src1_sel:WORD_1
	v_or_b32_sdwa v34, v34, v37 dst_sel:DWORD dst_unused:UNUSED_PAD src0_sel:DWORD src1_sel:WORD_1
	global_store_dwordx2 v[62:63], v[34:35], off offset:3584
	s_branch .LBB0_660

; template <int NR>
; __device__ __forceinline__ void norm_add_rows(const bf16_t* __restrict__ Yb, const float* xi, float* xo, const float* __restrict__ gpost,
;                                               const float* __restrict__ gpre, bf16_t* __restrict__ Hb, int row0, int rstride, int lane) {
;     ...
;     for (int q = 0; q < NR; ++q) { const size_t ro = (size_t)(row0 + q * rstride) * DM;
; #pragma unroll
;         for (int j = 0; j < 8; ++j) yb[q][j] = ((const u32x2*)(Yb + ro))[lane + 64 * j];
; #pragma unroll
;         for (int j = 0; j < 8; ++j) v[q][j] = ((const f32x4*)(xi + ro))[lane + 64 * j]; }
;     f32x4 gp[8];
; #pragma unroll
;     for (int j = 0; j < 8; ++j) gp[j] = ((const f32x4*)gpost)[lane + 64 * j];
; #pragma unroll
;     for (int q = 0; q < NR; ++q) { const size_t ro = (size_t)(row0 + q * rstride) * DM;
;         f32x4 y[8]; float ss = 0.f;
; #pragma unroll
;         for (int j = 0; j < 8; ++j) { y[j].x = __uint_as_float(yb[q][j].x << 16); y[j].y = __uint_as_float(yb[q][j].x & 0xffff0000u); y[j].z = __uint_as_float(yb[q][j].y << 16); y[j].w = __uint_as_float(yb[q][j].y & 0xffff0000u);
;             ss += (y[j].x * y[j].x + y[j].y * y[j].y) + (y[j].z * y[j].z + y[j].w * y[j].w); }
;         const float rs = rsqrtf(wave_sum(ss) * (1.0f / DM) + EPS);
;         float ss2 = 0.f;
; #pragma unroll
;         for (int j = 0; j < 8; ++j) { v[q][j] = v[q][j] + y[j] * rs * gp[j]; ((f32x4*)(xo + ro))[lane + 64 * j] = v[q][j];
.LBB0_669:
	global_load_dwordx2 v[78:79], v[76:77], off
	global_load_dwordx2 v[82:83], v[76:77], off offset:512
	global_load_dwordx2 v[84:85], v[76:77], off offset:1024
	global_load_dwordx2 v[90:91], v[76:77], off offset:1536
	global_load_dwordx2 v[94:95], v[76:77], off offset:2048
	global_load_dwordx2 v[102:103], v[76:77], off offset:2560
	global_load_dwordx2 v[108:109], v[76:77], off offset:3072
	global_load_dwordx2 v[106:107], v[76:77], off offset:3584
	v_lshl_add_u64 v[34:35], s[18:19], 0, v[0:1]
	global_load_dwordx4 v[62:65], v[34:35], off
	global_load_dwordx4 v[58:61], v[34:35], off offset:1024
	global_load_dwordx4 v[54:57], v[34:35], off offset:2048
	global_load_dwordx4 v[50:53], v[34:35], off offset:3072
	s_movk_i32 s10, 0x1000
	v_add_co_u32_e32 v34, vcc, s10, v34
	s_waitcnt vmcnt(0)
	v_and_b32_e32 v97, 0xffff0000, v78
	v_addc_co_u32_e32 v35, vcc, 0, v35, vcc
	global_load_dwordx4 v[46:49], v[34:35], off
	global_load_dwordx4 v[42:45], v[34:35], off offset:1024
	global_load_dwordx4 v[38:41], v[34:35], off offset:2048
	s_nop 0
	global_load_dwordx4 v[34:37], v[34:35], off offset:3072
	v_and_b32_e32 v101, 0xffff0000, v79
	v_lshlrev_b32_e32 v96, 16, v78
	v_lshlrev_b32_e32 v100, 16, v79
	v_mul_f32_e32 v78, v97, v97
	v_mul_f32_e32 v79, v101, v101
	v_fmac_f32_e32 v78, v96, v96
	v_fmac_f32_e32 v79, v100, v100
	v_add_f32_e32 v86, v78, v79
	v_and_b32_e32 v81, 0xffff0000, v82
	v_and_b32_e32 v79, 0xffff0000, v83
	v_lshlrev_b32_e32 v80, 16, v82
	v_lshlrev_b32_e32 v78, 16, v83
	v_mul_f32_e32 v82, v81, v81
	v_mul_f32_e32 v83, v79, v79
	v_fmac_f32_e32 v82, v80, v80
	v_fmac_f32_e32 v83, v78, v78
	v_add_f32_e32 v82, v82, v83
	v_and_b32_e32 v89, 0xffff0000, v84
	v_and_b32_e32 v87, 0xffff0000, v85
	v_add_f32_e32 v82, v86, v82
	v_lshlrev_b32_e32 v88, 16, v84
	v_lshlrev_b32_e32 v86, 16, v85
	v_mul_f32_e32 v83, v89, v89
	v_mul_f32_e32 v84, v87, v87
	v_fmac_f32_e32 v83, v88, v88
	v_fmac_f32_e32 v84, v86, v86
	v_add_f32_e32 v83, v83, v84
	v_add_f32_e32 v92, v82, v83
	v_and_b32_e32 v85, 0xffff0000, v90
	v_and_b32_e32 v83, 0xffff0000, v91
	v_lshlrev_b32_e32 v84, 16, v90
	v_lshlrev_b32_e32 v82, 16, v91
	v_mul_f32_e32 v90, v85, v85
	v_mul_f32_e32 v91, v83, v83
	v_fmac_f32_e32 v90, v84, v84
	v_fmac_f32_e32 v91, v82, v82
	v_add_f32_e32 v90, v90, v91
	v_and_b32_e32 v93, 0xffff0000, v94
	v_and_b32_e32 v91, 0xffff0000, v95
	v_add_f32_e32 v98, v92, v90
	v_lshlrev_b32_e32 v92, 16, v94
	v_lshlrev_b32_e32 v90, 16, v95
	v_mul_f32_e32 v94, v93, v93
	v_mul_f32_e32 v95, v91, v91
	v_fmac_f32_e32 v94, v92, v92
	v_fmac_f32_e32 v95, v90, v90
	v_add_f32_e32 v94, v94, v95
	v_and_b32_e32 v99, 0xffff0000, v102
	v_and_b32_e32 v95, 0xffff0000, v103
	v_add_f32_e32 v104, v98, v94
	v_lshlrev_b32_e32 v98, 16, v102
	v_lshlrev_b32_e32 v94, 16, v103
	v_mul_f32_e32 v102, v99, v99
	v_mul_f32_e32 v103, v95, v95
	v_fmac_f32_e32 v102, v98, v98
	v_fmac_f32_e32 v103, v94, v94
	v_add_f32_e32 v102, v102, v103
	v_and_b32_e32 v105, 0xffff0000, v108
	v_and_b32_e32 v103, 0xffff0000, v109
	v_add_f32_e32 v110, v104, v102
	v_lshlrev_b32_e32 v104, 16, v108
	v_lshlrev_b32_e32 v102, 16, v109
	v_mul_f32_e32 v108, v105, v105
	v_mul_f32_e32 v109, v103, v103
	v_fmac_f32_e32 v108, v104, v104
	v_fmac_f32_e32 v109, v102, v102
	v_add_f32_e32 v108, v108, v109
	v_add_f32_e32 v110, v110, v108
	v_lshlrev_b32_e32 v108, 16, v106
	v_and_b32_e32 v109, 0xffff0000, v106
	v_lshlrev_b32_e32 v106, 16, v107
	v_and_b32_e32 v107, 0xffff0000, v107
	v_mul_f32_e32 v111, v109, v109
	v_mul_f32_e32 v112, v107, v107
	v_fmac_f32_e32 v111, v108, v108
	v_fmac_f32_e32 v112, v106, v106
	v_add_f32_e32 v111, v111, v112
	v_add_f32_e32 v110, v110, v111
	ds_swizzle_b32 v111, v110 offset:swizzle(SWAP,1)
	s_waitcnt lgkmcnt(0)
	v_add_f32_e32 v110, v110, v111
	ds_swizzle_b32 v111, v110 offset:swizzle(SWAP,2)
	s_waitcnt lgkmcnt(0)
	v_add_f32_e32 v110, v110, v111
	ds_swizzle_b32 v111, v110 offset:swizzle(SWAP,4)
	s_waitcnt lgkmcnt(0)
	v_add_f32_e32 v110, v110, v111
	ds_swizzle_b32 v111, v110 offset:swizzle(SWAP,8)
	s_waitcnt lgkmcnt(0)
	v_add_f32_e32 v110, v110, v111
	ds_swizzle_b32 v111, v110 offset:swizzle(SWAP,16)
	s_waitcnt lgkmcnt(0)
	v_add_f32_e32 v110, v110, v111
	v_mov_b32_e32 v111, v110
	s_nop 1
	v_permlane32_swap_b32_e32 v110, v111
	v_add_f32_e32 v110, v110, v111
	v_fmamk_f32 v110, v110, 0x3a000000, v177
	v_cmp_gt_f32_e32 vcc, s35, v110
	v_mul_f32_e32 v111, 0x4b800000, v110
	s_nop 0
	v_cndmask_b32_e32 v110, v110, v111, vcc
	v_rsq_f32_e32 v110, v110
	s_nop 0
	v_mul_f32_e32 v111, 0x45800000, v110
	v_cndmask_b32_e32 v110, v110, v111, vcc
	v_mul_f32_e32 v80, v80, v110
	v_mul_f32_e32 v81, v81, v110
	v_mul_f32_e32 v78, v78, v110
	v_mul_f32_e32 v79, v79, v110
	v_fma_f32 v58, v6, v80, v58
	v_fma_f32 v59, v7, v81, v59
	v_mul_f32_e32 v80, v86, v110
	v_mul_f32_e32 v81, v87, v110
	v_fma_f32 v60, v8, v78, v60
	v_fma_f32 v61, v9, v79, v61
	v_mul_f32_e32 v78, v88, v110
	v_mul_f32_e32 v79, v89, v110
	v_fma_f32 v56, v12, v80, v56
	v_fma_f32 v57, v13, v81, v57
	v_mul_f32_e32 v80, v82, v110
	v_mul_f32_e32 v81, v83, v110
	v_mul_f32_e32 v96, v96, v110
	v_mul_f32_e32 v97, v97, v110
	v_fma_f32 v54, v10, v78, v54
	v_fma_f32 v55, v11, v79, v55
	v_mul_f32_e32 v78, v84, v110
	v_mul_f32_e32 v79, v85, v110
	v_fma_f32 v52, v16, v80, v52
	v_fma_f32 v53, v17, v81, v53
	v_mul_f32_e32 v80, v90, v110
	v_mul_f32_e32 v81, v91, v110
	v_fma_f32 v62, v2, v96, v62
	v_fma_f32 v63, v3, v97, v63
	v_lshl_add_u64 v[96:97], s[16:17], 0, v[0:1]
	v_fma_f32 v50, v14, v78, v50
	v_fma_f32 v51, v15, v79, v51
	v_mul_f32_e32 v78, v92, v110
	v_mul_f32_e32 v79, v93, v110
	s_waitcnt vmcnt(3)
; __device__ __forceinline__ unsigned pk2(float lo, float hi) { return f2bf(lo) | (f2bf(hi) << 16); }
; template <int NR>
; __device__ __forceinline__ void norm_add_rows(const bf16_t* __restrict__ Yb, const float* xi, float* xo, const float* __restrict__ gpost,
;                                               const float* __restrict__ gpre, bf16_t* __restrict__ Hb, int row0, int rstride, int lane) {
;     ...
;         for (int j = 0; j < 8; ++j) { v[q][j] = v[q][j] + y[j] * rs * gp[j]; ((f32x4*)(xo + ro))[lane + 64 * j] = v[q][j];
;             ss2 += (v[q][j].x * v[q][j].x + v[q][j].y * v[q][j].y) + (v[q][j].z * v[q][j].z + v[q][j].w * v[q][j].w); }
;         if (gpre) {
;             const float rs2 = rsqrtf(wave_sum(ss2) * (1.0f / DM) + EPS);
; #pragma unroll
;             for (int j = 0; j < 8; ++j) { const f32x4 gg = ((const f32x4*)gpre)[lane + 64 * j];
;                 u32x2 w; w.x = pk2(v[q][j].x * rs2 * gg.x, v[q][j].y * rs2 * gg.y); w.y = pk2(v[q][j].z * rs2 * gg.z, v[q][j].w * rs2 * gg.w); ((u32x2*)(Hb + ro))[lane + 64 * j] = w; }
	v_fma_f32 v48, v20, v80, v48
	v_fma_f32 v49, v21, v81, v49
	v_mul_f32_e32 v80, v98, v110
	v_mul_f32_e32 v81, v99, v110
	v_mul_f32_e32 v82, v94, v110
	v_mul_f32_e32 v83, v95, v110
	v_fma_f32 v46, v18, v78, v46
	v_fma_f32 v47, v19, v79, v47
	v_add_co_u32_e32 v78, vcc, s10, v96
	s_waitcnt vmcnt(2)
	v_fma_f32 v44, v24, v82, v44
	v_fma_f32 v45, v25, v83, v45
	v_fma_f32 v42, v22, v80, v42
	v_fma_f32 v43, v23, v81, v43
	v_mul_f32_e32 v80, v104, v110
	v_mul_f32_e32 v81, v105, v110
	v_mul_f32_e32 v82, v102, v110
	v_mul_f32_e32 v83, v103, v110
	v_mul_f32_e32 v100, v100, v110
	v_mul_f32_e32 v101, v101, v110
	v_addc_co_u32_e32 v79, vcc, 0, v97, vcc
	s_waitcnt vmcnt(1)
	v_fma_f32 v40, v28, v82, v40
	v_fma_f32 v41, v29, v83, v41
	v_fma_f32 v38, v26, v80, v38
	v_fma_f32 v39, v27, v81, v39
	v_mul_f32_e32 v80, v108, v110
	v_mul_f32_e32 v81, v109, v110
	v_mul_f32_e32 v82, v106, v110
	v_mul_f32_e32 v83, v107, v110
	v_fma_f32 v64, v4, v100, v64
	v_fma_f32 v65, v5, v101, v65
	s_waitcnt vmcnt(0)
	v_fma_f32 v36, v32, v82, v36
	v_fma_f32 v37, v33, v83, v37
	v_fma_f32 v34, v30, v80, v34
	v_fma_f32 v35, v31, v81, v35
	s_andn2_b64 vcc, exec, s[6:7]
	global_store_dwordx4 v[96:97], v[62:65], off
	global_store_dwordx4 v[96:97], v[58:61], off offset:1024
	global_store_dwordx4 v[96:97], v[54:57], off offset:2048
	global_store_dwordx4 v[96:97], v[50:53], off offset:3072
	global_store_dwordx4 v[78:79], v[46:49], off
	global_store_dwordx4 v[78:79], v[42:45], off offset:1024
	global_store_dwordx4 v[78:79], v[38:41], off offset:2048
	global_store_dwordx4 v[78:79], v[34:37], off offset:3072
	s_cbranch_vccnz .LBB0_668
	v_mul_f32_e32 v78, v63, v63
	v_mul_f32_e32 v79, v65, v65
	v_fmac_f32_e32 v78, v62, v62
	v_fmac_f32_e32 v79, v64, v64
	v_add_f32_e32 v78, v78, v79
	v_mul_f32_e32 v79, v59, v59
	v_mul_f32_e32 v80, v61, v61
	v_fmac_f32_e32 v79, v58, v58
	v_fmac_f32_e32 v80, v60, v60
	v_add_f32_e32 v79, v79, v80
	v_add_f32_e32 v78, v78, v79
	v_mul_f32_e32 v79, v55, v55
	v_mul_f32_e32 v80, v57, v57
	v_fmac_f32_e32 v79, v54, v54
	v_fmac_f32_e32 v80, v56, v56
	v_add_f32_e32 v79, v79, v80
	v_add_f32_e32 v78, v79, v78
	v_mul_f32_e32 v79, v51, v51
	v_mul_f32_e32 v80, v53, v53
	v_fmac_f32_e32 v79, v50, v50
	v_fmac_f32_e32 v80, v52, v52
	v_add_f32_e32 v79, v79, v80
	v_add_f32_e32 v78, v79, v78
	v_mul_f32_e32 v79, v47, v47
	v_mul_f32_e32 v80, v49, v49
	v_fmac_f32_e32 v79, v46, v46
	v_fmac_f32_e32 v80, v48, v48
	v_add_f32_e32 v79, v79, v80
	v_add_f32_e32 v78, v79, v78
	v_mul_f32_e32 v79, v43, v43
	v_mul_f32_e32 v80, v45, v45
	v_fmac_f32_e32 v79, v42, v42
	v_fmac_f32_e32 v80, v44, v44
	v_add_f32_e32 v79, v79, v80
	v_add_f32_e32 v78, v79, v78
	v_mul_f32_e32 v79, v39, v39
	v_mul_f32_e32 v80, v41, v41
	v_fmac_f32_e32 v79, v38, v38
	v_fmac_f32_e32 v80, v40, v40
	v_add_f32_e32 v79, v79, v80
	v_add_f32_e32 v78, v79, v78
	v_mul_f32_e32 v79, v35, v35
	v_mul_f32_e32 v80, v37, v37
	v_fmac_f32_e32 v79, v34, v34
	v_fmac_f32_e32 v80, v36, v36
	v_add_f32_e32 v79, v79, v80
	global_load_dwordx4 v[80:83], v[66:67], off
	v_add_f32_e32 v78, v79, v78
	ds_swizzle_b32 v79, v78 offset:swizzle(SWAP,1)
	v_mov_b32_e32 v85, v64
	v_mov_b32_e32 v64, v63
	v_mov_b32_e32 v84, v62
	s_mov_b32 s10, 0xe7600000
	s_waitcnt lgkmcnt(0)
	v_add_f32_e32 v78, v78, v79
	ds_swizzle_b32 v79, v78 offset:swizzle(SWAP,2)
	s_waitcnt lgkmcnt(0)
	v_add_f32_e32 v78, v78, v79
	ds_swizzle_b32 v79, v78 offset:swizzle(SWAP,4)
	s_waitcnt lgkmcnt(0)
	v_add_f32_e32 v78, v78, v79
	ds_swizzle_b32 v79, v78 offset:swizzle(SWAP,8)
	s_waitcnt lgkmcnt(0)
	v_add_f32_e32 v78, v78, v79
	ds_swizzle_b32 v79, v78 offset:swizzle(SWAP,16)
	s_waitcnt lgkmcnt(0)
	v_add_f32_e32 v78, v78, v79
	v_mov_b32_e32 v79, v78
	s_nop 1
	v_permlane32_swap_b32_e32 v78, v79
	v_add_f32_e32 v78, v78, v79
	v_fmamk_f32 v78, v78, 0x3a000000, v177
	v_cmp_gt_f32_e32 vcc, s35, v78
	v_mul_f32_e32 v79, 0x4b800000, v78
	s_waitcnt vmcnt(0)
	v_mov_b32_e32 v87, v82
	v_cndmask_b32_e32 v78, v78, v79, vcc
	v_rsq_f32_e32 v78, v78
	v_mov_b32_e32 v82, v81
	v_mov_b32_e32 v86, v80
	v_mov_b32_e32 v81, v60
	v_mul_f32_e32 v79, 0x45800000, v78
	v_cndmask_b32_e32 v78, v78, v79, vcc
	v_mul_f32_e32 v62, v64, v78
	v_mul_f32_e32 v63, v65, v78
	v_mul_f32_e32 v84, v84, v78
	v_mul_f32_e32 v85, v85, v78
	v_mul_f32_e32 v62, v82, v62
	v_mul_f32_e32 v63, v83, v63
	v_mul_f32_e32 v84, v86, v84
	v_mul_f32_e32 v85, v87, v85
	v_and_b32_sdwa v79, v63, v206 dst_sel:DWORD dst_unused:UNUSED_PAD src0_sel:WORD_1 src1_sel:DWORD
	v_and_b32_sdwa v64, v85, v206 dst_sel:DWORD dst_unused:UNUSED_PAD src0_sel:WORD_1 src1_sel:DWORD
	v_and_b32_sdwa v80, v62, v206 dst_sel:DWORD dst_unused:UNUSED_PAD src0_sel:WORD_1 src1_sel:DWORD
	v_add3_u32 v63, v63, v79, s0
	v_and_b32_sdwa v65, v84, v206 dst_sel:DWORD dst_unused:UNUSED_PAD src0_sel:WORD_1 src1_sel:DWORD
	v_add3_u32 v64, v85, v64, s0
	v_add3_u32 v62, v62, v80, s0
	v_and_b32_e32 v63, 0xffff0000, v63
	v_add3_u32 v65, v84, v65, s0
	v_and_b32_e32 v62, 0xffff0000, v62
	v_or_b32_sdwa v63, v63, v64 dst_sel:DWORD dst_unused:UNUSED_PAD src0_sel:DWORD src1_sel:WORD_1
	v_add_co_u32_e32 v64, vcc, s10, v76
	v_or_b32_sdwa v62, v62, v65 dst_sel:DWORD dst_unused:UNUSED_PAD src0_sel:DWORD src1_sel:WORD_1
	s_nop 0
	v_addc_co_u32_e32 v65, vcc, -1, v77, vcc
	global_store_dwordx2 v[64:65], v[62:63], off
	global_load_dwordx4 v[62:65], v[66:67], off offset:1024
	v_mov_b32_e32 v80, v58
	v_mul_f32_e32 v80, v80, v78
	v_mul_f32_e32 v81, v81, v78
	v_mov_b32_e32 v60, v59
	v_mul_f32_e32 v58, v60, v78
	v_mul_f32_e32 v59, v61, v78
	s_mov_b32 s10, 0xe7601000
	s_waitcnt vmcnt(0)
; __device__ __forceinline__ unsigned pk2(float lo, float hi) { return f2bf(lo) | (f2bf(hi) << 16); }
; template <int NR>
; __device__ __forceinline__ void norm_add_rows(const bf16_t* __restrict__ Yb, const float* xi, float* xo, const float* __restrict__ gpost,
;                                               const float* __restrict__ gpre, bf16_t* __restrict__ Hb, int row0, int rstride, int lane) {
;     ...
;         if (gpre) {
;             const float rs2 = rsqrtf(wave_sum(ss2) * (1.0f / DM) + EPS);
; #pragma unroll
;             for (int j = 0; j < 8; ++j) { const f32x4 gg = ((const f32x4*)gpre)[lane + 64 * j];
;                 u32x2 w; w.x = pk2(v[q][j].x * rs2 * gg.x, v[q][j].y * rs2 * gg.y); w.y = pk2(v[q][j].z * rs2 * gg.z, v[q][j].w * rs2 * gg.w); ((u32x2*)(Hb + ro))[lane + 64 * j] = w; }
	v_mov_b32_e32 v82, v62
	v_mov_b32_e32 v83, v64
	v_mul_f32_e32 v80, v82, v80
	v_mul_f32_e32 v81, v83, v81
	v_mov_b32_e32 v64, v63
	v_mul_f32_e32 v58, v64, v58
	v_mul_f32_e32 v59, v65, v59
	v_and_b32_sdwa v61, v80, v206 dst_sel:DWORD dst_unused:UNUSED_PAD src0_sel:WORD_1 src1_sel:DWORD
	v_add3_u32 v62, v80, v61, s0
	v_and_b32_sdwa v61, v59, v206 dst_sel:DWORD dst_unused:UNUSED_PAD src0_sel:WORD_1 src1_sel:DWORD
	v_and_b32_sdwa v63, v58, v206 dst_sel:DWORD dst_unused:UNUSED_PAD src0_sel:WORD_1 src1_sel:DWORD
	v_and_b32_sdwa v60, v81, v206 dst_sel:DWORD dst_unused:UNUSED_PAD src0_sel:WORD_1 src1_sel:DWORD
	v_add3_u32 v59, v59, v61, s0
	v_add3_u32 v58, v58, v63, s0
	v_add3_u32 v60, v81, v60, s0
	v_and_b32_e32 v59, 0xffff0000, v59
	v_and_b32_e32 v58, 0xffff0000, v58
	v_or_b32_sdwa v61, v59, v60 dst_sel:DWORD dst_unused:UNUSED_PAD src0_sel:DWORD src1_sel:WORD_1
	v_or_b32_sdwa v60, v58, v62 dst_sel:DWORD dst_unused:UNUSED_PAD src0_sel:DWORD src1_sel:WORD_1
	v_add_co_u32_e32 v58, vcc, s10, v76
	v_mov_b32_e32 v65, v56
	s_nop 0
	v_addc_co_u32_e32 v59, vcc, -1, v77, vcc
	global_store_dwordx2 v[58:59], v[60:61], off offset:-3584
	global_load_dwordx4 v[60:63], v[66:67], off offset:2048
	v_mov_b32_e32 v56, v55
	v_mov_b32_e32 v64, v54
	v_mul_f32_e32 v54, v56, v78
	v_mul_f32_e32 v55, v57, v78
	v_mul_f32_e32 v64, v64, v78
	v_mul_f32_e32 v65, v65, v78
	s_waitcnt vmcnt(0)
	v_mov_b32_e32 v81, v62
	v_mov_b32_e32 v62, v61
	v_mov_b32_e32 v80, v60
	v_mul_f32_e32 v54, v62, v54
	v_mul_f32_e32 v55, v63, v55
	v_mul_f32_e32 v64, v80, v64
	v_mul_f32_e32 v65, v81, v65
	v_and_b32_sdwa v60, v55, v206 dst_sel:DWORD dst_unused:UNUSED_PAD src0_sel:WORD_1 src1_sel:DWORD
	v_and_b32_sdwa v61, v54, v206 dst_sel:DWORD dst_unused:UNUSED_PAD src0_sel:WORD_1 src1_sel:DWORD
	v_and_b32_sdwa v56, v65, v206 dst_sel:DWORD dst_unused:UNUSED_PAD src0_sel:WORD_1 src1_sel:DWORD
	v_and_b32_sdwa v57, v64, v206 dst_sel:DWORD dst_unused:UNUSED_PAD src0_sel:WORD_1 src1_sel:DWORD
	v_add3_u32 v55, v55, v60, s0
	v_add3_u32 v54, v54, v61, s0
	v_add3_u32 v57, v64, v57, s0
	v_add3_u32 v56, v65, v56, s0
	v_and_b32_e32 v55, 0xffff0000, v55
	v_and_b32_e32 v54, 0xffff0000, v54
	v_or_b32_sdwa v55, v55, v56 dst_sel:DWORD dst_unused:UNUSED_PAD src0_sel:DWORD src1_sel:WORD_1
	v_or_b32_sdwa v54, v54, v57 dst_sel:DWORD dst_unused:UNUSED_PAD src0_sel:DWORD src1_sel:WORD_1
	global_store_dwordx2 v[58:59], v[54:55], off offset:-3072
	global_load_dwordx4 v[54:57], v[66:67], off offset:3072
	v_mov_b32_e32 v61, v52
	v_mov_b32_e32 v52, v51
	v_mov_b32_e32 v60, v50
	v_mul_f32_e32 v50, v52, v78
	v_mul_f32_e32 v51, v53, v78
	v_mul_f32_e32 v60, v60, v78
	v_mul_f32_e32 v61, v61, v78
	s_waitcnt vmcnt(0)
	v_mov_b32_e32 v63, v56
	v_mov_b32_e32 v56, v55
	v_mov_b32_e32 v62, v54
	v_mul_f32_e32 v50, v56, v50
	v_mul_f32_e32 v51, v57, v51
	v_mul_f32_e32 v60, v62, v60
	v_mul_f32_e32 v61, v63, v61
	v_and_b32_sdwa v54, v51, v206 dst_sel:DWORD dst_unused:UNUSED_PAD src0_sel:WORD_1 src1_sel:DWORD
	v_and_b32_sdwa v55, v50, v206 dst_sel:DWORD dst_unused:UNUSED_PAD src0_sel:WORD_1 src1_sel:DWORD
	v_and_b32_sdwa v52, v61, v206 dst_sel:DWORD dst_unused:UNUSED_PAD src0_sel:WORD_1 src1_sel:DWORD
	v_and_b32_sdwa v53, v60, v206 dst_sel:DWORD dst_unused:UNUSED_PAD src0_sel:WORD_1 src1_sel:DWORD
	v_add3_u32 v51, v51, v54, s0
	v_add3_u32 v50, v50, v55, s0
	v_add3_u32 v53, v60, v53, s0
	v_add3_u32 v52, v61, v52, s0
	v_and_b32_e32 v51, 0xffff0000, v51
	v_and_b32_e32 v50, 0xffff0000, v50
	v_or_b32_sdwa v51, v51, v52 dst_sel:DWORD dst_unused:UNUSED_PAD src0_sel:DWORD src1_sel:WORD_1
	v_or_b32_sdwa v50, v50, v53 dst_sel:DWORD dst_unused:UNUSED_PAD src0_sel:DWORD src1_sel:WORD_1
	global_store_dwordx2 v[58:59], v[50:51], off offset:-2560
	global_load_dwordx4 v[50:53], v[68:69], off
	v_mov_b32_e32 v55, v48
	v_mov_b32_e32 v48, v47
	v_mov_b32_e32 v54, v46
	v_mul_f32_e32 v46, v48, v78
	v_mul_f32_e32 v47, v49, v78
	v_mul_f32_e32 v54, v54, v78
	v_mul_f32_e32 v55, v55, v78
	s_waitcnt vmcnt(0)
; __device__ __forceinline__ unsigned pk2(float lo, float hi) { return f2bf(lo) | (f2bf(hi) << 16); }
; template <int NR>
; __device__ __forceinline__ void norm_add_rows(const bf16_t* __restrict__ Yb, const float* xi, float* xo, const float* __restrict__ gpost,
;                                               const float* __restrict__ gpre, bf16_t* __restrict__ Hb, int row0, int rstride, int lane) {
;     ...
;         if (gpre) {
;             const float rs2 = rsqrtf(wave_sum(ss2) * (1.0f / DM) + EPS);
; #pragma unroll
;             for (int j = 0; j < 8; ++j) { const f32x4 gg = ((const f32x4*)gpre)[lane + 64 * j];
;                 u32x2 w; w.x = pk2(v[q][j].x * rs2 * gg.x, v[q][j].y * rs2 * gg.y); w.y = pk2(v[q][j].z * rs2 * gg.z, v[q][j].w * rs2 * gg.w); ((u32x2*)(Hb + ro))[lane + 64 * j] = w; }
	v_mov_b32_e32 v57, v52
	v_mov_b32_e32 v52, v51
	v_mov_b32_e32 v56, v50
	v_mul_f32_e32 v46, v52, v46
	v_mul_f32_e32 v47, v53, v47
	v_mul_f32_e32 v54, v56, v54
	v_mul_f32_e32 v55, v57, v55
	v_and_b32_sdwa v50, v47, v206 dst_sel:DWORD dst_unused:UNUSED_PAD src0_sel:WORD_1 src1_sel:DWORD
	v_and_b32_sdwa v51, v46, v206 dst_sel:DWORD dst_unused:UNUSED_PAD src0_sel:WORD_1 src1_sel:DWORD
	v_and_b32_sdwa v48, v55, v206 dst_sel:DWORD dst_unused:UNUSED_PAD src0_sel:WORD_1 src1_sel:DWORD
	v_and_b32_sdwa v49, v54, v206 dst_sel:DWORD dst_unused:UNUSED_PAD src0_sel:WORD_1 src1_sel:DWORD
	v_add3_u32 v47, v47, v50, s0
	v_add3_u32 v46, v46, v51, s0
	v_add3_u32 v49, v54, v49, s0
	v_add3_u32 v48, v55, v48, s0
	v_and_b32_e32 v47, 0xffff0000, v47
	v_and_b32_e32 v46, 0xffff0000, v46
	v_or_b32_sdwa v47, v47, v48 dst_sel:DWORD dst_unused:UNUSED_PAD src0_sel:DWORD src1_sel:WORD_1
	v_or_b32_sdwa v46, v46, v49 dst_sel:DWORD dst_unused:UNUSED_PAD src0_sel:DWORD src1_sel:WORD_1
	global_store_dwordx2 v[58:59], v[46:47], off offset:-2048
	global_load_dwordx4 v[46:49], v[70:71], off
	v_mov_b32_e32 v51, v44
	v_mov_b32_e32 v44, v43
	v_mov_b32_e32 v50, v42
	v_mul_f32_e32 v42, v44, v78
	v_mul_f32_e32 v43, v45, v78
	v_mul_f32_e32 v50, v50, v78
	v_mul_f32_e32 v51, v51, v78
	s_waitcnt vmcnt(0)
	v_mov_b32_e32 v53, v48
	v_mov_b32_e32 v48, v47
	v_mov_b32_e32 v52, v46
	v_mul_f32_e32 v42, v42, v48
	v_mul_f32_e32 v43, v43, v49
	v_mul_f32_e32 v50, v50, v52
	v_mul_f32_e32 v51, v51, v53
	v_and_b32_sdwa v46, v43, v206 dst_sel:DWORD dst_unused:UNUSED_PAD src0_sel:WORD_1 src1_sel:DWORD
	v_and_b32_sdwa v47, v42, v206 dst_sel:DWORD dst_unused:UNUSED_PAD src0_sel:WORD_1 src1_sel:DWORD
	v_and_b32_sdwa v44, v51, v206 dst_sel:DWORD dst_unused:UNUSED_PAD src0_sel:WORD_1 src1_sel:DWORD
	v_and_b32_sdwa v45, v50, v206 dst_sel:DWORD dst_unused:UNUSED_PAD src0_sel:WORD_1 src1_sel:DWORD
	v_add3_u32 v43, v43, v46, s0
	v_add3_u32 v42, v42, v47, s0
	v_add3_u32 v45, v50, v45, s0
	v_add3_u32 v44, v51, v44, s0
	v_and_b32_e32 v43, 0xffff0000, v43
	v_and_b32_e32 v42, 0xffff0000, v42
	v_or_b32_sdwa v43, v43, v44 dst_sel:DWORD dst_unused:UNUSED_PAD src0_sel:DWORD src1_sel:WORD_1
	v_or_b32_sdwa v42, v42, v45 dst_sel:DWORD dst_unused:UNUSED_PAD src0_sel:DWORD src1_sel:WORD_1
	global_store_dwordx2 v[58:59], v[42:43], off offset:-1536
	global_load_dwordx4 v[42:45], v[72:73], off
	v_mov_b32_e32 v47, v40
	v_mov_b32_e32 v40, v39
	v_mov_b32_e32 v46, v38
	v_mul_f32_e32 v38, v40, v78
	v_mul_f32_e32 v39, v41, v78
	v_mul_f32_e32 v46, v46, v78
	v_mul_f32_e32 v47, v47, v78
	s_waitcnt vmcnt(0)
	v_mov_b32_e32 v49, v44
	v_mov_b32_e32 v44, v43
	v_mov_b32_e32 v48, v42
	v_mul_f32_e32 v38, v38, v44
	v_mul_f32_e32 v39, v39, v45
	v_mul_f32_e32 v46, v46, v48
	v_mul_f32_e32 v47, v47, v49
	v_and_b32_sdwa v42, v39, v206 dst_sel:DWORD dst_unused:UNUSED_PAD src0_sel:WORD_1 src1_sel:DWORD
	v_and_b32_sdwa v43, v38, v206 dst_sel:DWORD dst_unused:UNUSED_PAD src0_sel:WORD_1 src1_sel:DWORD
	v_and_b32_sdwa v40, v47, v206 dst_sel:DWORD dst_unused:UNUSED_PAD src0_sel:WORD_1 src1_sel:DWORD
	v_and_b32_sdwa v41, v46, v206 dst_sel:DWORD dst_unused:UNUSED_PAD src0_sel:WORD_1 src1_sel:DWORD
	v_add3_u32 v39, v39, v42, s0
	v_add3_u32 v38, v38, v43, s0
	v_add3_u32 v41, v46, v41, s0
	v_add3_u32 v40, v47, v40, s0
	v_and_b32_e32 v39, 0xffff0000, v39
	v_and_b32_e32 v38, 0xffff0000, v38
	v_or_b32_sdwa v39, v39, v40 dst_sel:DWORD dst_unused:UNUSED_PAD src0_sel:DWORD src1_sel:WORD_1
	v_or_b32_sdwa v38, v38, v41 dst_sel:DWORD dst_unused:UNUSED_PAD src0_sel:DWORD src1_sel:WORD_1
	global_store_dwordx2 v[58:59], v[38:39], off offset:-1024
	global_load_dwordx4 v[38:41], v[74:75], off
	v_mov_b32_e32 v43, v36
	v_mov_b32_e32 v36, v35
	v_mov_b32_e32 v42, v34
	v_mul_f32_e32 v34, v36, v78
	v_mul_f32_e32 v35, v37, v78
	v_mul_f32_e32 v42, v42, v78
	v_mul_f32_e32 v43, v43, v78
	s_waitcnt vmcnt(0)
	v_mov_b32_e32 v45, v40
	v_mov_b32_e32 v40, v39
	v_mov_b32_e32 v44, v38
	v_mul_f32_e32 v34, v34, v40
	v_mul_f32_e32 v35, v35, v41
	v_mul_f32_e32 v42, v42, v44
	v_mul_f32_e32 v43, v43, v45
	v_and_b32_sdwa v38, v35, v206 dst_sel:DWORD dst_unused:UNUSED_PAD src0_sel:WORD_1 src1_sel:DWORD
	v_and_b32_sdwa v39, v34, v206 dst_sel:DWORD dst_unused:UNUSED_PAD src0_sel:WORD_1 src1_sel:DWORD
	v_and_b32_sdwa v36, v43, v206 dst_sel:DWORD dst_unused:UNUSED_PAD src0_sel:WORD_1 src1_sel:DWORD
	v_and_b32_sdwa v37, v42, v206 dst_sel:DWORD dst_unused:UNUSED_PAD src0_sel:WORD_1 src1_sel:DWORD
	v_add3_u32 v35, v35, v38, s0
	v_add3_u32 v34, v34, v39, s0
	v_add3_u32 v37, v42, v37, s0
	v_add3_u32 v36, v43, v36, s0
	v_and_b32_e32 v35, 0xffff0000, v35
	v_and_b32_e32 v34, 0xffff0000, v34
	v_or_b32_sdwa v35, v35, v36 dst_sel:DWORD dst_unused:UNUSED_PAD src0_sel:DWORD src1_sel:WORD_1
	v_or_b32_sdwa v34, v34, v37 dst_sel:DWORD dst_unused:UNUSED_PAD src0_sel:DWORD src1_sel:WORD_1
	global_store_dwordx2 v[58:59], v[34:35], off offset:-512
	s_branch .LBB0_668

; template <int NR>
; __device__ __forceinline__ void norm_add_rows(const bf16_t* __restrict__ Yb, const float* xi, float* xo, const float* __restrict__ gpost,
;                                               const float* __restrict__ gpre, bf16_t* __restrict__ Hb, int row0, int rstride, int lane) {
;     ...
;     for (int q = 0; q < NR; ++q) { const size_t ro = (size_t)(row0 + q * rstride) * DM;
; #pragma unroll
;         for (int j = 0; j < 8; ++j) yb[q][j] = ((const u32x2*)(Yb + ro))[lane + 64 * j];
; #pragma unroll
;         for (int j = 0; j < 8; ++j) v[q][j] = ((const f32x4*)(xi + ro))[lane + 64 * j]; }
;     f32x4 gp[8];
; #pragma unroll
;     for (int j = 0; j < 8; ++j) gp[j] = ((const f32x4*)gpost)[lane + 64 * j];
; #pragma unroll
;     for (int q = 0; q < NR; ++q) { const size_t ro = (size_t)(row0 + q * rstride) * DM;
;         f32x4 y[8]; float ss = 0.f;
; #pragma unroll
;         for (int j = 0; j < 8; ++j) { y[j].x = __uint_as_float(yb[q][j].x << 16); y[j].y = __uint_as_float(yb[q][j].x & 0xffff0000u); y[j].z = __uint_as_float(yb[q][j].y << 16); y[j].w = __uint_as_float(yb[q][j].y & 0xffff0000u);
;             ss += (y[j].x * y[j].x + y[j].y * y[j].y) + (y[j].z * y[j].z + y[j].w * y[j].w); }
;         const float rs = rsqrtf(wave_sum(ss) * (1.0f / DM) + EPS);
.LBB0_895:
	global_load_dwordx2 v[42:43], v[116:117], off
	global_load_dwordx2 v[44:45], v[116:117], off offset:512
	global_load_dwordx2 v[46:47], v[116:117], off offset:1024
	global_load_dwordx2 v[48:49], v[116:117], off offset:1536
	global_load_dwordx2 v[50:51], v[116:117], off offset:2048
	global_load_dwordx2 v[52:53], v[116:117], off offset:2560
	global_load_dwordx2 v[54:55], v[116:117], off offset:3072
	global_load_dwordx2 v[56:57], v[116:117], off offset:3584
	global_load_dwordx4 v[86:89], v[118:119], off offset:-4096
	global_load_dwordx4 v[90:93], v[118:119], off offset:-3072
	global_load_dwordx4 v[144:147], v[118:119], off offset:-2048
	global_load_dwordx4 v[82:85], v[118:119], off offset:-1024
	global_load_dwordx4 v[78:81], v[118:119], off
	global_load_dwordx4 v[74:77], v[118:119], off offset:1024
	global_load_dwordx4 v[70:73], v[118:119], off offset:2048
	global_load_dwordx4 v[66:69], v[118:119], off offset:3072
	s_ashr_i32 s25, s24, 31
	s_lshl_b64 s[4:5], s[24:25], 12
	v_lshl_add_u64 v[34:35], v[112:113], 0, s[4:5]
	global_load_dwordx2 v[142:143], v[34:35], off
	global_load_dwordx2 v[140:141], v[34:35], off offset:512
	global_load_dwordx2 v[138:139], v[34:35], off offset:1024
	global_load_dwordx2 v[136:137], v[34:35], off offset:1536
	global_load_dwordx2 v[134:135], v[34:35], off offset:2048
	global_load_dwordx2 v[132:133], v[34:35], off offset:2560
	global_load_dwordx2 v[130:131], v[34:35], off offset:3072
	global_load_dwordx2 v[128:129], v[34:35], off offset:3584
	s_lshl_b64 s[18:19], s[24:25], 13
	s_add_u32 s18, s16, s18
	s_addc_u32 s19, s17, s19
	global_load_dwordx4 v[38:41], v0, s[18:19]
	global_load_dwordx4 v[34:37], v0, s[18:19] offset:1024
	s_waitcnt vmcnt(0)
	v_and_b32_e32 v95, 0xffff0000, v42
	v_and_b32_e32 v97, 0xffff0000, v43
	v_and_b32_e32 v149, 0xffff0000, v44
	v_and_b32_e32 v151, 0xffff0000, v45
	v_lshlrev_b32_e32 v94, 16, v42
	v_lshlrev_b32_e32 v96, 16, v43
	v_lshlrev_b32_e32 v148, 16, v44
	v_lshlrev_b32_e32 v150, 16, v45
	v_and_b32_e32 v153, 0xffff0000, v46
	v_and_b32_e32 v155, 0xffff0000, v47
	v_mul_f32_e32 v42, v95, v95
	v_mul_f32_e32 v43, v97, v97
	v_mul_f32_e32 v44, v149, v149
	v_mul_f32_e32 v45, v151, v151
	v_lshlrev_b32_e32 v152, 16, v46
	v_lshlrev_b32_e32 v154, 16, v47
	v_and_b32_e32 v157, 0xffff0000, v48
	v_and_b32_e32 v159, 0xffff0000, v49
	v_mul_f32_e32 v46, v153, v153
	v_mul_f32_e32 v47, v155, v155
	v_fmac_f32_e32 v42, v94, v94
	v_fmac_f32_e32 v43, v96, v96
	v_fmac_f32_e32 v44, v148, v148
	v_fmac_f32_e32 v45, v150, v150
	v_lshlrev_b32_e32 v156, 16, v48
	v_lshlrev_b32_e32 v158, 16, v49
	v_and_b32_e32 v161, 0xffff0000, v50
	v_and_b32_e32 v163, 0xffff0000, v51
	v_mul_f32_e32 v48, v157, v157
	v_mul_f32_e32 v49, v159, v159
	v_fmac_f32_e32 v46, v152, v152
	v_fmac_f32_e32 v47, v154, v154
	v_add_f32_e32 v42, v42, v43
	v_add_f32_e32 v43, v44, v45
	v_lshlrev_b32_e32 v160, 16, v50
	v_lshlrev_b32_e32 v162, 16, v51
	v_and_b32_e32 v165, 0xffff0000, v52
	v_and_b32_e32 v167, 0xffff0000, v53
	v_mul_f32_e32 v50, v161, v161
	v_mul_f32_e32 v51, v163, v163
	v_fmac_f32_e32 v48, v156, v156
	v_fmac_f32_e32 v49, v158, v158
	v_add_f32_e32 v44, v46, v47
	v_add_f32_e32 v42, v42, v43
	v_lshlrev_b32_e32 v164, 16, v52
	v_lshlrev_b32_e32 v166, 16, v53
	v_mul_f32_e32 v52, v165, v165
	v_mul_f32_e32 v53, v167, v167
	v_fmac_f32_e32 v50, v160, v160
	v_fmac_f32_e32 v51, v162, v162
	v_add_f32_e32 v45, v48, v49
	v_add_f32_e32 v42, v42, v44
	v_fmac_f32_e32 v52, v164, v164
	v_add_f32_e32 v46, v50, v51
	v_add_f32_e32 v42, v42, v45
	v_fmac_f32_e32 v53, v166, v166
	v_add_f32_e32 v42, v42, v46
	v_add_f32_e32 v43, v52, v53
	v_and_b32_e32 v169, 0xffff0000, v54
	v_and_b32_e32 v171, 0xffff0000, v55
	v_add_f32_e32 v42, v42, v43
	v_lshlrev_b32_e32 v168, 16, v54
	v_lshlrev_b32_e32 v170, 16, v55
	v_mul_f32_e32 v43, v169, v169
	v_mul_f32_e32 v44, v171, v171
	v_fmac_f32_e32 v43, v168, v168
	v_fmac_f32_e32 v44, v170, v170
	v_add_f32_e32 v43, v43, v44
	v_and_b32_e32 v173, 0xffff0000, v56
	v_and_b32_e32 v175, 0xffff0000, v57
	v_add_f32_e32 v42, v42, v43
	v_lshlrev_b32_e32 v172, 16, v56
	v_lshlrev_b32_e32 v174, 16, v57
	v_mul_f32_e32 v43, v173, v173
	v_mul_f32_e32 v44, v175, v175
	v_fmac_f32_e32 v43, v172, v172
	v_fmac_f32_e32 v44, v174, v174
	v_add_f32_e32 v43, v43, v44
	v_add_f32_e32 v42, v42, v43
	ds_swizzle_b32 v43, v42 offset:swizzle(SWAP,1)
	global_load_dwordx4 v[62:65], v0, s[18:19] offset:2048
	global_load_dwordx4 v[58:61], v0, s[18:19] offset:3072
	global_load_dwordx4 v[54:57], v120, s[18:19]
	global_load_dwordx4 v[50:53], v122, s[18:19]
	s_waitcnt lgkmcnt(0)
	v_add_f32_e32 v99, v42, v43
	global_load_dwordx4 v[46:49], v124, s[18:19]
	global_load_dwordx4 v[42:45], v126, s[18:19]
	ds_swizzle_b32 v101, v99 offset:swizzle(SWAP,2)
	s_waitcnt lgkmcnt(0)
	v_add_f32_e32 v99, v99, v101
	ds_swizzle_b32 v101, v99 offset:swizzle(SWAP,4)
	s_waitcnt lgkmcnt(0)
	v_add_f32_e32 v99, v99, v101
	ds_swizzle_b32 v101, v99 offset:swizzle(SWAP,8)
	s_waitcnt lgkmcnt(0)
	v_add_f32_e32 v99, v99, v101
	ds_swizzle_b32 v101, v99 offset:swizzle(SWAP,16)
	s_waitcnt lgkmcnt(0)
; template <int NR>
; __device__ __forceinline__ void norm_add_rows(const bf16_t* __restrict__ Yb, const float* xi, float* xo, const float* __restrict__ gpost,
;                                               const float* __restrict__ gpre, bf16_t* __restrict__ Hb, int row0, int rstride, int lane) {
;     ...
;         const float rs = rsqrtf(wave_sum(ss) * (1.0f / DM) + EPS);
;         float ss2 = 0.f;
; #pragma unroll
;         for (int j = 0; j < 8; ++j) { v[q][j] = v[q][j] + y[j] * rs * gp[j]; ((f32x4*)(xo + ro))[lane + 64 * j] = v[q][j];
;             ss2 += (v[q][j].x * v[q][j].x + v[q][j].y * v[q][j].y) + (v[q][j].z * v[q][j].z + v[q][j].w * v[q][j].w); }
;         if (gpre) {
;             const float rs2 = rsqrtf(wave_sum(ss2) * (1.0f / DM) + EPS);
	v_add_f32_e32 v99, v99, v101
	v_mov_b32_e32 v101, v99
	s_nop 1
	v_permlane32_swap_b32_e32 v99, v101
	v_add_f32_e32 v99, v99, v101
	v_fmamk_f32 v99, v99, 0x3a000000, v177
	v_mul_f32_e32 v101, 0x4b800000, v99
	v_cmp_gt_f32_e32 vcc, s35, v99
	s_nop 1
	v_cndmask_b32_e32 v99, v99, v101, vcc
	v_rsq_f32_e32 v99, v99
	s_nop 0
	v_mul_f32_e32 v101, 0x45800000, v99
	v_cndmask_b32_e32 v176, v99, v101, vcc
	v_mul_f32_e32 v94, v94, v176
	v_mul_f32_e32 v95, v95, v176
	v_mul_f32_e32 v96, v96, v176
	v_mul_f32_e32 v97, v97, v176
	v_fma_f32 v94, v10, v94, v86
	v_fma_f32 v95, v11, v95, v87
	v_fma_f32 v96, v12, v96, v88
	v_fma_f32 v97, v13, v97, v89
	v_mul_f32_e32 v86, v148, v176
	v_mul_f32_e32 v87, v149, v176
	v_mul_f32_e32 v88, v150, v176
	v_mul_f32_e32 v89, v151, v176
	v_fma_f32 v90, v2, v86, v90
	v_fma_f32 v91, v3, v87, v91
	v_fma_f32 v92, v4, v88, v92
	v_fma_f32 v93, v5, v89, v93
	v_mul_f32_e32 v86, v152, v176
	v_mul_f32_e32 v87, v153, v176
	v_mul_f32_e32 v88, v154, v176
	v_mul_f32_e32 v89, v155, v176
	v_fma_f32 v86, v6, v86, v144
	v_fma_f32 v87, v7, v87, v145
	v_fma_f32 v88, v8, v88, v146
	v_fma_f32 v89, v9, v89, v147
	v_mul_f32_e32 v144, v156, v176
	v_mul_f32_e32 v145, v157, v176
	v_mul_f32_e32 v146, v158, v176
	v_mul_f32_e32 v147, v159, v176
	v_fma_f32 v82, v26, v144, v82
	v_fma_f32 v83, v27, v145, v83
	v_fma_f32 v84, v28, v146, v84
	v_fma_f32 v85, v29, v147, v85
	v_mul_f32_e32 v144, v160, v176
	v_mul_f32_e32 v145, v161, v176
	v_mul_f32_e32 v146, v162, v176
	v_mul_f32_e32 v147, v163, v176
	v_fma_f32 v78, v14, v144, v78
	v_fma_f32 v79, v15, v145, v79
	v_fma_f32 v80, v16, v146, v80
	v_fma_f32 v81, v17, v147, v81
	v_mul_f32_e32 v144, v164, v176
	v_mul_f32_e32 v145, v165, v176
	v_mul_f32_e32 v146, v166, v176
	v_mul_f32_e32 v147, v167, v176
	v_fma_f32 v74, v18, v144, v74
	v_fma_f32 v75, v19, v145, v75
	v_fma_f32 v76, v20, v146, v76
	v_fma_f32 v77, v21, v147, v77
	v_mul_f32_e32 v144, v168, v176
	v_mul_f32_e32 v145, v169, v176
	v_mul_f32_e32 v146, v170, v176
	v_mul_f32_e32 v147, v171, v176
	v_fma_f32 v70, v22, v144, v70
	v_fma_f32 v71, v23, v145, v71
	v_fma_f32 v72, v24, v146, v72
	v_fma_f32 v73, v25, v147, v73
	v_mul_f32_e32 v144, v172, v176
	v_mul_f32_e32 v145, v173, v176
	v_mul_f32_e32 v146, v174, v176
	v_mul_f32_e32 v147, v175, v176
	v_cndmask_b32_e64 v99, 0, 1, s[6:7]
	v_fma_f32 v68, v32, v146, v68
	v_fma_f32 v69, v33, v147, v69
	v_fma_f32 v66, v30, v144, v66
	v_fma_f32 v67, v31, v145, v67
	v_cmp_ne_u32_e64 s[4:5], 1, v99
	s_andn2_b64 vcc, exec, s[6:7]
	global_store_dwordx4 v[118:119], v[94:97], off offset:-4096
	global_store_dwordx4 v[118:119], v[90:93], off offset:-3072
	global_store_dwordx4 v[118:119], v[86:89], off offset:-2048
	global_store_dwordx4 v[118:119], v[82:85], off offset:-1024
	global_store_dwordx4 v[118:119], v[78:81], off
	global_store_dwordx4 v[118:119], v[74:77], off offset:1024
	global_store_dwordx4 v[118:119], v[70:73], off offset:2048
	global_store_dwordx4 v[118:119], v[66:69], off offset:3072
	s_cbranch_vccnz .LBB0_897
	global_load_dwordx4 v[146:149], v[102:103], off
	v_mul_f32_e32 v99, v95, v95
	v_mul_f32_e32 v101, v97, v97
	v_fmac_f32_e32 v99, v94, v94
	v_fmac_f32_e32 v101, v96, v96
	v_add_f32_e32 v99, v99, v101
	v_mul_f32_e32 v101, v91, v91
	v_mul_f32_e32 v121, v93, v93
	v_fmac_f32_e32 v101, v90, v90
	v_fmac_f32_e32 v121, v92, v92
	v_add_f32_e32 v101, v101, v121
	v_add_f32_e32 v99, v99, v101
	v_mul_f32_e32 v101, v87, v87
	v_mul_f32_e32 v121, v89, v89
	v_fmac_f32_e32 v101, v86, v86
	v_fmac_f32_e32 v121, v88, v88
	v_add_f32_e32 v101, v101, v121
	v_add_f32_e32 v99, v101, v99
	v_mul_f32_e32 v101, v83, v83
	v_mul_f32_e32 v121, v85, v85
	v_fmac_f32_e32 v101, v82, v82
	v_fmac_f32_e32 v121, v84, v84
	v_add_f32_e32 v101, v101, v121
	v_add_f32_e32 v99, v101, v99
	v_mul_f32_e32 v101, v79, v79
	v_mul_f32_e32 v121, v81, v81
	v_fmac_f32_e32 v101, v78, v78
	v_fmac_f32_e32 v121, v80, v80
	v_add_f32_e32 v101, v101, v121
	v_add_f32_e32 v99, v101, v99
	v_mul_f32_e32 v101, v75, v75
	v_mul_f32_e32 v121, v77, v77
	v_fmac_f32_e32 v101, v74, v74
	v_fmac_f32_e32 v121, v76, v76
	v_add_f32_e32 v101, v101, v121
	v_add_f32_e32 v99, v101, v99
	v_mul_f32_e32 v101, v71, v71
	v_mul_f32_e32 v121, v73, v73
	v_fmac_f32_e32 v101, v70, v70
	v_fmac_f32_e32 v121, v72, v72
	v_add_f32_e32 v101, v101, v121
	v_add_f32_e32 v99, v101, v99
	v_mul_f32_e32 v101, v67, v67
	v_mul_f32_e32 v121, v69, v69
	v_fmac_f32_e32 v101, v66, v66
	v_fmac_f32_e32 v121, v68, v68
	v_add_f32_e32 v101, v101, v121
	v_add_f32_e32 v99, v101, v99
	ds_swizzle_b32 v101, v99 offset:swizzle(SWAP,1)
	v_mov_b32_e32 v151, v96
	v_mov_b32_e32 v96, v95
	v_mov_b32_e32 v150, v94
	s_mov_b32 s11, 0xe7600000
	s_waitcnt lgkmcnt(0)
	v_add_f32_e32 v99, v99, v101
	ds_swizzle_b32 v101, v99 offset:swizzle(SWAP,2)
	s_waitcnt lgkmcnt(0)
	v_add_f32_e32 v99, v99, v101
	ds_swizzle_b32 v101, v99 offset:swizzle(SWAP,4)
	s_waitcnt lgkmcnt(0)
	v_add_f32_e32 v99, v99, v101
	ds_swizzle_b32 v101, v99 offset:swizzle(SWAP,8)
	s_waitcnt lgkmcnt(0)
	v_add_f32_e32 v99, v99, v101
	ds_swizzle_b32 v101, v99 offset:swizzle(SWAP,16)
	s_waitcnt lgkmcnt(0)
	v_add_f32_e32 v99, v99, v101
	v_mov_b32_e32 v101, v99
	s_nop 1
	v_permlane32_swap_b32_e32 v99, v101
	v_add_f32_e32 v99, v99, v101
	v_fmamk_f32 v99, v99, 0x3a000000, v177
	v_cmp_gt_f32_e32 vcc, s35, v99
	v_mul_f32_e32 v101, 0x4b800000, v99
	s_waitcnt vmcnt(0)
; __device__ __forceinline__ unsigned pk2(float lo, float hi) { return f2bf(lo) | (f2bf(hi) << 16); }
; template <int NR>
; __device__ __forceinline__ void norm_add_rows(const bf16_t* __restrict__ Yb, const float* xi, float* xo, const float* __restrict__ gpost,
;                                               const float* __restrict__ gpre, bf16_t* __restrict__ Hb, int row0, int rstride, int lane) {
;     ...
;             const float rs2 = rsqrtf(wave_sum(ss2) * (1.0f / DM) + EPS);
; #pragma unroll
;             for (int j = 0; j < 8; ++j) { const f32x4 gg = ((const f32x4*)gpre)[lane + 64 * j];
;                 u32x2 w; w.x = pk2(v[q][j].x * rs2 * gg.x, v[q][j].y * rs2 * gg.y); w.y = pk2(v[q][j].z * rs2 * gg.z, v[q][j].w * rs2 * gg.w); ((u32x2*)(Hb + ro))[lane + 64 * j] = w; }
	v_mov_b32_e32 v153, v148
	v_cndmask_b32_e32 v99, v99, v101, vcc
	v_rsq_f32_e32 v99, v99
	v_mov_b32_e32 v148, v147
	v_mov_b32_e32 v152, v146
	v_mov_b32_e32 v146, v90
	v_mul_f32_e32 v101, 0x45800000, v99
	v_cndmask_b32_e32 v144, v99, v101, vcc
	v_mul_f32_e32 v94, v96, v144
	v_mul_f32_e32 v95, v97, v144
	v_mul_f32_e32 v150, v150, v144
	v_mul_f32_e32 v151, v151, v144
	v_mul_f32_e32 v94, v148, v94
	v_mul_f32_e32 v95, v149, v95
	v_mul_f32_e32 v150, v152, v150
	v_mul_f32_e32 v151, v153, v151
	v_and_b32_sdwa v99, v95, v206 dst_sel:DWORD dst_unused:UNUSED_PAD src0_sel:WORD_1 src1_sel:DWORD
	v_and_b32_sdwa v96, v151, v206 dst_sel:DWORD dst_unused:UNUSED_PAD src0_sel:WORD_1 src1_sel:DWORD
	v_and_b32_sdwa v101, v94, v206 dst_sel:DWORD dst_unused:UNUSED_PAD src0_sel:WORD_1 src1_sel:DWORD
	v_add3_u32 v95, v95, v99, s0
	v_and_b32_sdwa v97, v150, v206 dst_sel:DWORD dst_unused:UNUSED_PAD src0_sel:WORD_1 src1_sel:DWORD
	v_add3_u32 v96, v151, v96, s0
	v_add3_u32 v94, v94, v101, s0
	v_and_b32_e32 v95, 0xffff0000, v95
	v_add3_u32 v97, v150, v97, s0
	v_and_b32_e32 v94, 0xffff0000, v94
	v_or_b32_sdwa v95, v95, v96 dst_sel:DWORD dst_unused:UNUSED_PAD src0_sel:DWORD src1_sel:WORD_1
	v_add_co_u32_e32 v96, vcc, s11, v116
	v_or_b32_sdwa v94, v94, v97 dst_sel:DWORD dst_unused:UNUSED_PAD src0_sel:DWORD src1_sel:WORD_1
	s_nop 0
	v_addc_co_u32_e32 v97, vcc, -1, v117, vcc
	global_store_dwordx2 v[96:97], v[94:95], off
	global_load_dwordx4 v[94:97], v[102:103], off offset:1024
	v_mov_b32_e32 v147, v92
	v_mul_f32_e32 v146, v146, v144
	v_mul_f32_e32 v147, v147, v144
	v_mov_b32_e32 v92, v91
	v_mul_f32_e32 v90, v92, v144
	v_mul_f32_e32 v91, v93, v144
	s_mov_b32 s11, 0xe7601000
	s_waitcnt vmcnt(0)
	v_mov_b32_e32 v148, v94
	v_mov_b32_e32 v149, v96
	v_mul_f32_e32 v146, v148, v146
	v_mul_f32_e32 v147, v149, v147
	v_mov_b32_e32 v96, v95
	v_mul_f32_e32 v90, v96, v90
	v_mul_f32_e32 v91, v97, v91
	v_and_b32_sdwa v93, v146, v206 dst_sel:DWORD dst_unused:UNUSED_PAD src0_sel:WORD_1 src1_sel:DWORD
	v_add3_u32 v94, v146, v93, s0
	v_and_b32_sdwa v93, v91, v206 dst_sel:DWORD dst_unused:UNUSED_PAD src0_sel:WORD_1 src1_sel:DWORD
	v_and_b32_sdwa v95, v90, v206 dst_sel:DWORD dst_unused:UNUSED_PAD src0_sel:WORD_1 src1_sel:DWORD
	v_and_b32_sdwa v92, v147, v206 dst_sel:DWORD dst_unused:UNUSED_PAD src0_sel:WORD_1 src1_sel:DWORD
	v_add3_u32 v91, v91, v93, s0
	v_add3_u32 v90, v90, v95, s0
	v_add3_u32 v92, v147, v92, s0
	v_and_b32_e32 v91, 0xffff0000, v91
	v_and_b32_e32 v90, 0xffff0000, v90
	v_or_b32_sdwa v93, v91, v92 dst_sel:DWORD dst_unused:UNUSED_PAD src0_sel:DWORD src1_sel:WORD_1
	v_or_b32_sdwa v92, v90, v94 dst_sel:DWORD dst_unused:UNUSED_PAD src0_sel:DWORD src1_sel:WORD_1
	v_add_co_u32_e32 v90, vcc, s11, v116
	v_mov_b32_e32 v97, v88
	s_nop 0
	v_addc_co_u32_e32 v91, vcc, -1, v117, vcc
	global_store_dwordx2 v[90:91], v[92:93], off offset:-3584
	global_load_dwordx4 v[92:95], v[102:103], off offset:2048
	v_mov_b32_e32 v88, v87
	v_mov_b32_e32 v96, v86
	v_mul_f32_e32 v86, v88, v144
	v_mul_f32_e32 v87, v89, v144
	v_mul_f32_e32 v96, v96, v144
	v_mul_f32_e32 v97, v97, v144
	s_waitcnt vmcnt(0)
	v_mov_b32_e32 v147, v94
	v_mov_b32_e32 v94, v93
	v_mov_b32_e32 v146, v92
	v_mul_f32_e32 v86, v94, v86
	v_mul_f32_e32 v87, v95, v87
	v_mul_f32_e32 v96, v146, v96
	v_mul_f32_e32 v97, v147, v97
	v_and_b32_sdwa v92, v87, v206 dst_sel:DWORD dst_unused:UNUSED_PAD src0_sel:WORD_1 src1_sel:DWORD
	v_and_b32_sdwa v93, v86, v206 dst_sel:DWORD dst_unused:UNUSED_PAD src0_sel:WORD_1 src1_sel:DWORD
	v_and_b32_sdwa v88, v97, v206 dst_sel:DWORD dst_unused:UNUSED_PAD src0_sel:WORD_1 src1_sel:DWORD
	v_and_b32_sdwa v89, v96, v206 dst_sel:DWORD dst_unused:UNUSED_PAD src0_sel:WORD_1 src1_sel:DWORD
	v_add3_u32 v87, v87, v92, s0
	v_add3_u32 v86, v86, v93, s0
	v_add3_u32 v89, v96, v89, s0
	v_add3_u32 v88, v97, v88, s0
	v_and_b32_e32 v87, 0xffff0000, v87
	v_and_b32_e32 v86, 0xffff0000, v86
	v_or_b32_sdwa v87, v87, v88 dst_sel:DWORD dst_unused:UNUSED_PAD src0_sel:DWORD src1_sel:WORD_1
	v_or_b32_sdwa v86, v86, v89 dst_sel:DWORD dst_unused:UNUSED_PAD src0_sel:DWORD src1_sel:WORD_1
	global_store_dwordx2 v[90:91], v[86:87], off offset:-3072
	global_load_dwordx4 v[86:89], v[102:103], off offset:3072
	v_mov_b32_e32 v93, v84
	v_mov_b32_e32 v84, v83
	v_mov_b32_e32 v92, v82
	v_mul_f32_e32 v82, v84, v144
	v_mul_f32_e32 v83, v85, v144
	v_mul_f32_e32 v92, v92, v144
	v_mul_f32_e32 v93, v93, v144
	s_waitcnt vmcnt(0)
	v_mov_b32_e32 v95, v88
	v_mov_b32_e32 v88, v87
	v_mov_b32_e32 v94, v86
	v_mul_f32_e32 v82, v88, v82
	v_mul_f32_e32 v83, v89, v83
	v_mul_f32_e32 v92, v94, v92
	v_mul_f32_e32 v93, v95, v93
	v_and_b32_sdwa v86, v83, v206 dst_sel:DWORD dst_unused:UNUSED_PAD src0_sel:WORD_1 src1_sel:DWORD
	v_and_b32_sdwa v87, v82, v206 dst_sel:DWORD dst_unused:UNUSED_PAD src0_sel:WORD_1 src1_sel:DWORD
	v_and_b32_sdwa v84, v93, v206 dst_sel:DWORD dst_unused:UNUSED_PAD src0_sel:WORD_1 src1_sel:DWORD
	v_and_b32_sdwa v85, v92, v206 dst_sel:DWORD dst_unused:UNUSED_PAD src0_sel:WORD_1 src1_sel:DWORD
	v_add3_u32 v83, v83, v86, s0
	v_add3_u32 v82, v82, v87, s0
	v_add3_u32 v85, v92, v85, s0
	v_add3_u32 v84, v93, v84, s0
	v_and_b32_e32 v83, 0xffff0000, v83
	v_and_b32_e32 v82, 0xffff0000, v82
	v_or_b32_sdwa v83, v83, v84 dst_sel:DWORD dst_unused:UNUSED_PAD src0_sel:DWORD src1_sel:WORD_1
	v_or_b32_sdwa v82, v82, v85 dst_sel:DWORD dst_unused:UNUSED_PAD src0_sel:DWORD src1_sel:WORD_1
	global_store_dwordx2 v[90:91], v[82:83], off offset:-2560
	global_load_dwordx4 v[82:85], v[104:105], off
	v_mov_b32_e32 v87, v80
	v_mov_b32_e32 v80, v79
	v_mov_b32_e32 v86, v78
	v_mul_f32_e32 v78, v80, v144
	v_mul_f32_e32 v79, v81, v144
	v_mul_f32_e32 v86, v86, v144
	v_mul_f32_e32 v87, v87, v144
	s_waitcnt vmcnt(0)
; __device__ __forceinline__ unsigned pk2(float lo, float hi) { return f2bf(lo) | (f2bf(hi) << 16); }
; template <int NR>
; __device__ __forceinline__ void norm_add_rows(const bf16_t* __restrict__ Yb, const float* xi, float* xo, const float* __restrict__ gpost,
;                                               const float* __restrict__ gpre, bf16_t* __restrict__ Hb, int row0, int rstride, int lane) {
;     ...
;         if (gpre) {
;             const float rs2 = rsqrtf(wave_sum(ss2) * (1.0f / DM) + EPS);
; #pragma unroll
;             for (int j = 0; j < 8; ++j) { const f32x4 gg = ((const f32x4*)gpre)[lane + 64 * j];
;                 u32x2 w; w.x = pk2(v[q][j].x * rs2 * gg.x, v[q][j].y * rs2 * gg.y); w.y = pk2(v[q][j].z * rs2 * gg.z, v[q][j].w * rs2 * gg.w); ((u32x2*)(Hb + ro))[lane + 64 * j] = w; }
	v_mov_b32_e32 v89, v84
	v_mov_b32_e32 v84, v83
	v_mov_b32_e32 v88, v82
	v_mul_f32_e32 v78, v84, v78
	v_mul_f32_e32 v79, v85, v79
	v_mul_f32_e32 v86, v88, v86
	v_mul_f32_e32 v87, v89, v87
	v_and_b32_sdwa v82, v79, v206 dst_sel:DWORD dst_unused:UNUSED_PAD src0_sel:WORD_1 src1_sel:DWORD
	v_and_b32_sdwa v83, v78, v206 dst_sel:DWORD dst_unused:UNUSED_PAD src0_sel:WORD_1 src1_sel:DWORD
	v_and_b32_sdwa v80, v87, v206 dst_sel:DWORD dst_unused:UNUSED_PAD src0_sel:WORD_1 src1_sel:DWORD
	v_and_b32_sdwa v81, v86, v206 dst_sel:DWORD dst_unused:UNUSED_PAD src0_sel:WORD_1 src1_sel:DWORD
	v_add3_u32 v79, v79, v82, s0
	v_add3_u32 v78, v78, v83, s0
	v_add3_u32 v81, v86, v81, s0
	v_add3_u32 v80, v87, v80, s0
	v_and_b32_e32 v79, 0xffff0000, v79
	v_and_b32_e32 v78, 0xffff0000, v78
	v_or_b32_sdwa v79, v79, v80 dst_sel:DWORD dst_unused:UNUSED_PAD src0_sel:DWORD src1_sel:WORD_1
	v_or_b32_sdwa v78, v78, v81 dst_sel:DWORD dst_unused:UNUSED_PAD src0_sel:DWORD src1_sel:WORD_1
	global_store_dwordx2 v[90:91], v[78:79], off offset:-2048
	global_load_dwordx4 v[78:81], v[106:107], off
	v_mov_b32_e32 v83, v76
	v_mov_b32_e32 v76, v75
	v_mov_b32_e32 v82, v74
	v_mul_f32_e32 v74, v76, v144
	v_mul_f32_e32 v75, v77, v144
	v_mul_f32_e32 v82, v82, v144
	v_mul_f32_e32 v83, v83, v144
	s_waitcnt vmcnt(0)
	v_mov_b32_e32 v85, v80
	v_mov_b32_e32 v80, v79
	v_mov_b32_e32 v84, v78
	v_mul_f32_e32 v74, v74, v80
	v_mul_f32_e32 v75, v75, v81
	v_mul_f32_e32 v82, v82, v84
	v_mul_f32_e32 v83, v83, v85
	v_and_b32_sdwa v78, v75, v206 dst_sel:DWORD dst_unused:UNUSED_PAD src0_sel:WORD_1 src1_sel:DWORD
	v_and_b32_sdwa v79, v74, v206 dst_sel:DWORD dst_unused:UNUSED_PAD src0_sel:WORD_1 src1_sel:DWORD
	v_and_b32_sdwa v76, v83, v206 dst_sel:DWORD dst_unused:UNUSED_PAD src0_sel:WORD_1 src1_sel:DWORD
	v_and_b32_sdwa v77, v82, v206 dst_sel:DWORD dst_unused:UNUSED_PAD src0_sel:WORD_1 src1_sel:DWORD
	v_add3_u32 v75, v75, v78, s0
	v_add3_u32 v74, v74, v79, s0
	v_add3_u32 v77, v82, v77, s0
	v_add3_u32 v76, v83, v76, s0
	v_and_b32_e32 v75, 0xffff0000, v75
	v_and_b32_e32 v74, 0xffff0000, v74
	v_or_b32_sdwa v75, v75, v76 dst_sel:DWORD dst_unused:UNUSED_PAD src0_sel:DWORD src1_sel:WORD_1
	v_or_b32_sdwa v74, v74, v77 dst_sel:DWORD dst_unused:UNUSED_PAD src0_sel:DWORD src1_sel:WORD_1
	global_store_dwordx2 v[90:91], v[74:75], off offset:-1536
	global_load_dwordx4 v[74:77], v[108:109], off
	v_mov_b32_e32 v79, v72
	v_mov_b32_e32 v72, v71
	v_mov_b32_e32 v78, v70
	v_mul_f32_e32 v70, v72, v144
	v_mul_f32_e32 v71, v73, v144
	v_mul_f32_e32 v78, v78, v144
	v_mul_f32_e32 v79, v79, v144
	s_waitcnt vmcnt(0)
	v_mov_b32_e32 v81, v76
	v_mov_b32_e32 v76, v75
	v_mov_b32_e32 v80, v74
	v_mul_f32_e32 v70, v70, v76
	v_mul_f32_e32 v71, v71, v77
	v_mul_f32_e32 v78, v78, v80
	v_mul_f32_e32 v79, v79, v81
	v_and_b32_sdwa v74, v71, v206 dst_sel:DWORD dst_unused:UNUSED_PAD src0_sel:WORD_1 src1_sel:DWORD
	v_and_b32_sdwa v75, v70, v206 dst_sel:DWORD dst_unused:UNUSED_PAD src0_sel:WORD_1 src1_sel:DWORD
	v_and_b32_sdwa v72, v79, v206 dst_sel:DWORD dst_unused:UNUSED_PAD src0_sel:WORD_1 src1_sel:DWORD
	v_and_b32_sdwa v73, v78, v206 dst_sel:DWORD dst_unused:UNUSED_PAD src0_sel:WORD_1 src1_sel:DWORD
	v_add3_u32 v71, v71, v74, s0
	v_add3_u32 v70, v70, v75, s0
	v_add3_u32 v73, v78, v73, s0
	v_add3_u32 v72, v79, v72, s0
	v_and_b32_e32 v71, 0xffff0000, v71
	v_and_b32_e32 v70, 0xffff0000, v70
	v_or_b32_sdwa v71, v71, v72 dst_sel:DWORD dst_unused:UNUSED_PAD src0_sel:DWORD src1_sel:WORD_1
	v_or_b32_sdwa v70, v70, v73 dst_sel:DWORD dst_unused:UNUSED_PAD src0_sel:DWORD src1_sel:WORD_1
	global_store_dwordx2 v[90:91], v[70:71], off offset:-1024
	global_load_dwordx4 v[70:73], v[110:111], off
	v_mov_b32_e32 v75, v68
	v_mov_b32_e32 v68, v67
	v_mov_b32_e32 v74, v66
	v_mul_f32_e32 v66, v68, v144
	v_mul_f32_e32 v67, v69, v144
	v_mul_f32_e32 v74, v74, v144
	v_mul_f32_e32 v75, v75, v144
	s_waitcnt vmcnt(0)
	v_mov_b32_e32 v77, v72
	v_mov_b32_e32 v72, v71
	v_mov_b32_e32 v76, v70
	v_mul_f32_e32 v66, v66, v72
	v_mul_f32_e32 v67, v67, v73
	v_mul_f32_e32 v74, v74, v76
	v_mul_f32_e32 v75, v75, v77
	v_and_b32_sdwa v70, v67, v206 dst_sel:DWORD dst_unused:UNUSED_PAD src0_sel:WORD_1 src1_sel:DWORD
	v_and_b32_sdwa v71, v66, v206 dst_sel:DWORD dst_unused:UNUSED_PAD src0_sel:WORD_1 src1_sel:DWORD
	v_and_b32_sdwa v68, v75, v206 dst_sel:DWORD dst_unused:UNUSED_PAD src0_sel:WORD_1 src1_sel:DWORD
	v_and_b32_sdwa v69, v74, v206 dst_sel:DWORD dst_unused:UNUSED_PAD src0_sel:WORD_1 src1_sel:DWORD
	v_add3_u32 v67, v67, v70, s0
	v_add3_u32 v66, v66, v71, s0
	v_add3_u32 v69, v74, v69, s0
	v_add3_u32 v68, v75, v68, s0
	v_and_b32_e32 v67, 0xffff0000, v67
	v_and_b32_e32 v66, 0xffff0000, v66
	v_or_b32_sdwa v67, v67, v68 dst_sel:DWORD dst_unused:UNUSED_PAD src0_sel:DWORD src1_sel:WORD_1
	v_or_b32_sdwa v66, v66, v69 dst_sel:DWORD dst_unused:UNUSED_PAD src0_sel:DWORD src1_sel:WORD_1
	global_store_dwordx2 v[90:91], v[66:67], off offset:-512
; template <int NR>
; __device__ __forceinline__ void norm_add_rows(const bf16_t* __restrict__ Yb, const float* xi, float* xo, const float* __restrict__ gpost,
;                                               const float* __restrict__ gpre, bf16_t* __restrict__ Hb, int row0, int rstride, int lane) {
;     ...
;     for (int q = 0; q < NR; ++q) { const size_t ro = (size_t)(row0 + q * rstride) * DM;
;         f32x4 y[8]; float ss = 0.f;
; #pragma unroll
;         for (int j = 0; j < 8; ++j) { y[j].x = __uint_as_float(yb[q][j].x << 16); y[j].y = __uint_as_float(yb[q][j].x & 0xffff0000u); y[j].z = __uint_as_float(yb[q][j].y << 16); y[j].w = __uint_as_float(yb[q][j].y & 0xffff0000u);
;             ss += (y[j].x * y[j].x + y[j].y * y[j].y) + (y[j].z * y[j].z + y[j].w * y[j].w); }
;         const float rs = rsqrtf(wave_sum(ss) * (1.0f / DM) + EPS);
;         float ss2 = 0.f;
; #pragma unroll
;         for (int j = 0; j < 8; ++j) { v[q][j] = v[q][j] + y[j] * rs * gp[j]; ((f32x4*)(xo + ro))[lane + 64 * j] = v[q][j];
.LBB0_897:
	s_nop 0
	v_and_b32_e32 v67, 0xffff0000, v142
	v_and_b32_e32 v69, 0xffff0000, v143
	v_lshlrev_b32_e32 v66, 16, v142
	v_lshlrev_b32_e32 v68, 16, v143
	v_mul_f32_e32 v70, v67, v67
	v_mul_f32_e32 v71, v69, v69
	v_fmac_f32_e32 v70, v66, v66
	v_fmac_f32_e32 v71, v68, v68
	v_and_b32_e32 v85, 0xffff0000, v140
	v_and_b32_e32 v87, 0xffff0000, v141
	v_add_f32_e32 v70, v70, v71
	v_lshlrev_b32_e32 v84, 16, v140
	v_lshlrev_b32_e32 v86, 16, v141
	v_mul_f32_e32 v71, v85, v85
	v_mul_f32_e32 v72, v87, v87
	v_fmac_f32_e32 v71, v84, v84
	v_fmac_f32_e32 v72, v86, v86
	v_add_f32_e32 v71, v71, v72
	v_and_b32_e32 v89, 0xffff0000, v138
	v_and_b32_e32 v91, 0xffff0000, v139
	v_add_f32_e32 v70, v70, v71
	v_lshlrev_b32_e32 v88, 16, v138
	v_lshlrev_b32_e32 v90, 16, v139
	v_mul_f32_e32 v71, v89, v89
	v_mul_f32_e32 v72, v91, v91
	v_fmac_f32_e32 v71, v88, v88
	v_fmac_f32_e32 v72, v90, v90
	v_add_f32_e32 v71, v71, v72
	v_and_b32_e32 v93, 0xffff0000, v136
	v_and_b32_e32 v95, 0xffff0000, v137
	v_add_f32_e32 v70, v70, v71
	v_lshlrev_b32_e32 v92, 16, v136
	v_lshlrev_b32_e32 v94, 16, v137
	v_mul_f32_e32 v71, v93, v93
	v_mul_f32_e32 v72, v95, v95
	v_fmac_f32_e32 v71, v92, v92
	v_fmac_f32_e32 v72, v94, v94
	v_add_f32_e32 v71, v71, v72
	v_lshlrev_b32_e32 v96, 16, v134
	v_and_b32_e32 v97, 0xffff0000, v134
	v_lshlrev_b32_e32 v134, 16, v135
	v_and_b32_e32 v135, 0xffff0000, v135
	v_add_f32_e32 v70, v70, v71
	v_mul_f32_e32 v71, v97, v97
	v_mul_f32_e32 v72, v135, v135
	v_fmac_f32_e32 v71, v96, v96
	v_fmac_f32_e32 v72, v134, v134
	v_add_f32_e32 v71, v71, v72
	v_lshlrev_b32_e32 v136, 16, v132
	v_and_b32_e32 v137, 0xffff0000, v132
	v_lshlrev_b32_e32 v132, 16, v133
	v_and_b32_e32 v133, 0xffff0000, v133
	v_add_f32_e32 v70, v70, v71
	v_mul_f32_e32 v71, v137, v137
	v_mul_f32_e32 v72, v133, v133
	v_fmac_f32_e32 v71, v136, v136
	v_fmac_f32_e32 v72, v132, v132
	v_add_f32_e32 v71, v71, v72
	v_lshlrev_b32_e32 v138, 16, v130
	v_and_b32_e32 v139, 0xffff0000, v130
	v_lshlrev_b32_e32 v130, 16, v131
	v_and_b32_e32 v131, 0xffff0000, v131
	v_add_f32_e32 v70, v70, v71
	v_mul_f32_e32 v71, v139, v139
	v_mul_f32_e32 v72, v131, v131
	v_fmac_f32_e32 v71, v138, v138
	v_fmac_f32_e32 v72, v130, v130
	v_add_f32_e32 v71, v71, v72
	v_lshlrev_b32_e32 v140, 16, v128
	v_and_b32_e32 v141, 0xffff0000, v128
	v_lshlrev_b32_e32 v128, 16, v129
	v_and_b32_e32 v129, 0xffff0000, v129
	v_add_f32_e32 v70, v70, v71
	v_mul_f32_e32 v71, v141, v141
	v_mul_f32_e32 v72, v129, v129
	v_fmac_f32_e32 v71, v140, v140
	v_fmac_f32_e32 v72, v128, v128
	v_add_f32_e32 v71, v71, v72
	v_add_f32_e32 v70, v70, v71
	ds_swizzle_b32 v71, v70 offset:swizzle(SWAP,1)
	v_mov_b32_e32 v121, v1
	v_mov_b32_e32 v123, v1
	v_mov_b32_e32 v125, v1
	v_mov_b32_e32 v127, v1
	s_waitcnt lgkmcnt(0)
	v_add_f32_e32 v70, v70, v71
	ds_swizzle_b32 v71, v70 offset:swizzle(SWAP,2)
	v_lshl_add_u64 v[82:83], s[18:19], 0, v[0:1]
	v_lshl_add_u64 v[80:81], s[18:19], 0, v[120:121]
	v_lshl_add_u64 v[78:79], s[18:19], 0, v[122:123]
	v_lshl_add_u64 v[76:77], s[18:19], 0, v[124:125]
	s_waitcnt lgkmcnt(0)
	v_add_f32_e32 v70, v70, v71
	ds_swizzle_b32 v71, v70 offset:swizzle(SWAP,4)
	v_lshl_add_u64 v[74:75], s[18:19], 0, v[126:127]
	s_waitcnt lgkmcnt(0)
	v_add_f32_e32 v70, v70, v71
	ds_swizzle_b32 v71, v70 offset:swizzle(SWAP,8)
	s_waitcnt lgkmcnt(0)
	v_add_f32_e32 v70, v70, v71
	ds_swizzle_b32 v71, v70 offset:swizzle(SWAP,16)
	s_waitcnt lgkmcnt(0)
	v_add_f32_e32 v70, v70, v71
	v_mov_b32_e32 v71, v70
	s_nop 1
	v_permlane32_swap_b32_e32 v70, v71
	v_add_f32_e32 v70, v70, v71
	v_fmamk_f32 v70, v70, 0x3a000000, v177
	v_cmp_gt_f32_e32 vcc, s35, v70
	v_mul_f32_e32 v71, 0x4b800000, v70
	s_nop 0
	v_cndmask_b32_e32 v70, v70, v71, vcc
	v_rsq_f32_e32 v70, v70
	s_nop 0
	v_mul_f32_e32 v71, 0x45800000, v70
	v_cndmask_b32_e32 v142, v70, v71, vcc
	v_mul_f32_e32 v66, v66, v142
	v_mul_f32_e32 v67, v67, v142
	v_mul_f32_e32 v68, v68, v142
	v_mul_f32_e32 v69, v69, v142
	v_fma_f32 v70, v10, v66, v38
	v_fma_f32 v71, v11, v67, v39
	v_fma_f32 v72, v12, v68, v40
	v_fma_f32 v73, v13, v69, v41
	v_mul_f32_e32 v38, v84, v142
	v_mul_f32_e32 v39, v85, v142
	v_mul_f32_e32 v40, v86, v142
	v_mul_f32_e32 v41, v87, v142
	v_fma_f32 v66, v2, v38, v34
	v_fma_f32 v67, v3, v39, v35
	v_fma_f32 v68, v4, v40, v36
	v_fma_f32 v69, v5, v41, v37
	v_mul_f32_e32 v34, v88, v142
	v_mul_f32_e32 v35, v89, v142
	v_mul_f32_e32 v36, v90, v142
	v_mul_f32_e32 v37, v91, v142
	s_waitcnt vmcnt(13)
	v_fma_f32 v62, v6, v34, v62
	v_fma_f32 v63, v7, v35, v63
	v_fma_f32 v64, v8, v36, v64
	v_fma_f32 v65, v9, v37, v65
	v_mul_f32_e32 v34, v92, v142
	v_mul_f32_e32 v35, v93, v142
	v_mul_f32_e32 v36, v94, v142
	v_mul_f32_e32 v37, v95, v142
	s_waitcnt vmcnt(12)
	v_fma_f32 v58, v26, v34, v58
	v_fma_f32 v59, v27, v35, v59
	v_fma_f32 v60, v28, v36, v60
	v_fma_f32 v61, v29, v37, v61
	v_mul_f32_e32 v34, v96, v142
	v_mul_f32_e32 v35, v97, v142
	v_mul_f32_e32 v36, v134, v142
	v_mul_f32_e32 v37, v135, v142
	s_waitcnt vmcnt(11)
	v_fma_f32 v54, v14, v34, v54
	v_fma_f32 v55, v15, v35, v55
	v_fma_f32 v56, v16, v36, v56
	v_fma_f32 v57, v17, v37, v57
	v_mul_f32_e32 v34, v136, v142
	v_mul_f32_e32 v35, v137, v142
	v_mul_f32_e32 v36, v132, v142
	v_mul_f32_e32 v37, v133, v142
	s_waitcnt vmcnt(10)
	v_fma_f32 v50, v18, v34, v50
	v_fma_f32 v51, v19, v35, v51
	v_fma_f32 v52, v20, v36, v52
	v_fma_f32 v53, v21, v37, v53
	v_mul_f32_e32 v34, v138, v142
	v_mul_f32_e32 v35, v139, v142
	v_mul_f32_e32 v36, v130, v142
	v_mul_f32_e32 v37, v131, v142
	s_waitcnt vmcnt(9)
	v_fma_f32 v38, v22, v34, v46
	v_fma_f32 v39, v23, v35, v47
	v_fma_f32 v40, v24, v36, v48
	v_fma_f32 v41, v25, v37, v49
	v_mul_f32_e32 v34, v140, v142
	v_mul_f32_e32 v35, v141, v142
	v_mul_f32_e32 v36, v128, v142
	v_mul_f32_e32 v37, v129, v142
	s_waitcnt vmcnt(8)
	v_fma_f32 v34, v30, v34, v42
	v_fma_f32 v35, v31, v35, v43
	v_fma_f32 v36, v32, v36, v44
	v_fma_f32 v37, v33, v37, v45
	s_and_b64 vcc, exec, s[4:5]
	global_store_dwordx4 v[82:83], v[70:73], off
	global_store_dwordx4 v[82:83], v[66:69], off offset:1024
	global_store_dwordx4 v[82:83], v[62:65], off offset:2048
	global_store_dwordx4 v[82:83], v[58:61], off offset:3072
	global_store_dwordx4 v[80:81], v[54:57], off
	global_store_dwordx4 v[78:79], v[50:53], off
	global_store_dwordx4 v[76:77], v[38:41], off
	global_store_dwordx4 v[74:75], v[34:37], off
	s_cbranch_vccnz .LBB0_894
; __device__ __forceinline__ unsigned pk2(float lo, float hi) { return f2bf(lo) | (f2bf(hi) << 16); }
; template <int NR>
; __device__ __forceinline__ void norm_add_rows(const bf16_t* __restrict__ Yb, const float* xi, float* xo, const float* __restrict__ gpost,
;                                               const float* __restrict__ gpre, bf16_t* __restrict__ Hb, int row0, int rstride, int lane) {
;     ...
;         for (int j = 0; j < 8; ++j) { v[q][j] = v[q][j] + y[j] * rs * gp[j]; ((f32x4*)(xo + ro))[lane + 64 * j] = v[q][j];
;             ss2 += (v[q][j].x * v[q][j].x + v[q][j].y * v[q][j].y) + (v[q][j].z * v[q][j].z + v[q][j].w * v[q][j].w); }
;         if (gpre) {
;             const float rs2 = rsqrtf(wave_sum(ss2) * (1.0f / DM) + EPS);
; #pragma unroll
;             for (int j = 0; j < 8; ++j) { const f32x4 gg = ((const f32x4*)gpre)[lane + 64 * j];
;                 u32x2 w; w.x = pk2(v[q][j].x * rs2 * gg.x, v[q][j].y * rs2 * gg.y); w.y = pk2(v[q][j].z * rs2 * gg.z, v[q][j].w * rs2 * gg.w); ((u32x2*)(Hb + ro))[lane + 64 * j] = w; }
	v_mul_f32_e32 v42, v71, v71
	v_mul_f32_e32 v43, v73, v73
	v_fmac_f32_e32 v42, v70, v70
	v_fmac_f32_e32 v43, v72, v72
	v_add_f32_e32 v42, v42, v43
	v_mul_f32_e32 v43, v67, v67
	v_mul_f32_e32 v44, v69, v69
	v_fmac_f32_e32 v43, v66, v66
	v_fmac_f32_e32 v44, v68, v68
	v_add_f32_e32 v43, v43, v44
	v_add_f32_e32 v42, v42, v43
	v_mul_f32_e32 v43, v63, v63
	v_mul_f32_e32 v44, v65, v65
	v_fmac_f32_e32 v43, v62, v62
	v_fmac_f32_e32 v44, v64, v64
	v_add_f32_e32 v43, v43, v44
	v_add_f32_e32 v42, v43, v42
	v_mul_f32_e32 v43, v59, v59
	v_mul_f32_e32 v44, v61, v61
	v_fmac_f32_e32 v43, v58, v58
	v_fmac_f32_e32 v44, v60, v60
	v_add_f32_e32 v43, v43, v44
	v_add_f32_e32 v42, v43, v42
	v_mul_f32_e32 v43, v55, v55
	v_mul_f32_e32 v44, v57, v57
	v_fmac_f32_e32 v43, v54, v54
	v_fmac_f32_e32 v44, v56, v56
	v_add_f32_e32 v43, v43, v44
	v_add_f32_e32 v42, v43, v42
	v_mul_f32_e32 v43, v51, v51
	v_mul_f32_e32 v44, v53, v53
	v_fmac_f32_e32 v43, v50, v50
	v_fmac_f32_e32 v44, v52, v52
	v_add_f32_e32 v43, v43, v44
	v_add_f32_e32 v42, v43, v42
	v_mul_f32_e32 v43, v39, v39
	v_mul_f32_e32 v44, v41, v41
	v_fmac_f32_e32 v43, v38, v38
	v_fmac_f32_e32 v44, v40, v40
	v_add_f32_e32 v43, v43, v44
	v_add_f32_e32 v42, v43, v42
	v_mul_f32_e32 v43, v35, v35
	v_mul_f32_e32 v44, v37, v37
	v_fmac_f32_e32 v43, v34, v34
	v_fmac_f32_e32 v44, v36, v36
	v_add_f32_e32 v43, v43, v44
	global_load_dwordx4 v[44:47], v[102:103], off
	v_add_f32_e32 v42, v43, v42
	ds_swizzle_b32 v43, v42 offset:swizzle(SWAP,1)
	v_mov_b32_e32 v48, v70
	v_mov_b32_e32 v49, v72
	v_mov_b32_e32 v72, v71
	s_lshl_b64 s[4:5], s[24:25], 11
	s_waitcnt lgkmcnt(0)
	v_add_f32_e32 v42, v42, v43
	ds_swizzle_b32 v43, v42 offset:swizzle(SWAP,2)
	s_waitcnt lgkmcnt(0)
	v_add_f32_e32 v42, v42, v43
	ds_swizzle_b32 v43, v42 offset:swizzle(SWAP,4)
	s_waitcnt lgkmcnt(0)
	v_add_f32_e32 v42, v42, v43
	ds_swizzle_b32 v43, v42 offset:swizzle(SWAP,8)
	s_waitcnt lgkmcnt(0)
	v_add_f32_e32 v42, v42, v43
	ds_swizzle_b32 v43, v42 offset:swizzle(SWAP,16)
	s_waitcnt lgkmcnt(0)
	v_add_f32_e32 v42, v42, v43
	v_mov_b32_e32 v43, v42
	s_nop 1
	v_permlane32_swap_b32_e32 v42, v43
	v_add_f32_e32 v42, v42, v43
	v_fmamk_f32 v42, v42, 0x3a000000, v177
	v_cmp_gt_f32_e32 vcc, s35, v42
	v_mul_f32_e32 v43, 0x4b800000, v42
	s_waitcnt vmcnt(0)
	v_mov_b32_e32 v74, v44
	v_cndmask_b32_e32 v42, v42, v43, vcc
	v_rsq_f32_e32 v42, v42
	v_mov_b32_e32 v75, v46
	v_mov_b32_e32 v46, v45
	v_mul_f32_e32 v43, 0x45800000, v42
	v_cndmask_b32_e32 v42, v42, v43, vcc
	v_mul_f32_e32 v48, v48, v42
	v_mul_f32_e32 v49, v49, v42
	v_mul_f32_e32 v70, v72, v42
	v_mul_f32_e32 v71, v73, v42
	v_mul_f32_e32 v48, v74, v48
	v_mul_f32_e32 v49, v75, v49
	v_mul_f32_e32 v44, v46, v70
	v_mul_f32_e32 v45, v47, v71
	v_and_b32_sdwa v46, v48, v206 dst_sel:DWORD dst_unused:UNUSED_PAD src0_sel:WORD_1 src1_sel:DWORD
	v_add3_u32 v46, v48, v46, s0
	v_and_b32_sdwa v47, v45, v206 dst_sel:DWORD dst_unused:UNUSED_PAD src0_sel:WORD_1 src1_sel:DWORD
	v_and_b32_sdwa v48, v44, v206 dst_sel:DWORD dst_unused:UNUSED_PAD src0_sel:WORD_1 src1_sel:DWORD
	v_and_b32_sdwa v43, v49, v206 dst_sel:DWORD dst_unused:UNUSED_PAD src0_sel:WORD_1 src1_sel:DWORD
	v_add3_u32 v45, v45, v47, s0
	v_add3_u32 v44, v44, v48, s0
	v_add3_u32 v43, v49, v43, s0
	v_and_b32_e32 v45, 0xffff0000, v45
	v_and_b32_e32 v44, 0xffff0000, v44
	v_or_b32_sdwa v47, v45, v43 dst_sel:DWORD dst_unused:UNUSED_PAD src0_sel:DWORD src1_sel:WORD_1
	v_or_b32_sdwa v46, v44, v46 dst_sel:DWORD dst_unused:UNUSED_PAD src0_sel:DWORD src1_sel:WORD_1
	v_lshl_add_u64 v[44:45], s[4:5], 1, v[114:115]
	global_store_dwordx2 v[44:45], v[46:47], off
	global_load_dwordx4 v[46:49], v[102:103], off offset:1024
	v_mov_b32_e32 v71, v68
	v_mov_b32_e32 v68, v67
	v_mov_b32_e32 v70, v66
	v_mul_f32_e32 v66, v68, v42
	v_mul_f32_e32 v67, v69, v42
	v_mul_f32_e32 v70, v70, v42
	v_mul_f32_e32 v71, v71, v42
	s_waitcnt vmcnt(0)
	v_mov_b32_e32 v73, v48
	v_mov_b32_e32 v48, v47
	v_mov_b32_e32 v72, v46
	v_mul_f32_e32 v46, v48, v66
	v_mul_f32_e32 v47, v49, v67
	v_mul_f32_e32 v70, v72, v70
	v_mul_f32_e32 v71, v73, v71
	v_and_b32_sdwa v49, v47, v206 dst_sel:DWORD dst_unused:UNUSED_PAD src0_sel:WORD_1 src1_sel:DWORD
	v_and_b32_sdwa v66, v46, v206 dst_sel:DWORD dst_unused:UNUSED_PAD src0_sel:WORD_1 src1_sel:DWORD
	v_and_b32_sdwa v43, v71, v206 dst_sel:DWORD dst_unused:UNUSED_PAD src0_sel:WORD_1 src1_sel:DWORD
	v_and_b32_sdwa v48, v70, v206 dst_sel:DWORD dst_unused:UNUSED_PAD src0_sel:WORD_1 src1_sel:DWORD
	v_add3_u32 v47, v47, v49, s0
	v_add3_u32 v46, v46, v66, s0
	v_add3_u32 v48, v70, v48, s0
	v_add3_u32 v43, v71, v43, s0
	v_and_b32_e32 v47, 0xffff0000, v47
	v_and_b32_e32 v46, 0xffff0000, v46
	v_or_b32_sdwa v47, v47, v43 dst_sel:DWORD dst_unused:UNUSED_PAD src0_sel:DWORD src1_sel:WORD_1
	v_or_b32_sdwa v46, v46, v48 dst_sel:DWORD dst_unused:UNUSED_PAD src0_sel:DWORD src1_sel:WORD_1
	global_store_dwordx2 v[44:45], v[46:47], off offset:512
	global_load_dwordx4 v[46:49], v[102:103], off offset:2048
	v_mov_b32_e32 v67, v64
	v_mov_b32_e32 v64, v63
	v_mov_b32_e32 v66, v62
	v_mul_f32_e32 v62, v64, v42
	v_mul_f32_e32 v63, v65, v42
	v_mul_f32_e32 v66, v66, v42
	v_mul_f32_e32 v67, v67, v42
	s_waitcnt vmcnt(0)
; __device__ __forceinline__ unsigned pk2(float lo, float hi) { return f2bf(lo) | (f2bf(hi) << 16); }
; template <int NR>
; __device__ __forceinline__ void norm_add_rows(const bf16_t* __restrict__ Yb, const float* xi, float* xo, const float* __restrict__ gpost,
;                                               const float* __restrict__ gpre, bf16_t* __restrict__ Hb, int row0, int rstride, int lane) {
;     ...
;         if (gpre) {
;             const float rs2 = rsqrtf(wave_sum(ss2) * (1.0f / DM) + EPS);
; #pragma unroll
;             for (int j = 0; j < 8; ++j) { const f32x4 gg = ((const f32x4*)gpre)[lane + 64 * j];
;                 u32x2 w; w.x = pk2(v[q][j].x * rs2 * gg.x, v[q][j].y * rs2 * gg.y); w.y = pk2(v[q][j].z * rs2 * gg.z, v[q][j].w * rs2 * gg.w); ((u32x2*)(Hb + ro))[lane + 64 * j] = w; }
	v_mov_b32_e32 v69, v48
	v_mov_b32_e32 v48, v47
	v_mov_b32_e32 v68, v46
	v_mul_f32_e32 v46, v48, v62
	v_mul_f32_e32 v47, v49, v63
	v_mul_f32_e32 v66, v68, v66
	v_mul_f32_e32 v67, v69, v67
	v_and_b32_sdwa v49, v47, v206 dst_sel:DWORD dst_unused:UNUSED_PAD src0_sel:WORD_1 src1_sel:DWORD
	v_and_b32_sdwa v62, v46, v206 dst_sel:DWORD dst_unused:UNUSED_PAD src0_sel:WORD_1 src1_sel:DWORD
	v_and_b32_sdwa v43, v67, v206 dst_sel:DWORD dst_unused:UNUSED_PAD src0_sel:WORD_1 src1_sel:DWORD
	v_and_b32_sdwa v48, v66, v206 dst_sel:DWORD dst_unused:UNUSED_PAD src0_sel:WORD_1 src1_sel:DWORD
	v_add3_u32 v47, v47, v49, s0
	v_add3_u32 v46, v46, v62, s0
	v_add3_u32 v48, v66, v48, s0
	v_add3_u32 v43, v67, v43, s0
	v_and_b32_e32 v47, 0xffff0000, v47
	v_and_b32_e32 v46, 0xffff0000, v46
	v_or_b32_sdwa v47, v47, v43 dst_sel:DWORD dst_unused:UNUSED_PAD src0_sel:DWORD src1_sel:WORD_1
	v_or_b32_sdwa v46, v46, v48 dst_sel:DWORD dst_unused:UNUSED_PAD src0_sel:DWORD src1_sel:WORD_1
	global_store_dwordx2 v[44:45], v[46:47], off offset:1024
	global_load_dwordx4 v[46:49], v[102:103], off offset:3072
	v_mov_b32_e32 v63, v60
	v_mov_b32_e32 v60, v59
	v_mov_b32_e32 v62, v58
	v_mul_f32_e32 v58, v60, v42
	v_mul_f32_e32 v59, v61, v42
	v_mul_f32_e32 v62, v62, v42
	v_mul_f32_e32 v63, v63, v42
	s_waitcnt vmcnt(0)
	v_mov_b32_e32 v65, v48
	v_mov_b32_e32 v48, v47
	v_mov_b32_e32 v64, v46
	v_mul_f32_e32 v46, v48, v58
	v_mul_f32_e32 v47, v49, v59
	v_mul_f32_e32 v62, v64, v62
	v_mul_f32_e32 v63, v65, v63
	v_and_b32_sdwa v49, v47, v206 dst_sel:DWORD dst_unused:UNUSED_PAD src0_sel:WORD_1 src1_sel:DWORD
	v_and_b32_sdwa v58, v46, v206 dst_sel:DWORD dst_unused:UNUSED_PAD src0_sel:WORD_1 src1_sel:DWORD
	v_and_b32_sdwa v43, v63, v206 dst_sel:DWORD dst_unused:UNUSED_PAD src0_sel:WORD_1 src1_sel:DWORD
	v_and_b32_sdwa v48, v62, v206 dst_sel:DWORD dst_unused:UNUSED_PAD src0_sel:WORD_1 src1_sel:DWORD
	v_add3_u32 v47, v47, v49, s0
	v_add3_u32 v46, v46, v58, s0
	v_add3_u32 v48, v62, v48, s0
	v_add3_u32 v43, v63, v43, s0
	v_and_b32_e32 v47, 0xffff0000, v47
	v_and_b32_e32 v46, 0xffff0000, v46
	v_or_b32_sdwa v47, v47, v43 dst_sel:DWORD dst_unused:UNUSED_PAD src0_sel:DWORD src1_sel:WORD_1
	v_or_b32_sdwa v46, v46, v48 dst_sel:DWORD dst_unused:UNUSED_PAD src0_sel:DWORD src1_sel:WORD_1
	global_store_dwordx2 v[44:45], v[46:47], off offset:1536
	global_load_dwordx4 v[46:49], v[104:105], off
	v_mov_b32_e32 v59, v56
	v_mov_b32_e32 v56, v55
	v_mov_b32_e32 v58, v54
	v_mul_f32_e32 v54, v56, v42
	v_mul_f32_e32 v55, v57, v42
	v_mul_f32_e32 v58, v58, v42
	v_mul_f32_e32 v59, v59, v42
	s_waitcnt vmcnt(0)
	v_mov_b32_e32 v61, v48
	v_mov_b32_e32 v48, v47
	v_mov_b32_e32 v60, v46
	v_mul_f32_e32 v46, v48, v54
	v_mul_f32_e32 v47, v49, v55
	v_mul_f32_e32 v58, v60, v58
	v_mul_f32_e32 v59, v61, v59
	v_and_b32_sdwa v49, v47, v206 dst_sel:DWORD dst_unused:UNUSED_PAD src0_sel:WORD_1 src1_sel:DWORD
	v_and_b32_sdwa v54, v46, v206 dst_sel:DWORD dst_unused:UNUSED_PAD src0_sel:WORD_1 src1_sel:DWORD
	v_and_b32_sdwa v43, v59, v206 dst_sel:DWORD dst_unused:UNUSED_PAD src0_sel:WORD_1 src1_sel:DWORD
	v_and_b32_sdwa v48, v58, v206 dst_sel:DWORD dst_unused:UNUSED_PAD src0_sel:WORD_1 src1_sel:DWORD
	v_add3_u32 v47, v47, v49, s0
	v_add3_u32 v46, v46, v54, s0
	v_add3_u32 v48, v58, v48, s0
	v_add3_u32 v43, v59, v43, s0
	v_and_b32_e32 v47, 0xffff0000, v47
	v_and_b32_e32 v46, 0xffff0000, v46
	v_or_b32_sdwa v47, v47, v43 dst_sel:DWORD dst_unused:UNUSED_PAD src0_sel:DWORD src1_sel:WORD_1
	v_or_b32_sdwa v46, v46, v48 dst_sel:DWORD dst_unused:UNUSED_PAD src0_sel:DWORD src1_sel:WORD_1
	global_store_dwordx2 v[44:45], v[46:47], off offset:2048
	global_load_dwordx4 v[46:49], v[106:107], off
	v_mov_b32_e32 v55, v52
	v_mov_b32_e32 v52, v51
	v_mov_b32_e32 v54, v50
	v_mul_f32_e32 v50, v52, v42
	v_mul_f32_e32 v51, v53, v42
	v_mul_f32_e32 v54, v54, v42
	v_mul_f32_e32 v55, v55, v42
	s_waitcnt vmcnt(0)
; __device__ __forceinline__ unsigned pk2(float lo, float hi) { return f2bf(lo) | (f2bf(hi) << 16); }
; template <int NR>
; __device__ __forceinline__ void norm_add_rows(const bf16_t* __restrict__ Yb, const float* xi, float* xo, const float* __restrict__ gpost,
;                                               const float* __restrict__ gpre, bf16_t* __restrict__ Hb, int row0, int rstride, int lane) {
;     ...
;         if (gpre) {
;             const float rs2 = rsqrtf(wave_sum(ss2) * (1.0f / DM) + EPS);
; #pragma unroll
;             for (int j = 0; j < 8; ++j) { const f32x4 gg = ((const f32x4*)gpre)[lane + 64 * j];
;                 u32x2 w; w.x = pk2(v[q][j].x * rs2 * gg.x, v[q][j].y * rs2 * gg.y); w.y = pk2(v[q][j].z * rs2 * gg.z, v[q][j].w * rs2 * gg.w); ((u32x2*)(Hb + ro))[lane + 64 * j] = w; }
	v_mov_b32_e32 v57, v48
	v_mov_b32_e32 v48, v47
	v_mov_b32_e32 v56, v46
	v_mul_f32_e32 v46, v50, v48
	v_mul_f32_e32 v47, v51, v49
	v_mul_f32_e32 v54, v54, v56
	v_mul_f32_e32 v55, v55, v57
	v_and_b32_sdwa v49, v47, v206 dst_sel:DWORD dst_unused:UNUSED_PAD src0_sel:WORD_1 src1_sel:DWORD
	v_and_b32_sdwa v50, v46, v206 dst_sel:DWORD dst_unused:UNUSED_PAD src0_sel:WORD_1 src1_sel:DWORD
	v_and_b32_sdwa v43, v55, v206 dst_sel:DWORD dst_unused:UNUSED_PAD src0_sel:WORD_1 src1_sel:DWORD
	v_and_b32_sdwa v48, v54, v206 dst_sel:DWORD dst_unused:UNUSED_PAD src0_sel:WORD_1 src1_sel:DWORD
	v_add3_u32 v47, v47, v49, s0
	v_add3_u32 v46, v46, v50, s0
	v_add3_u32 v48, v54, v48, s0
	v_add3_u32 v43, v55, v43, s0
	v_and_b32_e32 v47, 0xffff0000, v47
	v_and_b32_e32 v46, 0xffff0000, v46
	v_or_b32_sdwa v47, v47, v43 dst_sel:DWORD dst_unused:UNUSED_PAD src0_sel:DWORD src1_sel:WORD_1
	v_or_b32_sdwa v46, v46, v48 dst_sel:DWORD dst_unused:UNUSED_PAD src0_sel:DWORD src1_sel:WORD_1
	global_store_dwordx2 v[44:45], v[46:47], off offset:2560
	global_load_dwordx4 v[46:49], v[108:109], off
	v_mov_b32_e32 v51, v40
	v_mov_b32_e32 v40, v39
	v_mov_b32_e32 v50, v38
	v_mul_f32_e32 v38, v40, v42
	v_mul_f32_e32 v39, v41, v42
	v_mul_f32_e32 v50, v50, v42
	v_mul_f32_e32 v51, v51, v42
	s_waitcnt vmcnt(0)
	v_mov_b32_e32 v53, v48
	v_mov_b32_e32 v48, v47
	v_mov_b32_e32 v52, v46
	v_mul_f32_e32 v38, v38, v48
	v_mul_f32_e32 v39, v39, v49
	v_mul_f32_e32 v50, v50, v52
	v_mul_f32_e32 v51, v51, v53
	v_and_b32_sdwa v43, v39, v206 dst_sel:DWORD dst_unused:UNUSED_PAD src0_sel:WORD_1 src1_sel:DWORD
	v_and_b32_sdwa v46, v38, v206 dst_sel:DWORD dst_unused:UNUSED_PAD src0_sel:WORD_1 src1_sel:DWORD
	v_and_b32_sdwa v40, v51, v206 dst_sel:DWORD dst_unused:UNUSED_PAD src0_sel:WORD_1 src1_sel:DWORD
	v_and_b32_sdwa v41, v50, v206 dst_sel:DWORD dst_unused:UNUSED_PAD src0_sel:WORD_1 src1_sel:DWORD
	v_add3_u32 v39, v39, v43, s0
	v_add3_u32 v38, v38, v46, s0
	v_add3_u32 v41, v50, v41, s0
	v_add3_u32 v40, v51, v40, s0
	v_and_b32_e32 v39, 0xffff0000, v39
	v_and_b32_e32 v38, 0xffff0000, v38
	v_or_b32_sdwa v39, v39, v40 dst_sel:DWORD dst_unused:UNUSED_PAD src0_sel:DWORD src1_sel:WORD_1
	v_or_b32_sdwa v38, v38, v41 dst_sel:DWORD dst_unused:UNUSED_PAD src0_sel:DWORD src1_sel:WORD_1
	global_store_dwordx2 v[44:45], v[38:39], off offset:3072
	global_load_dwordx4 v[38:41], v[110:111], off
	v_mov_b32_e32 v47, v36
	v_mov_b32_e32 v36, v35
	v_mov_b32_e32 v46, v34
	v_mul_f32_e32 v34, v36, v42
	v_mul_f32_e32 v35, v37, v42
	v_mul_f32_e32 v46, v46, v42
	v_mul_f32_e32 v47, v47, v42
	s_waitcnt vmcnt(0)
	v_mov_b32_e32 v49, v40
	v_mov_b32_e32 v40, v39
	v_mov_b32_e32 v48, v38
	v_mul_f32_e32 v34, v34, v40
	v_mul_f32_e32 v35, v35, v41
	v_mul_f32_e32 v46, v46, v48
	v_mul_f32_e32 v47, v47, v49
	v_and_b32_sdwa v38, v35, v206 dst_sel:DWORD dst_unused:UNUSED_PAD src0_sel:WORD_1 src1_sel:DWORD
	v_and_b32_sdwa v39, v34, v206 dst_sel:DWORD dst_unused:UNUSED_PAD src0_sel:WORD_1 src1_sel:DWORD
	v_and_b32_sdwa v36, v47, v206 dst_sel:DWORD dst_unused:UNUSED_PAD src0_sel:WORD_1 src1_sel:DWORD
	v_and_b32_sdwa v37, v46, v206 dst_sel:DWORD dst_unused:UNUSED_PAD src0_sel:WORD_1 src1_sel:DWORD
	v_add3_u32 v35, v35, v38, s0
	v_add3_u32 v34, v34, v39, s0
	v_add3_u32 v37, v46, v37, s0
	v_add3_u32 v36, v47, v36, s0
	v_and_b32_e32 v35, 0xffff0000, v35
	v_and_b32_e32 v34, 0xffff0000, v34
	v_or_b32_sdwa v35, v35, v36 dst_sel:DWORD dst_unused:UNUSED_PAD src0_sel:DWORD src1_sel:WORD_1
	v_or_b32_sdwa v34, v34, v37 dst_sel:DWORD dst_unused:UNUSED_PAD src0_sel:DWORD src1_sel:WORD_1
	global_store_dwordx2 v[44:45], v[34:35], off offset:3584
	s_branch .LBB0_894

; template <int NR>
; __device__ __forceinline__ void norm_add_rows(const bf16_t* __restrict__ Yb, const float* xi, float* xo, const float* __restrict__ gpost,
;                                               const float* __restrict__ gpre, bf16_t* __restrict__ Hb, int row0, int rstride, int lane) {
;     ...
;     for (int q = 0; q < NR; ++q) { const size_t ro = (size_t)(row0 + q * rstride) * DM;
; #pragma unroll
;         for (int j = 0; j < 8; ++j) yb[q][j] = ((const u32x2*)(Yb + ro))[lane + 64 * j];
; #pragma unroll
;         for (int j = 0; j < 8; ++j) v[q][j] = ((const f32x4*)(xi + ro))[lane + 64 * j]; }
;     f32x4 gp[8];
; #pragma unroll
;     for (int j = 0; j < 8; ++j) gp[j] = ((const f32x4*)gpost)[lane + 64 * j];
; #pragma unroll
;     for (int q = 0; q < NR; ++q) { const size_t ro = (size_t)(row0 + q * rstride) * DM;
;         f32x4 y[8]; float ss = 0.f;
; #pragma unroll
;         for (int j = 0; j < 8; ++j) { y[j].x = __uint_as_float(yb[q][j].x << 16); y[j].y = __uint_as_float(yb[q][j].x & 0xffff0000u); y[j].z = __uint_as_float(yb[q][j].y << 16); y[j].w = __uint_as_float(yb[q][j].y & 0xffff0000u);
;             ss += (y[j].x * y[j].x + y[j].y * y[j].y) + (y[j].z * y[j].z + y[j].w * y[j].w); }
;         const float rs = rsqrtf(wave_sum(ss) * (1.0f / DM) + EPS);
;         float ss2 = 0.f;
; #pragma unroll
;         for (int j = 0; j < 8; ++j) { v[q][j] = v[q][j] + y[j] * rs * gp[j]; ((f32x4*)(xo + ro))[lane + 64 * j] = v[q][j];
.LBB0_903:
	global_load_dwordx2 v[80:81], v[76:77], off
	global_load_dwordx2 v[82:83], v[76:77], off offset:512
	global_load_dwordx2 v[92:93], v[76:77], off offset:1024
	global_load_dwordx2 v[96:97], v[76:77], off offset:1536
	global_load_dwordx2 v[100:101], v[76:77], off offset:2048
	global_load_dwordx2 v[104:105], v[76:77], off offset:2560
	global_load_dwordx2 v[110:111], v[76:77], off offset:3072
	global_load_dwordx2 v[108:109], v[76:77], off offset:3584
	global_load_dwordx4 v[62:65], v[78:79], off offset:-4096
	global_load_dwordx4 v[58:61], v[78:79], off offset:-3072
	global_load_dwordx4 v[54:57], v[78:79], off offset:-2048
	global_load_dwordx4 v[50:53], v[78:79], off offset:-1024
	global_load_dwordx4 v[46:49], v[78:79], off
	global_load_dwordx4 v[42:45], v[78:79], off offset:1024
	global_load_dwordx4 v[38:41], v[78:79], off offset:2048
	global_load_dwordx4 v[34:37], v[78:79], off offset:3072
	s_waitcnt vmcnt(0)
	v_and_b32_e32 v87, 0xffff0000, v80
	v_and_b32_e32 v85, 0xffff0000, v81
	v_lshlrev_b32_e32 v86, 16, v80
	v_lshlrev_b32_e32 v84, 16, v81
	v_mul_f32_e32 v0, v87, v87
	v_mul_f32_e32 v80, v85, v85
	v_fmac_f32_e32 v0, v86, v86
	v_fmac_f32_e32 v80, v84, v84
	v_and_b32_e32 v91, 0xffff0000, v82
	v_and_b32_e32 v89, 0xffff0000, v83
	v_add_f32_e32 v0, v0, v80
	v_lshlrev_b32_e32 v90, 16, v82
	v_lshlrev_b32_e32 v88, 16, v83
	v_mul_f32_e32 v80, v91, v91
	v_mul_f32_e32 v81, v89, v89
	v_fmac_f32_e32 v80, v90, v90
	v_fmac_f32_e32 v81, v88, v88
	v_add_f32_e32 v80, v80, v81
	v_lshlrev_b32_e32 v94, 16, v92
	v_and_b32_e32 v95, 0xffff0000, v92
	v_lshlrev_b32_e32 v92, 16, v93
	v_and_b32_e32 v93, 0xffff0000, v93
	v_add_f32_e32 v0, v0, v80
	v_mul_f32_e32 v80, v95, v95
	v_mul_f32_e32 v81, v93, v93
	v_fmac_f32_e32 v80, v94, v94
	v_fmac_f32_e32 v81, v92, v92
	v_add_f32_e32 v80, v80, v81
	v_lshlrev_b32_e32 v98, 16, v96
	v_and_b32_e32 v99, 0xffff0000, v96
	v_lshlrev_b32_e32 v96, 16, v97
	v_and_b32_e32 v97, 0xffff0000, v97
	v_add_f32_e32 v0, v0, v80
	v_mul_f32_e32 v80, v99, v99
	v_mul_f32_e32 v81, v97, v97
	v_fmac_f32_e32 v80, v98, v98
	v_fmac_f32_e32 v81, v96, v96
	v_add_f32_e32 v80, v80, v81
	v_and_b32_e32 v83, 0xffff0000, v100
	v_and_b32_e32 v81, 0xffff0000, v101
	v_add_f32_e32 v0, v0, v80
	v_lshlrev_b32_e32 v82, 16, v100
	v_lshlrev_b32_e32 v80, 16, v101
	v_mul_f32_e32 v100, v83, v83
	v_mul_f32_e32 v101, v81, v81
	v_fmac_f32_e32 v100, v82, v82
	v_fmac_f32_e32 v101, v80, v80
	v_add_f32_e32 v100, v100, v101
	v_and_b32_e32 v103, 0xffff0000, v104
	v_and_b32_e32 v101, 0xffff0000, v105
	v_add_f32_e32 v0, v0, v100
	v_lshlrev_b32_e32 v102, 16, v104
	v_lshlrev_b32_e32 v100, 16, v105
	v_mul_f32_e32 v104, v103, v103
	v_mul_f32_e32 v105, v101, v101
	v_fmac_f32_e32 v104, v102, v102
	v_fmac_f32_e32 v105, v100, v100
	v_add_f32_e32 v104, v104, v105
	v_and_b32_e32 v107, 0xffff0000, v110
	v_and_b32_e32 v105, 0xffff0000, v111
	v_add_f32_e32 v0, v0, v104
	v_lshlrev_b32_e32 v106, 16, v110
	v_lshlrev_b32_e32 v104, 16, v111
	v_mul_f32_e32 v110, v107, v107
	v_mul_f32_e32 v111, v105, v105
	v_fmac_f32_e32 v110, v106, v106
	v_fmac_f32_e32 v111, v104, v104
	v_add_f32_e32 v110, v110, v111
	v_add_f32_e32 v0, v0, v110
	v_lshlrev_b32_e32 v110, 16, v108
	v_and_b32_e32 v111, 0xffff0000, v108
	v_lshlrev_b32_e32 v108, 16, v109
	v_and_b32_e32 v109, 0xffff0000, v109
	v_mul_f32_e32 v112, v111, v111
	v_mul_f32_e32 v113, v109, v109
	v_fmac_f32_e32 v112, v110, v110
	v_fmac_f32_e32 v113, v108, v108
	v_add_f32_e32 v112, v112, v113
	v_add_f32_e32 v0, v0, v112
	ds_swizzle_b32 v112, v0 offset:swizzle(SWAP,1)
	s_waitcnt lgkmcnt(0)
	v_add_f32_e32 v0, v0, v112
	ds_swizzle_b32 v112, v0 offset:swizzle(SWAP,2)
	s_waitcnt lgkmcnt(0)
	v_add_f32_e32 v0, v0, v112
	ds_swizzle_b32 v112, v0 offset:swizzle(SWAP,4)
	s_waitcnt lgkmcnt(0)
	v_add_f32_e32 v0, v0, v112
	ds_swizzle_b32 v112, v0 offset:swizzle(SWAP,8)
	s_waitcnt lgkmcnt(0)
	v_add_f32_e32 v0, v0, v112
	ds_swizzle_b32 v112, v0 offset:swizzle(SWAP,16)
	s_waitcnt lgkmcnt(0)
	v_add_f32_e32 v0, v0, v112
	v_mov_b32_e32 v112, v0
	s_nop 1
	v_permlane32_swap_b32_e32 v0, v112
	v_add_f32_e32 v0, v0, v112
	v_fmamk_f32 v0, v0, 0x3a000000, v177
	v_cmp_gt_f32_e32 vcc, s35, v0
	v_mul_f32_e32 v112, 0x4b800000, v0
	s_nop 0
	v_cndmask_b32_e32 v0, v0, v112, vcc
	v_rsq_f32_e32 v0, v0
	s_nop 0
	v_mul_f32_e32 v112, 0x45800000, v0
	v_cndmask_b32_e32 v0, v0, v112, vcc
	v_mul_f32_e32 v86, v86, v0
	v_mul_f32_e32 v87, v87, v0
	v_mul_f32_e32 v84, v84, v0
	v_mul_f32_e32 v85, v85, v0
	v_mul_f32_e32 v82, v82, v0
	v_mul_f32_e32 v83, v83, v0
	v_mul_f32_e32 v80, v80, v0
	v_mul_f32_e32 v81, v81, v0
	v_fma_f32 v64, v20, v84, v64
	v_fma_f32 v65, v21, v85, v65
	v_fma_f32 v62, v18, v86, v62
	v_fma_f32 v63, v19, v87, v63
	v_mul_f32_e32 v84, v90, v0
	v_mul_f32_e32 v85, v91, v0
	v_mul_f32_e32 v86, v88, v0
	v_mul_f32_e32 v87, v89, v0
	v_fma_f32 v48, v16, v80, v48
	v_fma_f32 v49, v17, v81, v49
	v_fma_f32 v46, v14, v82, v46
	v_fma_f32 v47, v15, v83, v47
	v_mul_f32_e32 v80, v102, v0
	v_mul_f32_e32 v81, v103, v0
	v_mul_f32_e32 v82, v100, v0
	v_mul_f32_e32 v83, v101, v0
	v_fma_f32 v60, v4, v86, v60
	v_fma_f32 v61, v5, v87, v61
	v_fma_f32 v58, v2, v84, v58
	v_fma_f32 v59, v3, v85, v59
	v_mul_f32_e32 v84, v94, v0
	v_mul_f32_e32 v85, v95, v0
	v_mul_f32_e32 v86, v92, v0
	v_mul_f32_e32 v87, v93, v0
	v_fma_f32 v44, v24, v82, v44
	v_fma_f32 v45, v25, v83, v45
	v_fma_f32 v42, v22, v80, v42
	v_fma_f32 v43, v23, v81, v43
	v_mul_f32_e32 v80, v106, v0
	v_mul_f32_e32 v81, v107, v0
	v_mul_f32_e32 v82, v104, v0
	v_mul_f32_e32 v83, v105, v0
	v_fma_f32 v56, v8, v86, v56
	v_fma_f32 v57, v9, v87, v57
	v_fma_f32 v54, v6, v84, v54
	v_fma_f32 v55, v7, v85, v55
	v_mul_f32_e32 v84, v98, v0
	v_mul_f32_e32 v85, v99, v0
	v_mul_f32_e32 v86, v96, v0
	v_mul_f32_e32 v87, v97, v0
	v_fma_f32 v40, v28, v82, v40
	v_fma_f32 v41, v29, v83, v41
	v_fma_f32 v38, v26, v80, v38
	v_fma_f32 v39, v27, v81, v39
	v_mul_f32_e32 v80, v110, v0
	v_mul_f32_e32 v81, v111, v0
	v_mul_f32_e32 v82, v108, v0
	v_mul_f32_e32 v83, v109, v0
	v_fma_f32 v52, v12, v86, v52
	v_fma_f32 v53, v13, v87, v53
	v_fma_f32 v50, v10, v84, v50
	v_fma_f32 v51, v11, v85, v51
	v_fma_f32 v36, v32, v82, v36
	v_fma_f32 v37, v33, v83, v37
	v_fma_f32 v34, v30, v80, v34
	v_fma_f32 v35, v31, v81, v35
	s_andn2_b64 vcc, exec, s[16:17]
	global_store_dwordx4 v[78:79], v[62:65], off offset:-4096
	global_store_dwordx4 v[78:79], v[58:61], off offset:-3072
	global_store_dwordx4 v[78:79], v[54:57], off offset:-2048
	global_store_dwordx4 v[78:79], v[50:53], off offset:-1024
	global_store_dwordx4 v[78:79], v[46:49], off
	global_store_dwordx4 v[78:79], v[42:45], off offset:1024
	global_store_dwordx4 v[78:79], v[38:41], off offset:2048
	global_store_dwordx4 v[78:79], v[34:37], off offset:3072
	s_cbranch_vccnz .LBB0_902
; __device__ __forceinline__ unsigned pk2(float lo, float hi) { return f2bf(lo) | (f2bf(hi) << 16); }
; template <int NR>
; __device__ __forceinline__ void norm_add_rows(const bf16_t* __restrict__ Yb, const float* xi, float* xo, const float* __restrict__ gpost,
;                                               const float* __restrict__ gpre, bf16_t* __restrict__ Hb, int row0, int rstride, int lane) {
;     ...
;         for (int j = 0; j < 8; ++j) { v[q][j] = v[q][j] + y[j] * rs * gp[j]; ((f32x4*)(xo + ro))[lane + 64 * j] = v[q][j];
;             ss2 += (v[q][j].x * v[q][j].x + v[q][j].y * v[q][j].y) + (v[q][j].z * v[q][j].z + v[q][j].w * v[q][j].w); }
;         if (gpre) {
;             const float rs2 = rsqrtf(wave_sum(ss2) * (1.0f / DM) + EPS);
; #pragma unroll
;             for (int j = 0; j < 8; ++j) { const f32x4 gg = ((const f32x4*)gpre)[lane + 64 * j];
;                 u32x2 w; w.x = pk2(v[q][j].x * rs2 * gg.x, v[q][j].y * rs2 * gg.y); w.y = pk2(v[q][j].z * rs2 * gg.z, v[q][j].w * rs2 * gg.w); ((u32x2*)(Hb + ro))[lane + 64 * j] = w; }
	v_mul_f32_e32 v0, v63, v63
	v_mul_f32_e32 v80, v65, v65
	v_fmac_f32_e32 v0, v62, v62
	v_fmac_f32_e32 v80, v64, v64
	v_add_f32_e32 v0, v0, v80
	v_mul_f32_e32 v80, v59, v59
	v_mul_f32_e32 v81, v61, v61
	v_fmac_f32_e32 v80, v58, v58
	v_fmac_f32_e32 v81, v60, v60
	v_add_f32_e32 v80, v80, v81
	v_add_f32_e32 v0, v0, v80
	v_mul_f32_e32 v80, v55, v55
	v_mul_f32_e32 v81, v57, v57
	v_fmac_f32_e32 v80, v54, v54
	v_fmac_f32_e32 v81, v56, v56
	v_add_f32_e32 v80, v80, v81
	v_add_f32_e32 v0, v80, v0
	v_mul_f32_e32 v80, v51, v51
	v_mul_f32_e32 v81, v53, v53
	v_fmac_f32_e32 v80, v50, v50
	v_fmac_f32_e32 v81, v52, v52
	v_add_f32_e32 v80, v80, v81
	v_add_f32_e32 v0, v80, v0
	v_mul_f32_e32 v80, v47, v47
	v_mul_f32_e32 v81, v49, v49
	v_fmac_f32_e32 v80, v46, v46
	v_fmac_f32_e32 v81, v48, v48
	v_add_f32_e32 v80, v80, v81
	v_add_f32_e32 v0, v80, v0
	v_mul_f32_e32 v80, v43, v43
	v_mul_f32_e32 v81, v45, v45
	v_fmac_f32_e32 v80, v42, v42
	v_fmac_f32_e32 v81, v44, v44
	v_add_f32_e32 v80, v80, v81
	v_add_f32_e32 v0, v80, v0
	v_mul_f32_e32 v80, v39, v39
	v_mul_f32_e32 v81, v41, v41
	v_fmac_f32_e32 v80, v38, v38
	v_fmac_f32_e32 v81, v40, v40
	v_add_f32_e32 v80, v80, v81
	v_add_f32_e32 v0, v80, v0
	v_mul_f32_e32 v80, v35, v35
	v_mul_f32_e32 v81, v37, v37
	v_fmac_f32_e32 v80, v34, v34
	v_fmac_f32_e32 v81, v36, v36
	v_add_f32_e32 v80, v80, v81
	v_add_f32_e32 v0, v80, v0
	ds_swizzle_b32 v80, v0 offset:swizzle(SWAP,1)
	v_mov_b32_e32 v85, v64
	v_mov_b32_e32 v64, v63
	v_mov_b32_e32 v84, v62
	s_mov_b32 s4, 0xe7600000
	s_waitcnt lgkmcnt(0)
	v_add_f32_e32 v0, v0, v80
	ds_swizzle_b32 v80, v0 offset:swizzle(SWAP,2)
	s_waitcnt lgkmcnt(0)
	v_add_f32_e32 v0, v0, v80
	ds_swizzle_b32 v80, v0 offset:swizzle(SWAP,4)
	s_waitcnt lgkmcnt(0)
	v_add_f32_e32 v0, v0, v80
	ds_swizzle_b32 v80, v0 offset:swizzle(SWAP,8)
	s_waitcnt lgkmcnt(0)
	v_add_f32_e32 v0, v0, v80
	ds_swizzle_b32 v80, v0 offset:swizzle(SWAP,16)
	s_waitcnt lgkmcnt(0)
	v_add_f32_e32 v0, v0, v80
	v_mov_b32_e32 v80, v0
	s_nop 1
	v_permlane32_swap_b32_e32 v0, v80
	v_add_f32_e32 v0, v0, v80
	v_fmamk_f32 v0, v0, 0x3a000000, v177
	v_cmp_gt_f32_e32 vcc, s35, v0
	v_mul_f32_e32 v80, 0x4b800000, v0
	s_nop 0
	v_cndmask_b32_e32 v0, v0, v80, vcc
	v_rsq_f32_e32 v0, v0
	s_nop 0
	v_mul_f32_e32 v80, 0x45800000, v0
	v_cndmask_b32_e32 v0, v0, v80, vcc
	global_load_dwordx4 v[80:83], v[66:67], off
	v_mul_f32_e32 v62, v64, v0
	v_mul_f32_e32 v63, v65, v0
	v_mul_f32_e32 v84, v84, v0
	v_mul_f32_e32 v85, v85, v0
	s_waitcnt vmcnt(0)
	v_mov_b32_e32 v87, v82
	v_mov_b32_e32 v82, v81
	v_mov_b32_e32 v86, v80
	v_mul_f32_e32 v62, v82, v62
	v_mul_f32_e32 v63, v83, v63
	v_mul_f32_e32 v84, v86, v84
	v_mul_f32_e32 v85, v87, v85
	v_and_b32_sdwa v80, v63, v206 dst_sel:DWORD dst_unused:UNUSED_PAD src0_sel:WORD_1 src1_sel:DWORD
	v_and_b32_sdwa v64, v85, v206 dst_sel:DWORD dst_unused:UNUSED_PAD src0_sel:WORD_1 src1_sel:DWORD
	v_and_b32_sdwa v81, v62, v206 dst_sel:DWORD dst_unused:UNUSED_PAD src0_sel:WORD_1 src1_sel:DWORD
	v_add3_u32 v63, v63, v80, s0
	v_and_b32_sdwa v65, v84, v206 dst_sel:DWORD dst_unused:UNUSED_PAD src0_sel:WORD_1 src1_sel:DWORD
	v_add3_u32 v64, v85, v64, s0
	v_add3_u32 v62, v62, v81, s0
	v_and_b32_e32 v63, 0xffff0000, v63
	v_add3_u32 v65, v84, v65, s0
	v_and_b32_e32 v62, 0xffff0000, v62
	v_or_b32_sdwa v63, v63, v64 dst_sel:DWORD dst_unused:UNUSED_PAD src0_sel:DWORD src1_sel:WORD_1
	v_add_co_u32_e32 v64, vcc, s4, v76
	v_or_b32_sdwa v62, v62, v65 dst_sel:DWORD dst_unused:UNUSED_PAD src0_sel:DWORD src1_sel:WORD_1
	s_nop 0
	v_addc_co_u32_e32 v65, vcc, -1, v77, vcc
	global_store_dwordx2 v[64:65], v[62:63], off
	global_load_dwordx4 v[62:65], v[66:67], off offset:1024
	v_mov_b32_e32 v80, v58
	v_mov_b32_e32 v81, v60
	v_mul_f32_e32 v80, v80, v0
	v_mul_f32_e32 v81, v81, v0
	v_mov_b32_e32 v60, v59
	v_mul_f32_e32 v58, v60, v0
	v_mul_f32_e32 v59, v61, v0
	s_mov_b32 s4, 0xe7601000
	s_waitcnt vmcnt(0)
	v_mov_b32_e32 v82, v62
	v_mov_b32_e32 v83, v64
	v_mul_f32_e32 v80, v82, v80
	v_mul_f32_e32 v81, v83, v81
	v_mov_b32_e32 v64, v63
	v_mul_f32_e32 v58, v64, v58
	v_mul_f32_e32 v59, v65, v59
	v_and_b32_sdwa v61, v80, v206 dst_sel:DWORD dst_unused:UNUSED_PAD src0_sel:WORD_1 src1_sel:DWORD
	v_add3_u32 v62, v80, v61, s0
	v_and_b32_sdwa v61, v59, v206 dst_sel:DWORD dst_unused:UNUSED_PAD src0_sel:WORD_1 src1_sel:DWORD
	v_and_b32_sdwa v63, v58, v206 dst_sel:DWORD dst_unused:UNUSED_PAD src0_sel:WORD_1 src1_sel:DWORD
	v_and_b32_sdwa v60, v81, v206 dst_sel:DWORD dst_unused:UNUSED_PAD src0_sel:WORD_1 src1_sel:DWORD
	v_add3_u32 v59, v59, v61, s0
	v_add3_u32 v58, v58, v63, s0
	v_add3_u32 v60, v81, v60, s0
	v_and_b32_e32 v59, 0xffff0000, v59
	v_and_b32_e32 v58, 0xffff0000, v58
	v_or_b32_sdwa v61, v59, v60 dst_sel:DWORD dst_unused:UNUSED_PAD src0_sel:DWORD src1_sel:WORD_1
	v_or_b32_sdwa v60, v58, v62 dst_sel:DWORD dst_unused:UNUSED_PAD src0_sel:DWORD src1_sel:WORD_1
	v_add_co_u32_e32 v58, vcc, s4, v76
	v_mov_b32_e32 v65, v56
	s_nop 0
	v_addc_co_u32_e32 v59, vcc, -1, v77, vcc
	global_store_dwordx2 v[58:59], v[60:61], off offset:-3584
	global_load_dwordx4 v[60:63], v[66:67], off offset:2048
	v_mov_b32_e32 v56, v55
	v_mov_b32_e32 v64, v54
	v_mul_f32_e32 v54, v56, v0
	v_mul_f32_e32 v55, v57, v0
	v_mul_f32_e32 v64, v64, v0
	v_mul_f32_e32 v65, v65, v0
	s_waitcnt vmcnt(0)
; __device__ __forceinline__ unsigned pk2(float lo, float hi) { return f2bf(lo) | (f2bf(hi) << 16); }
; template <int NR>
; __device__ __forceinline__ void norm_add_rows(const bf16_t* __restrict__ Yb, const float* xi, float* xo, const float* __restrict__ gpost,
;                                               const float* __restrict__ gpre, bf16_t* __restrict__ Hb, int row0, int rstride, int lane) {
;     ...
;         if (gpre) {
;             const float rs2 = rsqrtf(wave_sum(ss2) * (1.0f / DM) + EPS);
; #pragma unroll
;             for (int j = 0; j < 8; ++j) { const f32x4 gg = ((const f32x4*)gpre)[lane + 64 * j];
;                 u32x2 w; w.x = pk2(v[q][j].x * rs2 * gg.x, v[q][j].y * rs2 * gg.y); w.y = pk2(v[q][j].z * rs2 * gg.z, v[q][j].w * rs2 * gg.w); ((u32x2*)(Hb + ro))[lane + 64 * j] = w; }
	v_mov_b32_e32 v81, v62
	v_mov_b32_e32 v62, v61
	v_mov_b32_e32 v80, v60
	v_mul_f32_e32 v54, v62, v54
	v_mul_f32_e32 v55, v63, v55
	v_mul_f32_e32 v64, v80, v64
	v_mul_f32_e32 v65, v81, v65
	v_and_b32_sdwa v60, v55, v206 dst_sel:DWORD dst_unused:UNUSED_PAD src0_sel:WORD_1 src1_sel:DWORD
	v_and_b32_sdwa v61, v54, v206 dst_sel:DWORD dst_unused:UNUSED_PAD src0_sel:WORD_1 src1_sel:DWORD
	v_and_b32_sdwa v56, v65, v206 dst_sel:DWORD dst_unused:UNUSED_PAD src0_sel:WORD_1 src1_sel:DWORD
	v_and_b32_sdwa v57, v64, v206 dst_sel:DWORD dst_unused:UNUSED_PAD src0_sel:WORD_1 src1_sel:DWORD
	v_add3_u32 v55, v55, v60, s0
	v_add3_u32 v54, v54, v61, s0
	v_add3_u32 v57, v64, v57, s0
	v_add3_u32 v56, v65, v56, s0
	v_and_b32_e32 v55, 0xffff0000, v55
	v_and_b32_e32 v54, 0xffff0000, v54
	v_or_b32_sdwa v55, v55, v56 dst_sel:DWORD dst_unused:UNUSED_PAD src0_sel:DWORD src1_sel:WORD_1
	v_or_b32_sdwa v54, v54, v57 dst_sel:DWORD dst_unused:UNUSED_PAD src0_sel:DWORD src1_sel:WORD_1
	global_store_dwordx2 v[58:59], v[54:55], off offset:-3072
	global_load_dwordx4 v[54:57], v[66:67], off offset:3072
	v_mov_b32_e32 v61, v52
	v_mov_b32_e32 v52, v51
	v_mov_b32_e32 v60, v50
	v_mul_f32_e32 v50, v52, v0
	v_mul_f32_e32 v51, v53, v0
	v_mul_f32_e32 v60, v60, v0
	v_mul_f32_e32 v61, v61, v0
	s_waitcnt vmcnt(0)
	v_mov_b32_e32 v63, v56
	v_mov_b32_e32 v56, v55
	v_mov_b32_e32 v62, v54
	v_mul_f32_e32 v50, v56, v50
	v_mul_f32_e32 v51, v57, v51
	v_mul_f32_e32 v60, v62, v60
	v_mul_f32_e32 v61, v63, v61
	v_and_b32_sdwa v54, v51, v206 dst_sel:DWORD dst_unused:UNUSED_PAD src0_sel:WORD_1 src1_sel:DWORD
	v_and_b32_sdwa v55, v50, v206 dst_sel:DWORD dst_unused:UNUSED_PAD src0_sel:WORD_1 src1_sel:DWORD
	v_and_b32_sdwa v52, v61, v206 dst_sel:DWORD dst_unused:UNUSED_PAD src0_sel:WORD_1 src1_sel:DWORD
	v_and_b32_sdwa v53, v60, v206 dst_sel:DWORD dst_unused:UNUSED_PAD src0_sel:WORD_1 src1_sel:DWORD
	v_add3_u32 v51, v51, v54, s0
	v_add3_u32 v50, v50, v55, s0
	v_add3_u32 v53, v60, v53, s0
	v_add3_u32 v52, v61, v52, s0
	v_and_b32_e32 v51, 0xffff0000, v51
	v_and_b32_e32 v50, 0xffff0000, v50
	v_or_b32_sdwa v51, v51, v52 dst_sel:DWORD dst_unused:UNUSED_PAD src0_sel:DWORD src1_sel:WORD_1
	v_or_b32_sdwa v50, v50, v53 dst_sel:DWORD dst_unused:UNUSED_PAD src0_sel:DWORD src1_sel:WORD_1
	global_store_dwordx2 v[58:59], v[50:51], off offset:-2560
	global_load_dwordx4 v[50:53], v[68:69], off
	v_mov_b32_e32 v55, v48
	v_mov_b32_e32 v48, v47
	v_mov_b32_e32 v54, v46
	v_mul_f32_e32 v46, v48, v0
	v_mul_f32_e32 v47, v49, v0
	v_mul_f32_e32 v54, v54, v0
	v_mul_f32_e32 v55, v55, v0
	s_waitcnt vmcnt(0)
	v_mov_b32_e32 v57, v52
	v_mov_b32_e32 v52, v51
	v_mov_b32_e32 v56, v50
	v_mul_f32_e32 v46, v52, v46
	v_mul_f32_e32 v47, v53, v47
	v_mul_f32_e32 v54, v56, v54
	v_mul_f32_e32 v55, v57, v55
	v_and_b32_sdwa v50, v47, v206 dst_sel:DWORD dst_unused:UNUSED_PAD src0_sel:WORD_1 src1_sel:DWORD
	v_and_b32_sdwa v51, v46, v206 dst_sel:DWORD dst_unused:UNUSED_PAD src0_sel:WORD_1 src1_sel:DWORD
	v_and_b32_sdwa v48, v55, v206 dst_sel:DWORD dst_unused:UNUSED_PAD src0_sel:WORD_1 src1_sel:DWORD
	v_and_b32_sdwa v49, v54, v206 dst_sel:DWORD dst_unused:UNUSED_PAD src0_sel:WORD_1 src1_sel:DWORD
	v_add3_u32 v47, v47, v50, s0
	v_add3_u32 v46, v46, v51, s0
	v_add3_u32 v49, v54, v49, s0
	v_add3_u32 v48, v55, v48, s0
	v_and_b32_e32 v47, 0xffff0000, v47
	v_and_b32_e32 v46, 0xffff0000, v46
	v_or_b32_sdwa v47, v47, v48 dst_sel:DWORD dst_unused:UNUSED_PAD src0_sel:DWORD src1_sel:WORD_1
	v_or_b32_sdwa v46, v46, v49 dst_sel:DWORD dst_unused:UNUSED_PAD src0_sel:DWORD src1_sel:WORD_1
	global_store_dwordx2 v[58:59], v[46:47], off offset:-2048
	global_load_dwordx4 v[46:49], v[70:71], off
	v_mov_b32_e32 v51, v44
	v_mov_b32_e32 v44, v43
	v_mov_b32_e32 v50, v42
	v_mul_f32_e32 v42, v44, v0
	v_mul_f32_e32 v43, v45, v0
	v_mul_f32_e32 v50, v50, v0
	v_mul_f32_e32 v51, v51, v0
	s_waitcnt vmcnt(0)
; __device__ __forceinline__ unsigned pk2(float lo, float hi) { return f2bf(lo) | (f2bf(hi) << 16); }
; template <int NR>
; __device__ __forceinline__ void norm_add_rows(const bf16_t* __restrict__ Yb, const float* xi, float* xo, const float* __restrict__ gpost,
;                                               const float* __restrict__ gpre, bf16_t* __restrict__ Hb, int row0, int rstride, int lane) {
;     ...
;         if (gpre) {
;             const float rs2 = rsqrtf(wave_sum(ss2) * (1.0f / DM) + EPS);
; #pragma unroll
;             for (int j = 0; j < 8; ++j) { const f32x4 gg = ((const f32x4*)gpre)[lane + 64 * j];
;                 u32x2 w; w.x = pk2(v[q][j].x * rs2 * gg.x, v[q][j].y * rs2 * gg.y); w.y = pk2(v[q][j].z * rs2 * gg.z, v[q][j].w * rs2 * gg.w); ((u32x2*)(Hb + ro))[lane + 64 * j] = w; }
	v_mov_b32_e32 v53, v48
	v_mov_b32_e32 v48, v47
	v_mov_b32_e32 v52, v46
	v_mul_f32_e32 v42, v42, v48
	v_mul_f32_e32 v43, v43, v49
	v_mul_f32_e32 v50, v50, v52
	v_mul_f32_e32 v51, v51, v53
	v_and_b32_sdwa v46, v43, v206 dst_sel:DWORD dst_unused:UNUSED_PAD src0_sel:WORD_1 src1_sel:DWORD
	v_and_b32_sdwa v47, v42, v206 dst_sel:DWORD dst_unused:UNUSED_PAD src0_sel:WORD_1 src1_sel:DWORD
	v_and_b32_sdwa v44, v51, v206 dst_sel:DWORD dst_unused:UNUSED_PAD src0_sel:WORD_1 src1_sel:DWORD
	v_and_b32_sdwa v45, v50, v206 dst_sel:DWORD dst_unused:UNUSED_PAD src0_sel:WORD_1 src1_sel:DWORD
	v_add3_u32 v43, v43, v46, s0
	v_add3_u32 v42, v42, v47, s0
	v_add3_u32 v45, v50, v45, s0
	v_add3_u32 v44, v51, v44, s0
	v_and_b32_e32 v43, 0xffff0000, v43
	v_and_b32_e32 v42, 0xffff0000, v42
	v_or_b32_sdwa v43, v43, v44 dst_sel:DWORD dst_unused:UNUSED_PAD src0_sel:DWORD src1_sel:WORD_1
	v_or_b32_sdwa v42, v42, v45 dst_sel:DWORD dst_unused:UNUSED_PAD src0_sel:DWORD src1_sel:WORD_1
	global_store_dwordx2 v[58:59], v[42:43], off offset:-1536
	global_load_dwordx4 v[42:45], v[72:73], off
	v_mov_b32_e32 v47, v40
	v_mov_b32_e32 v40, v39
	v_mov_b32_e32 v46, v38
	v_mul_f32_e32 v38, v40, v0
	v_mul_f32_e32 v39, v41, v0
	v_mul_f32_e32 v46, v46, v0
	v_mul_f32_e32 v47, v47, v0
	s_waitcnt vmcnt(0)
	v_mov_b32_e32 v49, v44
	v_mov_b32_e32 v44, v43
	v_mov_b32_e32 v48, v42
	v_mul_f32_e32 v38, v38, v44
	v_mul_f32_e32 v39, v39, v45
	v_mul_f32_e32 v46, v46, v48
	v_mul_f32_e32 v47, v47, v49
	v_and_b32_sdwa v42, v39, v206 dst_sel:DWORD dst_unused:UNUSED_PAD src0_sel:WORD_1 src1_sel:DWORD
	v_and_b32_sdwa v43, v38, v206 dst_sel:DWORD dst_unused:UNUSED_PAD src0_sel:WORD_1 src1_sel:DWORD
	v_and_b32_sdwa v40, v47, v206 dst_sel:DWORD dst_unused:UNUSED_PAD src0_sel:WORD_1 src1_sel:DWORD
	v_and_b32_sdwa v41, v46, v206 dst_sel:DWORD dst_unused:UNUSED_PAD src0_sel:WORD_1 src1_sel:DWORD
	v_add3_u32 v39, v39, v42, s0
	v_add3_u32 v38, v38, v43, s0
	v_add3_u32 v41, v46, v41, s0
	v_add3_u32 v40, v47, v40, s0
	v_and_b32_e32 v39, 0xffff0000, v39
	v_and_b32_e32 v38, 0xffff0000, v38
	v_or_b32_sdwa v39, v39, v40 dst_sel:DWORD dst_unused:UNUSED_PAD src0_sel:DWORD src1_sel:WORD_1
	v_or_b32_sdwa v38, v38, v41 dst_sel:DWORD dst_unused:UNUSED_PAD src0_sel:DWORD src1_sel:WORD_1
	global_store_dwordx2 v[58:59], v[38:39], off offset:-1024
	global_load_dwordx4 v[38:41], v[74:75], off
	v_mov_b32_e32 v43, v36
	v_mov_b32_e32 v36, v35
	v_mov_b32_e32 v42, v34
	v_mul_f32_e32 v34, v36, v0
	v_mul_f32_e32 v35, v37, v0
	v_mul_f32_e32 v42, v42, v0
	v_mul_f32_e32 v43, v43, v0
	s_waitcnt vmcnt(0)
	v_mov_b32_e32 v45, v40
	v_mov_b32_e32 v40, v39
	v_mov_b32_e32 v44, v38
	v_mul_f32_e32 v34, v34, v40
	v_mul_f32_e32 v35, v35, v41
	v_mul_f32_e32 v42, v42, v44
	v_mul_f32_e32 v43, v43, v45
	v_and_b32_sdwa v37, v35, v206 dst_sel:DWORD dst_unused:UNUSED_PAD src0_sel:WORD_1 src1_sel:DWORD
	v_and_b32_sdwa v38, v34, v206 dst_sel:DWORD dst_unused:UNUSED_PAD src0_sel:WORD_1 src1_sel:DWORD
	v_and_b32_sdwa v0, v43, v206 dst_sel:DWORD dst_unused:UNUSED_PAD src0_sel:WORD_1 src1_sel:DWORD
	v_and_b32_sdwa v36, v42, v206 dst_sel:DWORD dst_unused:UNUSED_PAD src0_sel:WORD_1 src1_sel:DWORD
	v_add3_u32 v35, v35, v37, s0
	v_add3_u32 v34, v34, v38, s0
	v_add3_u32 v36, v42, v36, s0
	v_add3_u32 v0, v43, v0, s0
	v_and_b32_e32 v35, 0xffff0000, v35
	v_and_b32_e32 v34, 0xffff0000, v34
	v_or_b32_sdwa v35, v35, v0 dst_sel:DWORD dst_unused:UNUSED_PAD src0_sel:DWORD src1_sel:WORD_1
	v_or_b32_sdwa v34, v34, v36 dst_sel:DWORD dst_unused:UNUSED_PAD src0_sel:DWORD src1_sel:WORD_1
	global_store_dwordx2 v[58:59], v[34:35], off offset:-512
	s_branch .LBB0_902
